# GEMM K-loops: s_setprio toggling around the MFMA blocks removed
# baseline (speedup 1.0000x reference)
.LBB0_81:
	s_add_i32 s1, 0, 0x10000
	v_add_u32_e32 v2, s1, v1
	ds_read_b128 v[82:85], v2
	ds_read_b128 v[150:153], v2 offset:1024
	ds_read_b128 v[158:161], v2 offset:2048
	ds_read_b128 v[178:181], v2 offset:3072
	s_cmp_eq_u32 s0, 18
	v_lshl_add_u64 v[66:67], v[64:65], 0, s[74:75]
	s_cselect_b64 vcc, -1, 0
	v_cndmask_b32_e32 v175, v67, v171, vcc
	v_cndmask_b32_e32 v174, v66, v170, vcc
	v_cndmask_b32_e32 v69, v63, v173, vcc
	v_cndmask_b32_e32 v68, v62, v172, vcc
	v_lshl_add_u64 v[76:77], v[64:65], 0, v[166:167]
	s_add_i32 m0, s19, 0xc000
	ds_read_b128 v[182:185], v155
	ds_read_b128 v[186:189], v155 offset:1024
	ds_read_b128 v[190:193], v155 offset:2048
	ds_read_b128 v[194:197], v155 offset:3072
	ds_read_b128 v[198:201], v155 offset:4096
	ds_read_b128 v[202:205], v155 offset:5120
	ds_read_b128 v[206:209], v155 offset:6144
	ds_read_b128 v[210:213], v155 offset:7168
	global_load_lds_dwordx4 v[76:77], off
	v_lshl_add_u64 v[64:65], v[64:65], 0, v[168:169]
	s_add_i32 m0, s19, 0xe000
	s_nop 0
	global_load_lds_dwordx4 v[64:65], off
	s_waitcnt lgkmcnt(8)
	s_barrier
	s_waitcnt lgkmcnt(0)
	s_waitcnt lgkmcnt(0)
	v_mfma_f32_16x16x32_bf16 v[146:149], v[82:85], v[182:185], v[146:149]
	v_mfma_f32_16x16x32_bf16 v[142:145], v[158:161], v[182:185], v[142:145]
	v_mfma_f32_16x16x32_bf16 v[130:133], v[82:85], v[190:193], v[130:133]
	v_mfma_f32_16x16x32_bf16 v[126:129], v[158:161], v[190:193], v[126:129]
	v_mfma_f32_16x16x32_bf16 v[114:117], v[82:85], v[198:201], v[114:117]
	v_mfma_f32_16x16x32_bf16 v[110:113], v[158:161], v[198:201], v[110:113]
	v_mfma_f32_16x16x32_bf16 v[98:101], v[82:85], v[206:209], v[98:101]
	v_mfma_f32_16x16x32_bf16 v[94:97], v[158:161], v[206:209], v[94:97]
	v_mfma_f32_16x16x32_bf16 v[146:149], v[150:153], v[186:189], v[146:149]
	v_mfma_f32_16x16x32_bf16 v[142:145], v[178:181], v[186:189], v[142:145]
	v_mfma_f32_16x16x32_bf16 v[130:133], v[150:153], v[194:197], v[130:133]
	v_mfma_f32_16x16x32_bf16 v[126:129], v[178:181], v[194:197], v[126:129]
	v_mfma_f32_16x16x32_bf16 v[114:117], v[150:153], v[202:205], v[114:117]
	v_mfma_f32_16x16x32_bf16 v[110:113], v[178:181], v[202:205], v[110:113]
	v_mfma_f32_16x16x32_bf16 v[98:101], v[150:153], v[210:213], v[98:101]
	v_mfma_f32_16x16x32_bf16 v[94:97], v[178:181], v[210:213], v[94:97]
	s_barrier
	s_add_i32 s6, 0, 0x14000
	s_add_i32 s1, s1, s18
	v_add_u32_e32 v2, s6, v1
	v_lshl_add_u64 v[64:65], v[68:69], 0, v[162:163]
	s_mov_b32 m0, s1
	ds_read_b128 v[214:217], v2
	ds_read_b128 v[234:237], v2 offset:1024
	ds_read_b128 v[238:241], v2 offset:2048
	ds_read_b128 v[242:245], v2 offset:3072
	global_load_lds_dwordx4 v[64:65], off
	v_lshl_add_u64 v[230:231], v[68:69], 0, v[164:165]
	s_add_i32 m0, s1, 0x2000
	s_nop 0
	global_load_lds_dwordx4 v[230:231], off
	s_barrier
	s_waitcnt lgkmcnt(0)
	s_waitcnt lgkmcnt(0)
	v_mfma_f32_16x16x32_bf16 v[138:141], v[214:217], v[182:185], v[138:141]
	v_mfma_f32_16x16x32_bf16 v[134:137], v[238:241], v[182:185], v[134:137]
	v_mfma_f32_16x16x32_bf16 v[122:125], v[214:217], v[190:193], v[122:125]
	v_mfma_f32_16x16x32_bf16 v[118:121], v[238:241], v[190:193], v[118:121]
	v_mfma_f32_16x16x32_bf16 v[106:109], v[214:217], v[198:201], v[106:109]
	v_mfma_f32_16x16x32_bf16 v[102:105], v[238:241], v[198:201], v[102:105]
	v_mfma_f32_16x16x32_bf16 v[90:93], v[214:217], v[206:209], v[90:93]
	v_mfma_f32_16x16x32_bf16 v[86:89], v[238:241], v[206:209], v[86:89]
	v_mfma_f32_16x16x32_bf16 v[138:141], v[234:237], v[186:189], v[138:141]
	v_mfma_f32_16x16x32_bf16 v[134:137], v[242:245], v[186:189], v[134:137]
	v_mfma_f32_16x16x32_bf16 v[122:125], v[234:237], v[194:197], v[122:125]
	v_mfma_f32_16x16x32_bf16 v[118:121], v[242:245], v[194:197], v[118:121]
	v_mfma_f32_16x16x32_bf16 v[106:109], v[234:237], v[202:205], v[106:109]
	v_mfma_f32_16x16x32_bf16 v[102:105], v[242:245], v[202:205], v[102:105]
	v_mfma_f32_16x16x32_bf16 v[90:93], v[234:237], v[210:213], v[90:93]
	v_mfma_f32_16x16x32_bf16 v[86:89], v[242:245], v[210:213], v[86:89]
	s_mov_b32 m0, s19
	v_lshl_add_u64 v[246:247], v[174:175], 0, v[162:163]
	s_barrier
	ds_read_b128 v[182:185], v155 offset:16384
	ds_read_b128 v[186:189], v155 offset:17408
	ds_read_b128 v[190:193], v155 offset:18432
	ds_read_b128 v[194:197], v155 offset:19456
	ds_read_b128 v[198:201], v155 offset:20480
	ds_read_b128 v[202:205], v155 offset:21504
	ds_read_b128 v[206:209], v155 offset:22528
	ds_read_b128 v[210:213], v155 offset:23552
	global_load_lds_dwordx4 v[246:247], off
	v_lshl_add_u64 v[248:249], v[174:175], 0, v[164:165]
	s_mov_b32 m0, s27
	s_nop 0
	global_load_lds_dwordx4 v[248:249], off
	s_barrier
	s_waitcnt lgkmcnt(0)
	s_waitcnt lgkmcnt(0)
	v_mfma_f32_16x16x32_bf16 v[76:79], v[82:85], v[182:185], v[78:81]
	v_mfma_f32_16x16x32_bf16 v[70:73], v[158:161], v[182:185], v[70:73]
	v_mfma_f32_16x16x32_bf16 v[50:53], v[82:85], v[190:193], v[50:53]
	v_mfma_f32_16x16x32_bf16 v[46:49], v[158:161], v[190:193], v[46:49]
	v_mfma_f32_16x16x32_bf16 v[32:35], v[82:85], v[198:201], v[32:35]
	v_mfma_f32_16x16x32_bf16 v[28:31], v[158:161], v[198:201], v[28:31]
	v_mfma_f32_16x16x32_bf16 v[16:19], v[82:85], v[206:209], v[16:19]
	v_mfma_f32_16x16x32_bf16 v[12:15], v[158:161], v[206:209], v[12:15]
	v_mfma_f32_16x16x32_bf16 v[76:79], v[150:153], v[186:189], v[76:79]
	v_mfma_f32_16x16x32_bf16 v[70:73], v[178:181], v[186:189], v[70:73]
	v_mfma_f32_16x16x32_bf16 v[50:53], v[150:153], v[194:197], v[50:53]
	v_mfma_f32_16x16x32_bf16 v[46:49], v[178:181], v[194:197], v[46:49]
	v_mfma_f32_16x16x32_bf16 v[32:35], v[150:153], v[202:205], v[32:35]
	v_mfma_f32_16x16x32_bf16 v[28:31], v[178:181], v[202:205], v[28:31]
	v_mfma_f32_16x16x32_bf16 v[16:19], v[150:153], v[210:213], v[16:19]
	v_mfma_f32_16x16x32_bf16 v[12:15], v[178:181], v[210:213], v[12:15]
	s_barrier
	v_lshl_add_u64 v[80:81], v[68:69], 0, s[14:15]
	s_add_i32 s1, s6, s18
	v_lshl_add_u64 v[82:83], v[80:81], 0, v[162:163]
	s_mov_b32 m0, s1
	v_lshl_add_u64 v[80:81], v[80:81], 0, v[164:165]
	global_load_lds_dwordx4 v[82:83], off
	s_add_i32 m0, s1, 0x2000
	s_nop 0
	global_load_lds_dwordx4 v[80:81], off
	s_waitcnt vmcnt(6)
	s_barrier
	v_mfma_f32_16x16x32_bf16 v[58:61], v[214:217], v[182:185], v[58:61]
	v_mfma_f32_16x16x32_bf16 v[54:57], v[238:241], v[182:185], v[54:57]
	v_mfma_f32_16x16x32_bf16 v[42:45], v[214:217], v[190:193], v[42:45]
	v_mfma_f32_16x16x32_bf16 v[38:41], v[238:241], v[190:193], v[38:41]
	v_mfma_f32_16x16x32_bf16 v[24:27], v[214:217], v[198:201], v[24:27]
	v_mfma_f32_16x16x32_bf16 v[20:23], v[238:241], v[198:201], v[20:23]
	v_mfma_f32_16x16x32_bf16 v[8:11], v[214:217], v[206:209], v[8:11]
	v_mfma_f32_16x16x32_bf16 v[4:7], v[238:241], v[206:209], v[4:7]
	v_mfma_f32_16x16x32_bf16 v[58:61], v[234:237], v[186:189], v[58:61]
	v_mfma_f32_16x16x32_bf16 v[54:57], v[242:245], v[186:189], v[54:57]
	v_mfma_f32_16x16x32_bf16 v[42:45], v[234:237], v[194:197], v[42:45]
	v_mfma_f32_16x16x32_bf16 v[38:41], v[242:245], v[194:197], v[38:41]
	v_mfma_f32_16x16x32_bf16 v[24:27], v[234:237], v[202:205], v[24:27]
	v_mfma_f32_16x16x32_bf16 v[20:23], v[242:245], v[202:205], v[20:23]
	v_mfma_f32_16x16x32_bf16 v[8:11], v[234:237], v[210:213], v[8:11]
	v_mfma_f32_16x16x32_bf16 v[4:7], v[242:245], v[210:213], v[4:7]
	s_add_i32 s1, 0, 0x18000
	v_add_u32_e32 v2, s1, v1
	s_barrier
	ds_read_b128 v[82:85], v2
	ds_read_b128 v[150:153], v2 offset:1024
	ds_read_b128 v[158:161], v2 offset:2048
	ds_read_b128 v[178:181], v2 offset:3072
	v_lshl_add_u64 v[80:81], v[174:175], 0, s[14:15]
	s_mov_b32 m0, s45
	v_lshl_add_u64 v[174:175], v[80:81], 0, v[162:163]
	ds_read_b128 v[182:185], v155 offset:32768
	ds_read_b128 v[186:189], v155 offset:33792
	ds_read_b128 v[190:193], v155 offset:34816
	ds_read_b128 v[194:197], v155 offset:35840
	ds_read_b128 v[198:201], v155 offset:36864
	ds_read_b128 v[202:205], v155 offset:37888
	ds_read_b128 v[206:209], v155 offset:38912
	ds_read_b128 v[210:213], v155 offset:39936
	global_load_lds_dwordx4 v[174:175], off
	v_lshl_add_u64 v[80:81], v[80:81], 0, v[164:165]
	s_mov_b32 m0, s46
	s_nop 0
	global_load_lds_dwordx4 v[80:81], off
	s_waitcnt lgkmcnt(8)
	s_barrier
	s_waitcnt lgkmcnt(0)
	s_waitcnt lgkmcnt(0)
	v_mfma_f32_16x16x32_bf16 v[146:149], v[82:85], v[182:185], v[146:149]
	v_mfma_f32_16x16x32_bf16 v[142:145], v[158:161], v[182:185], v[142:145]
	v_mfma_f32_16x16x32_bf16 v[130:133], v[82:85], v[190:193], v[130:133]
	v_mfma_f32_16x16x32_bf16 v[126:129], v[158:161], v[190:193], v[126:129]
	v_mfma_f32_16x16x32_bf16 v[114:117], v[82:85], v[198:201], v[114:117]
	v_mfma_f32_16x16x32_bf16 v[110:113], v[158:161], v[198:201], v[110:113]
	v_mfma_f32_16x16x32_bf16 v[98:101], v[82:85], v[206:209], v[98:101]
	v_mfma_f32_16x16x32_bf16 v[94:97], v[158:161], v[206:209], v[94:97]
	v_mfma_f32_16x16x32_bf16 v[146:149], v[150:153], v[186:189], v[146:149]
	v_mfma_f32_16x16x32_bf16 v[142:145], v[178:181], v[186:189], v[142:145]
	v_mfma_f32_16x16x32_bf16 v[130:133], v[150:153], v[194:197], v[130:133]
	v_mfma_f32_16x16x32_bf16 v[126:129], v[178:181], v[194:197], v[126:129]
	v_mfma_f32_16x16x32_bf16 v[114:117], v[150:153], v[202:205], v[114:117]
	v_mfma_f32_16x16x32_bf16 v[110:113], v[178:181], v[202:205], v[110:113]
	v_mfma_f32_16x16x32_bf16 v[98:101], v[150:153], v[210:213], v[98:101]
	v_mfma_f32_16x16x32_bf16 v[94:97], v[178:181], v[210:213], v[94:97]
	s_barrier
	s_add_i32 s6, 0, 0x1c000
	s_add_i32 s1, s1, s18
	v_add_u32_e32 v2, s6, v1
	v_lshl_add_u64 v[64:65], v[64:65], 0, s[24:25]
	s_mov_b32 m0, s1
	ds_read_b128 v[214:217], v2
	ds_read_b128 v[234:237], v2 offset:1024
	ds_read_b128 v[238:241], v2 offset:2048
	ds_read_b128 v[242:245], v2 offset:3072
	global_load_lds_dwordx4 v[64:65], off
	v_lshl_add_u64 v[64:65], v[230:231], 0, s[24:25]
	s_add_i32 m0, s1, 0x2000
	s_nop 0
	global_load_lds_dwordx4 v[64:65], off
	s_barrier
	s_waitcnt lgkmcnt(0)
	s_waitcnt lgkmcnt(0)
	v_mfma_f32_16x16x32_bf16 v[138:141], v[214:217], v[182:185], v[138:141]
	v_mfma_f32_16x16x32_bf16 v[134:137], v[238:241], v[182:185], v[134:137]
	v_mfma_f32_16x16x32_bf16 v[122:125], v[214:217], v[190:193], v[122:125]
	v_mfma_f32_16x16x32_bf16 v[118:121], v[238:241], v[190:193], v[118:121]
	v_mfma_f32_16x16x32_bf16 v[106:109], v[214:217], v[198:201], v[106:109]
	v_mfma_f32_16x16x32_bf16 v[102:105], v[238:241], v[198:201], v[102:105]
	v_mfma_f32_16x16x32_bf16 v[90:93], v[214:217], v[206:209], v[90:93]
	v_mfma_f32_16x16x32_bf16 v[86:89], v[238:241], v[206:209], v[86:89]
	v_mfma_f32_16x16x32_bf16 v[138:141], v[234:237], v[186:189], v[138:141]
	v_mfma_f32_16x16x32_bf16 v[134:137], v[242:245], v[186:189], v[134:137]
	v_mfma_f32_16x16x32_bf16 v[122:125], v[234:237], v[194:197], v[122:125]
	v_mfma_f32_16x16x32_bf16 v[118:121], v[242:245], v[194:197], v[118:121]
	v_mfma_f32_16x16x32_bf16 v[106:109], v[234:237], v[202:205], v[106:109]
	v_mfma_f32_16x16x32_bf16 v[102:105], v[242:245], v[202:205], v[102:105]
	v_mfma_f32_16x16x32_bf16 v[90:93], v[234:237], v[210:213], v[90:93]
	v_mfma_f32_16x16x32_bf16 v[86:89], v[242:245], v[210:213], v[86:89]
	s_mov_b32 m0, s47
	v_lshl_add_u64 v[64:65], v[246:247], 0, s[24:25]
	s_barrier
	ds_read_b128 v[182:185], v155 offset:49152
	ds_read_b128 v[186:189], v155 offset:50176
	ds_read_b128 v[190:193], v155 offset:51200
	ds_read_b128 v[194:197], v155 offset:52224
	ds_read_b128 v[198:201], v155 offset:53248
	ds_read_b128 v[202:205], v155 offset:54272
	ds_read_b128 v[206:209], v155 offset:55296
	ds_read_b128 v[210:213], v155 offset:56320
	global_load_lds_dwordx4 v[64:65], off
	v_lshl_add_u64 v[64:65], v[248:249], 0, s[24:25]
	s_mov_b32 m0, s48
	s_nop 0
	global_load_lds_dwordx4 v[64:65], off
	s_barrier
	s_waitcnt lgkmcnt(0)
	s_waitcnt lgkmcnt(0)
	v_mfma_f32_16x16x32_bf16 v[76:79], v[82:85], v[182:185], v[76:79]
	v_mfma_f32_16x16x32_bf16 v[70:73], v[158:161], v[182:185], v[70:73]
	v_mfma_f32_16x16x32_bf16 v[50:53], v[82:85], v[190:193], v[50:53]
	v_mfma_f32_16x16x32_bf16 v[46:49], v[158:161], v[190:193], v[46:49]
	v_mfma_f32_16x16x32_bf16 v[32:35], v[82:85], v[198:201], v[32:35]
	v_mfma_f32_16x16x32_bf16 v[28:31], v[158:161], v[198:201], v[28:31]
	v_mfma_f32_16x16x32_bf16 v[16:19], v[82:85], v[206:209], v[16:19]
	v_mfma_f32_16x16x32_bf16 v[12:15], v[158:161], v[206:209], v[12:15]
	v_mfma_f32_16x16x32_bf16 v[78:81], v[150:153], v[186:189], v[76:79]
	v_mfma_f32_16x16x32_bf16 v[70:73], v[178:181], v[186:189], v[70:73]
	v_mfma_f32_16x16x32_bf16 v[50:53], v[150:153], v[194:197], v[50:53]
	v_mfma_f32_16x16x32_bf16 v[46:49], v[178:181], v[194:197], v[46:49]
	v_mfma_f32_16x16x32_bf16 v[32:35], v[150:153], v[202:205], v[32:35]
	v_mfma_f32_16x16x32_bf16 v[28:31], v[178:181], v[202:205], v[28:31]
	v_mfma_f32_16x16x32_bf16 v[16:19], v[150:153], v[210:213], v[16:19]
	v_mfma_f32_16x16x32_bf16 v[12:15], v[178:181], v[210:213], v[12:15]
	s_barrier
	v_lshl_add_u64 v[64:65], v[68:69], 0, s[40:41]
	s_add_i32 s1, s6, s18
	v_lshl_add_u64 v[68:69], v[64:65], 0, v[162:163]
	s_mov_b32 m0, s1
	v_lshl_add_u64 v[64:65], v[64:65], 0, v[164:165]
	global_load_lds_dwordx4 v[68:69], off
	s_add_i32 m0, s1, 0x2000
	s_nop 0
	global_load_lds_dwordx4 v[64:65], off
	s_waitcnt vmcnt(6)
	s_barrier
	v_mfma_f32_16x16x32_bf16 v[58:61], v[214:217], v[182:185], v[58:61]
	v_mfma_f32_16x16x32_bf16 v[54:57], v[238:241], v[182:185], v[54:57]
	v_mfma_f32_16x16x32_bf16 v[42:45], v[214:217], v[190:193], v[42:45]
	v_mfma_f32_16x16x32_bf16 v[38:41], v[238:241], v[190:193], v[38:41]
	v_mfma_f32_16x16x32_bf16 v[24:27], v[214:217], v[198:201], v[24:27]
	v_mfma_f32_16x16x32_bf16 v[20:23], v[238:241], v[198:201], v[20:23]
	v_mfma_f32_16x16x32_bf16 v[8:11], v[214:217], v[206:209], v[8:11]
	v_mfma_f32_16x16x32_bf16 v[4:7], v[238:241], v[206:209], v[4:7]
	v_mfma_f32_16x16x32_bf16 v[58:61], v[234:237], v[186:189], v[58:61]
	v_mfma_f32_16x16x32_bf16 v[54:57], v[242:245], v[186:189], v[54:57]
	v_mfma_f32_16x16x32_bf16 v[42:45], v[234:237], v[194:197], v[42:45]
	v_mfma_f32_16x16x32_bf16 v[38:41], v[242:245], v[194:197], v[38:41]
	v_mfma_f32_16x16x32_bf16 v[24:27], v[234:237], v[202:205], v[24:27]
	v_mfma_f32_16x16x32_bf16 v[20:23], v[242:245], v[202:205], v[20:23]
	v_mfma_f32_16x16x32_bf16 v[8:11], v[234:237], v[210:213], v[8:11]
	v_mfma_f32_16x16x32_bf16 v[4:7], v[242:245], v[210:213], v[4:7]
	s_add_i32 s0, s0, 2
	v_lshl_add_u64 v[62:63], v[62:63], 0, s[74:75]
	s_cmp_gt_u32 s0, 19
	v_mov_b64_e32 v[64:65], v[66:67]
	s_barrier
	s_cbranch_scc0 .LBB0_81
	v_cmp_gt_i32_e32 vcc, 24, v176
	v_mov_b32_e32 v2, 0x3000
	v_mov_b32_e32 v62, 0x1800
	v_cndmask_b32_e32 v2, v2, v62, vcc
	v_cmp_lt_i32_e32 vcc, 15, v176
	v_lshl_or_b32 v150, v74, 8, v154
	v_ashrrev_i32_e32 v151, 31, v150
	v_cndmask_b32_e32 v2, 0, v2, vcc
	v_lshlrev_b32_e32 v2, 2, v2
	v_lshl_add_u64 v[62:63], s[12:13], 0, v[2:3]
	v_lshl_add_u64 v[62:63], v[150:151], 2, v[62:63]
	global_load_dwordx4 v[82:85], v[62:63], off
	global_load_dwordx4 v[74:77], v[62:63], off offset:64
	global_load_dwordx4 v[66:69], v[62:63], off offset:512
	s_nop 0
	global_load_dwordx4 v[62:65], v[62:63], off offset:576
	ds_bpermute_b32 v4, v250, v4
	ds_bpermute_b32 v5, v250, v5
	ds_bpermute_b32 v6, v250, v6
	ds_bpermute_b32 v7, v250, v7
	ds_bpermute_b32 v8, v250, v8
	ds_bpermute_b32 v9, v250, v9
	ds_bpermute_b32 v10, v250, v10
	ds_bpermute_b32 v11, v250, v11
	ds_bpermute_b32 v12, v250, v12
	ds_bpermute_b32 v13, v250, v13
	ds_bpermute_b32 v14, v250, v14
	ds_bpermute_b32 v15, v250, v15
	s_waitcnt lgkmcnt(0)
	ds_bpermute_b32 v16, v250, v16
	ds_bpermute_b32 v17, v250, v17
	ds_bpermute_b32 v18, v250, v18
	ds_bpermute_b32 v19, v250, v19
	ds_bpermute_b32 v20, v250, v20
	ds_bpermute_b32 v21, v250, v21
	ds_bpermute_b32 v22, v250, v22
	ds_bpermute_b32 v23, v250, v23
	ds_bpermute_b32 v24, v250, v24
	ds_bpermute_b32 v25, v250, v25
	ds_bpermute_b32 v26, v250, v26
	ds_bpermute_b32 v27, v250, v27
	s_waitcnt lgkmcnt(0)
	ds_bpermute_b32 v28, v250, v28
	ds_bpermute_b32 v29, v250, v29
	ds_bpermute_b32 v30, v250, v30
	ds_bpermute_b32 v31, v250, v31
	ds_bpermute_b32 v32, v250, v32
	ds_bpermute_b32 v33, v250, v33
	ds_bpermute_b32 v34, v250, v34
	ds_bpermute_b32 v35, v250, v35
	ds_bpermute_b32 v38, v250, v38
	ds_bpermute_b32 v39, v250, v39
	ds_bpermute_b32 v40, v250, v40
	ds_bpermute_b32 v41, v250, v41
	s_waitcnt lgkmcnt(0)
	ds_bpermute_b32 v42, v250, v42
	ds_bpermute_b32 v43, v250, v43
	ds_bpermute_b32 v44, v250, v44
	ds_bpermute_b32 v45, v250, v45
	ds_bpermute_b32 v46, v250, v46
	ds_bpermute_b32 v47, v250, v47
	ds_bpermute_b32 v48, v250, v48
	ds_bpermute_b32 v49, v250, v49
	ds_bpermute_b32 v50, v250, v50
	ds_bpermute_b32 v51, v250, v51
	ds_bpermute_b32 v52, v250, v52
	ds_bpermute_b32 v53, v250, v53
	s_waitcnt lgkmcnt(0)
	ds_bpermute_b32 v54, v250, v54
	ds_bpermute_b32 v55, v250, v55
	ds_bpermute_b32 v56, v250, v56
	ds_bpermute_b32 v57, v250, v57
	ds_bpermute_b32 v58, v250, v58
	ds_bpermute_b32 v59, v250, v59
	ds_bpermute_b32 v60, v250, v60
	ds_bpermute_b32 v61, v250, v61
	ds_bpermute_b32 v70, v250, v70
	ds_bpermute_b32 v71, v250, v71
	ds_bpermute_b32 v72, v250, v72
	ds_bpermute_b32 v73, v250, v73
	s_waitcnt lgkmcnt(0)
	ds_bpermute_b32 v78, v250, v78
	ds_bpermute_b32 v79, v250, v79
	ds_bpermute_b32 v80, v250, v80
	ds_bpermute_b32 v81, v250, v81
	ds_bpermute_b32 v86, v250, v86
	ds_bpermute_b32 v87, v250, v87
	ds_bpermute_b32 v88, v250, v88
	ds_bpermute_b32 v89, v250, v89
	ds_bpermute_b32 v90, v250, v90
	ds_bpermute_b32 v91, v250, v91
	ds_bpermute_b32 v92, v250, v92
	ds_bpermute_b32 v93, v250, v93
	s_waitcnt lgkmcnt(0)
	ds_bpermute_b32 v94, v250, v94
	ds_bpermute_b32 v95, v250, v95
	ds_bpermute_b32 v96, v250, v96
	ds_bpermute_b32 v97, v250, v97
	ds_bpermute_b32 v98, v250, v98
	ds_bpermute_b32 v99, v250, v99
	ds_bpermute_b32 v100, v250, v100
	ds_bpermute_b32 v101, v250, v101
	ds_bpermute_b32 v102, v250, v102
	ds_bpermute_b32 v103, v250, v103
	ds_bpermute_b32 v104, v250, v104
	ds_bpermute_b32 v105, v250, v105
	s_waitcnt lgkmcnt(0)
	ds_bpermute_b32 v106, v250, v106
	ds_bpermute_b32 v107, v250, v107
	ds_bpermute_b32 v108, v250, v108
	ds_bpermute_b32 v109, v250, v109
	ds_bpermute_b32 v110, v250, v110
	ds_bpermute_b32 v111, v250, v111
	ds_bpermute_b32 v112, v250, v112
	ds_bpermute_b32 v113, v250, v113
	ds_bpermute_b32 v114, v250, v114
	ds_bpermute_b32 v115, v250, v115
	ds_bpermute_b32 v116, v250, v116
	ds_bpermute_b32 v117, v250, v117
	s_waitcnt lgkmcnt(0)
	ds_bpermute_b32 v118, v250, v118
	ds_bpermute_b32 v119, v250, v119
	ds_bpermute_b32 v120, v250, v120
	ds_bpermute_b32 v121, v250, v121
	ds_bpermute_b32 v122, v250, v122
	ds_bpermute_b32 v123, v250, v123
	ds_bpermute_b32 v124, v250, v124
	ds_bpermute_b32 v125, v250, v125
	ds_bpermute_b32 v126, v250, v126
	ds_bpermute_b32 v127, v250, v127
	ds_bpermute_b32 v128, v250, v128
	ds_bpermute_b32 v129, v250, v129
	s_waitcnt lgkmcnt(0)
	ds_bpermute_b32 v130, v250, v130
	ds_bpermute_b32 v131, v250, v131
	ds_bpermute_b32 v132, v250, v132
	ds_bpermute_b32 v133, v250, v133
	ds_bpermute_b32 v134, v250, v134
	ds_bpermute_b32 v135, v250, v135
	ds_bpermute_b32 v136, v250, v136
	ds_bpermute_b32 v137, v250, v137
	ds_bpermute_b32 v138, v250, v138
	ds_bpermute_b32 v139, v250, v139
	ds_bpermute_b32 v140, v250, v140
	ds_bpermute_b32 v141, v250, v141
	s_waitcnt lgkmcnt(0)
	ds_bpermute_b32 v142, v250, v142
	ds_bpermute_b32 v143, v250, v143
	ds_bpermute_b32 v144, v250, v144
	ds_bpermute_b32 v145, v250, v145
	ds_bpermute_b32 v146, v250, v146
	ds_bpermute_b32 v147, v250, v147
	ds_bpermute_b32 v148, v250, v148
	ds_bpermute_b32 v149, v250, v149
	s_waitcnt lgkmcnt(0)
	s_cmp_eq_u32 s55, 0
	s_cselect_b64 s[6:7], -1, 0
	s_cmp_lg_u32 s55, 0
	s_mov_b64 s[40:41], 0xb0000
	s_cselect_b64 s[0:1], -1, 0
	v_add_u32_e32 v174, v37, v150
	v_mov_b32_e32 v175, v3
	v_lshlrev_b32_e32 v158, 8, v176
	v_ashrrev_i32_e32 v159, 31, v158
	v_lshlrev_b64 v[178:179], 12, v[158:159]
	v_lshl_add_u64 v[176:177], s[8:9], 0, v[178:179]
	s_and_b64 s[6:7], exec, s[6:7]
	s_cselect_b32 s7, s9, s35
	s_cselect_b32 s6, s8, s34
	v_lshl_add_u64 v[178:179], s[6:7], 0, v[178:179]
	s_and_b64 vcc, exec, s[0:1]
	s_cbranch_vccnz .Lrk_mul
	v_mov_b32_e32 v150, v174
	v_mov_b32_e32 v151, v3
	v_lshl_add_u64 v[152:153], v[150:151], 2, v[176:177]
	global_load_dwordx4 v[182:185], v[152:153], off
	global_load_dwordx4 v[186:189], v[152:153], off offset:64
	global_load_dwordx4 v[190:193], v[152:153], off offset:512
	global_load_dwordx4 v[194:197], v[152:153], off offset:576
	v_add_u32_e32 v150, 0x4000, v174
	v_mov_b32_e32 v151, v3
	v_lshl_add_u64 v[152:153], v[150:151], 2, v[176:177]
	global_load_dwordx4 v[198:201], v[152:153], off
	global_load_dwordx4 v[202:205], v[152:153], off offset:64
	global_load_dwordx4 v[206:209], v[152:153], off offset:512
	global_load_dwordx4 v[210:213], v[152:153], off offset:576
	v_add_u32_e32 v150, 0x8000, v174
	v_mov_b32_e32 v151, v3
	v_lshl_add_u64 v[152:153], v[150:151], 2, v[176:177]
	global_load_dwordx4 v[214:217], v[152:153], off
	global_load_dwordx4 v[234:237], v[152:153], off offset:64
	global_load_dwordx4 v[238:241], v[152:153], off offset:512
	global_load_dwordx4 v[242:245], v[152:153], off offset:576
	v_mov_b32_e32 v150, v174
	v_mov_b32_e32 v151, v3
	v_lshl_add_u64 v[158:159], v[150:151], 2, v[178:179]
	s_waitcnt vmcnt(11)
	v_pk_fma_f32 v[148:149], v[148:149], v[84:85], v[184:185]
	v_pk_fma_f32 v[146:147], v[146:147], v[82:83], v[182:183]
	global_store_dwordx4 v[158:159], v[146:149], off
	v_add_u32_e32 v150, 0xc000, v174
	v_mov_b32_e32 v151, v3
	v_lshl_add_u64 v[152:153], v[150:151], 2, v[176:177]
	global_load_dwordx4 v[182:185], v[152:153], off
	s_waitcnt vmcnt(12)
	v_pk_fma_f32 v[144:145], v[144:145], v[76:77], v[188:189]
	v_pk_fma_f32 v[142:143], v[142:143], v[74:75], v[186:187]
	global_store_dwordx4 v[158:159], v[142:145], off offset:64
	global_load_dwordx4 v[186:189], v[152:153], off offset:64
	s_waitcnt vmcnt(13)
	v_pk_fma_f32 v[140:141], v[140:141], v[68:69], v[192:193]
	v_pk_fma_f32 v[138:139], v[138:139], v[66:67], v[190:191]
	global_store_dwordx4 v[158:159], v[138:141], off offset:512
	global_load_dwordx4 v[190:193], v[152:153], off offset:512
	s_waitcnt vmcnt(14)
	v_pk_fma_f32 v[136:137], v[136:137], v[64:65], v[196:197]
	v_pk_fma_f32 v[134:135], v[134:135], v[62:63], v[194:195]
	global_store_dwordx4 v[158:159], v[134:137], off offset:576
	global_load_dwordx4 v[194:197], v[152:153], off offset:576
	v_add_u32_e32 v150, 0x4000, v174
	v_mov_b32_e32 v151, v3
	v_lshl_add_u64 v[158:159], v[150:151], 2, v[178:179]
	s_waitcnt vmcnt(15)
	v_pk_fma_f32 v[132:133], v[132:133], v[84:85], v[200:201]
	v_pk_fma_f32 v[130:131], v[130:131], v[82:83], v[198:199]
	global_store_dwordx4 v[158:159], v[130:133], off
	v_add_u32_e32 v150, 0x20000, v174
	v_mov_b32_e32 v151, v3
	v_lshl_add_u64 v[152:153], v[150:151], 2, v[176:177]
	global_load_dwordx4 v[198:201], v[152:153], off
	s_waitcnt vmcnt(16)
	v_pk_fma_f32 v[128:129], v[128:129], v[76:77], v[204:205]
	v_pk_fma_f32 v[126:127], v[126:127], v[74:75], v[202:203]
	global_store_dwordx4 v[158:159], v[126:129], off offset:64
	global_load_dwordx4 v[202:205], v[152:153], off offset:64
	s_waitcnt vmcnt(17)
	v_pk_fma_f32 v[124:125], v[124:125], v[68:69], v[208:209]
	v_pk_fma_f32 v[122:123], v[122:123], v[66:67], v[206:207]
	global_store_dwordx4 v[158:159], v[122:125], off offset:512
	global_load_dwordx4 v[206:209], v[152:153], off offset:512
	s_waitcnt vmcnt(18)
	v_pk_fma_f32 v[120:121], v[120:121], v[64:65], v[212:213]
	v_pk_fma_f32 v[118:119], v[118:119], v[62:63], v[210:211]
	global_store_dwordx4 v[158:159], v[118:121], off offset:576
	global_load_dwordx4 v[210:213], v[152:153], off offset:576
	v_add_u32_e32 v150, 0x8000, v174
	v_mov_b32_e32 v151, v3
	v_lshl_add_u64 v[158:159], v[150:151], 2, v[178:179]
	s_waitcnt vmcnt(19)
	v_pk_fma_f32 v[116:117], v[116:117], v[84:85], v[216:217]
	v_pk_fma_f32 v[114:115], v[114:115], v[82:83], v[214:215]
	global_store_dwordx4 v[158:159], v[114:117], off
	v_add_u32_e32 v150, 0x24000, v174
	v_mov_b32_e32 v151, v3
	v_lshl_add_u64 v[152:153], v[150:151], 2, v[176:177]
	global_load_dwordx4 v[214:217], v[152:153], off
	s_waitcnt vmcnt(20)
	v_pk_fma_f32 v[112:113], v[112:113], v[76:77], v[236:237]
	v_pk_fma_f32 v[110:111], v[110:111], v[74:75], v[234:235]
	global_store_dwordx4 v[158:159], v[110:113], off offset:64
	global_load_dwordx4 v[234:237], v[152:153], off offset:64
	s_waitcnt vmcnt(21)
	v_pk_fma_f32 v[108:109], v[108:109], v[68:69], v[240:241]
	v_pk_fma_f32 v[106:107], v[106:107], v[66:67], v[238:239]
	global_store_dwordx4 v[158:159], v[106:109], off offset:512
	global_load_dwordx4 v[238:241], v[152:153], off offset:512
	s_waitcnt vmcnt(22)
	v_pk_fma_f32 v[104:105], v[104:105], v[64:65], v[244:245]
	v_pk_fma_f32 v[102:103], v[102:103], v[62:63], v[242:243]
	global_store_dwordx4 v[158:159], v[102:105], off offset:576
	global_load_dwordx4 v[242:245], v[152:153], off offset:576
	v_add_u32_e32 v150, 0xc000, v174
	v_mov_b32_e32 v151, v3
	v_lshl_add_u64 v[158:159], v[150:151], 2, v[178:179]
	s_waitcnt vmcnt(22)
	v_pk_fma_f32 v[100:101], v[100:101], v[84:85], v[184:185]
	v_pk_fma_f32 v[98:99], v[98:99], v[82:83], v[182:183]
	global_store_dwordx4 v[158:159], v[98:101], off
	v_add_u32_e32 v150, 0x28000, v174
	v_mov_b32_e32 v151, v3
	v_lshl_add_u64 v[152:153], v[150:151], 2, v[176:177]
	global_load_dwordx4 v[182:185], v[152:153], off
	s_waitcnt vmcnt(22)
	v_pk_fma_f32 v[96:97], v[96:97], v[76:77], v[188:189]
	v_pk_fma_f32 v[94:95], v[94:95], v[74:75], v[186:187]
	global_store_dwordx4 v[158:159], v[94:97], off offset:64
	global_load_dwordx4 v[186:189], v[152:153], off offset:64
	s_waitcnt vmcnt(22)
	v_pk_fma_f32 v[92:93], v[92:93], v[68:69], v[192:193]
	v_pk_fma_f32 v[90:91], v[90:91], v[66:67], v[190:191]
	global_store_dwordx4 v[158:159], v[90:93], off offset:512
	global_load_dwordx4 v[190:193], v[152:153], off offset:512
	s_waitcnt vmcnt(22)
	v_pk_fma_f32 v[88:89], v[88:89], v[64:65], v[196:197]
	v_pk_fma_f32 v[86:87], v[86:87], v[62:63], v[194:195]
	global_store_dwordx4 v[158:159], v[86:89], off offset:576
	global_load_dwordx4 v[194:197], v[152:153], off offset:576
	v_add_u32_e32 v150, 0x20000, v174
	v_mov_b32_e32 v151, v3
	v_lshl_add_u64 v[158:159], v[150:151], 2, v[178:179]
	s_waitcnt vmcnt(22)
	v_pk_fma_f32 v[80:81], v[80:81], v[84:85], v[200:201]
	v_pk_fma_f32 v[78:79], v[78:79], v[82:83], v[198:199]
	global_store_dwordx4 v[158:159], v[78:81], off
	v_add_u32_e32 v150, 0x2c000, v174
	v_mov_b32_e32 v151, v3
	v_lshl_add_u64 v[152:153], v[150:151], 2, v[176:177]
	global_load_dwordx4 v[198:201], v[152:153], off
	s_waitcnt vmcnt(22)
	v_pk_fma_f32 v[72:73], v[72:73], v[76:77], v[204:205]
	v_pk_fma_f32 v[70:71], v[70:71], v[74:75], v[202:203]
	global_store_dwordx4 v[158:159], v[70:73], off offset:64
	global_load_dwordx4 v[202:205], v[152:153], off offset:64
	s_waitcnt vmcnt(22)
	v_pk_fma_f32 v[60:61], v[60:61], v[68:69], v[208:209]
	v_pk_fma_f32 v[58:59], v[58:59], v[66:67], v[206:207]
	global_store_dwordx4 v[158:159], v[58:61], off offset:512
	global_load_dwordx4 v[206:209], v[152:153], off offset:512
	s_waitcnt vmcnt(22)
	v_pk_fma_f32 v[56:57], v[56:57], v[64:65], v[212:213]
	v_pk_fma_f32 v[54:55], v[54:55], v[62:63], v[210:211]
	global_store_dwordx4 v[158:159], v[54:57], off offset:576
	global_load_dwordx4 v[210:213], v[152:153], off offset:576
	v_add_u32_e32 v150, 0x24000, v174
	v_mov_b32_e32 v151, v3
	v_lshl_add_u64 v[158:159], v[150:151], 2, v[178:179]
	s_waitcnt vmcnt(22)
	v_pk_fma_f32 v[52:53], v[52:53], v[84:85], v[216:217]
	v_pk_fma_f32 v[50:51], v[50:51], v[82:83], v[214:215]
	global_store_dwordx4 v[158:159], v[50:53], off
	s_waitcnt vmcnt(21)
	v_pk_fma_f32 v[48:49], v[48:49], v[76:77], v[236:237]
	v_pk_fma_f32 v[46:47], v[46:47], v[74:75], v[234:235]
	global_store_dwordx4 v[158:159], v[46:49], off offset:64
	s_waitcnt vmcnt(20)
	v_pk_fma_f32 v[44:45], v[44:45], v[68:69], v[240:241]
	v_pk_fma_f32 v[42:43], v[42:43], v[66:67], v[238:239]
	global_store_dwordx4 v[158:159], v[42:45], off offset:512
	s_waitcnt vmcnt(19)
	v_pk_fma_f32 v[40:41], v[40:41], v[64:65], v[244:245]
	v_pk_fma_f32 v[38:39], v[38:39], v[62:63], v[242:243]
	global_store_dwordx4 v[158:159], v[38:41], off offset:576
	v_add_u32_e32 v150, 0x28000, v174
	v_mov_b32_e32 v151, v3
	v_lshl_add_u64 v[158:159], v[150:151], 2, v[178:179]
	s_waitcnt vmcnt(18)
	v_pk_fma_f32 v[34:35], v[34:35], v[84:85], v[184:185]
	v_pk_fma_f32 v[32:33], v[32:33], v[82:83], v[182:183]
	global_store_dwordx4 v[158:159], v[32:35], off
	s_waitcnt vmcnt(17)
	v_pk_fma_f32 v[30:31], v[30:31], v[76:77], v[188:189]
	v_pk_fma_f32 v[28:29], v[28:29], v[74:75], v[186:187]
	global_store_dwordx4 v[158:159], v[28:31], off offset:64
	s_waitcnt vmcnt(16)
	v_pk_fma_f32 v[26:27], v[26:27], v[68:69], v[192:193]
	v_pk_fma_f32 v[24:25], v[24:25], v[66:67], v[190:191]
	global_store_dwordx4 v[158:159], v[24:27], off offset:512
	s_waitcnt vmcnt(15)
	v_pk_fma_f32 v[22:23], v[22:23], v[64:65], v[196:197]
	v_pk_fma_f32 v[20:21], v[20:21], v[62:63], v[194:195]
	global_store_dwordx4 v[158:159], v[20:23], off offset:576
	v_add_u32_e32 v150, 0x2c000, v174
	v_mov_b32_e32 v151, v3
	v_lshl_add_u64 v[158:159], v[150:151], 2, v[178:179]
	s_waitcnt vmcnt(14)
	v_pk_fma_f32 v[18:19], v[18:19], v[84:85], v[200:201]
	v_pk_fma_f32 v[16:17], v[16:17], v[82:83], v[198:199]
	global_store_dwordx4 v[158:159], v[16:19], off
	s_waitcnt vmcnt(13)
	v_pk_fma_f32 v[14:15], v[14:15], v[76:77], v[204:205]
	v_pk_fma_f32 v[12:13], v[12:13], v[74:75], v[202:203]
	global_store_dwordx4 v[158:159], v[12:15], off offset:64
	s_waitcnt vmcnt(12)
	v_pk_fma_f32 v[10:11], v[10:11], v[68:69], v[208:209]
	v_pk_fma_f32 v[8:9], v[8:9], v[66:67], v[206:207]
	global_store_dwordx4 v[158:159], v[8:11], off offset:512
	s_waitcnt vmcnt(11)
	v_pk_fma_f32 v[6:7], v[6:7], v[64:65], v[212:213]
	v_pk_fma_f32 v[4:5], v[4:5], v[62:63], v[210:211]
	global_store_dwordx4 v[158:159], v[4:7], off offset:576
	s_branch .Lrk_tail

.LBB0_245:
	s_add_u32 s16, s14, 0xfffc0080
	s_addc_u32 s17, s15, -1
	s_add_i32 s83, 0, 0x10000
	v_add_u32_e32 v158, s83, v37
	ds_read_b128 v[144:147], v158
	ds_read_b128 v[150:153], v158 offset:1024
	ds_read_b128 v[154:157], v158 offset:2048
	ds_read_b128 v[158:161], v158 offset:3072
	s_cmp_eq_u32 s82, 12
	s_cselect_b32 s19, s7, s17
	s_cselect_b32 s18, s78, s16
	s_cselect_b32 s17, s1, s81
	s_cselect_b32 s16, s79, s80
	v_lshl_add_u64 v[194:195], s[14:15], 0, v[140:141]
	s_add_i32 m0, s9, 0xc000
	ds_read_b128 v[162:165], v149
	ds_read_b128 v[166:169], v149 offset:1024
	ds_read_b128 v[170:173], v149 offset:2048
	ds_read_b128 v[174:177], v149 offset:3072
	ds_read_b128 v[178:181], v149 offset:4096
	ds_read_b128 v[182:185], v149 offset:5120
	ds_read_b128 v[186:189], v149 offset:6144
	ds_read_b128 v[190:193], v149 offset:7168
	global_load_lds_dwordx4 v[194:195], off
	v_lshl_add_u64 v[194:195], s[14:15], 0, v[142:143]
	s_add_i32 m0, s9, 0xe000
	s_nop 0
	global_load_lds_dwordx4 v[194:195], off
	s_waitcnt lgkmcnt(8)
	s_barrier
	s_waitcnt lgkmcnt(0)
	s_waitcnt lgkmcnt(0)
	v_mfma_f32_16x16x32_bf16 v[130:133], v[144:147], v[162:165], v[130:133]
	v_mfma_f32_16x16x32_bf16 v[126:129], v[154:157], v[162:165], v[126:129]
	v_mfma_f32_16x16x32_bf16 v[122:125], v[144:147], v[170:173], v[122:125]
	v_mfma_f32_16x16x32_bf16 v[114:117], v[154:157], v[170:173], v[114:117]
	v_mfma_f32_16x16x32_bf16 v[106:109], v[144:147], v[178:181], v[106:109]
	v_mfma_f32_16x16x32_bf16 v[98:101], v[154:157], v[178:181], v[98:101]
	v_mfma_f32_16x16x32_bf16 v[90:93], v[144:147], v[186:189], v[90:93]
	v_mfma_f32_16x16x32_bf16 v[82:85], v[154:157], v[186:189], v[82:85]
	v_mfma_f32_16x16x32_bf16 v[130:133], v[150:153], v[166:169], v[130:133]
	v_mfma_f32_16x16x32_bf16 v[126:129], v[158:161], v[166:169], v[126:129]
	v_mfma_f32_16x16x32_bf16 v[122:125], v[150:153], v[174:177], v[122:125]
	v_mfma_f32_16x16x32_bf16 v[114:117], v[158:161], v[174:177], v[114:117]
	v_mfma_f32_16x16x32_bf16 v[106:109], v[150:153], v[182:185], v[106:109]
	v_mfma_f32_16x16x32_bf16 v[98:101], v[158:161], v[182:185], v[98:101]
	v_mfma_f32_16x16x32_bf16 v[90:93], v[150:153], v[190:193], v[90:93]
	v_mfma_f32_16x16x32_bf16 v[82:85], v[158:161], v[190:193], v[82:85]
	s_barrier
	s_add_i32 s86, 0, 0x14000
	s_add_i32 s83, s83, s45
	v_add_u32_e32 v206, s86, v37
	v_lshl_add_u64 v[210:211], s[16:17], 0, v[2:3]
	s_mov_b32 m0, s83
	ds_read_b128 v[194:197], v206
	ds_read_b128 v[198:201], v206 offset:1024
	ds_read_b128 v[202:205], v206 offset:2048
	ds_read_b128 v[206:209], v206 offset:3072
	global_load_lds_dwordx4 v[210:211], off
	v_lshl_add_u64 v[212:213], s[16:17], 0, v[134:135]
	s_add_i32 m0, s83, 0x2000
	s_nop 0
	global_load_lds_dwordx4 v[212:213], off
	s_barrier
	s_waitcnt lgkmcnt(0)
	s_waitcnt lgkmcnt(0)
	v_mfma_f32_16x16x32_bf16 v[118:121], v[194:197], v[162:165], v[118:121]
	v_mfma_f32_16x16x32_bf16 v[110:113], v[202:205], v[162:165], v[110:113]
	v_mfma_f32_16x16x32_bf16 v[102:105], v[194:197], v[170:173], v[102:105]
	v_mfma_f32_16x16x32_bf16 v[94:97], v[202:205], v[170:173], v[94:97]
	v_mfma_f32_16x16x32_bf16 v[86:89], v[194:197], v[178:181], v[86:89]
	v_mfma_f32_16x16x32_bf16 v[78:81], v[202:205], v[178:181], v[78:81]
	v_mfma_f32_16x16x32_bf16 v[74:77], v[194:197], v[186:189], v[74:77]
	v_mfma_f32_16x16x32_bf16 v[70:73], v[202:205], v[186:189], v[70:73]
	v_mfma_f32_16x16x32_bf16 v[118:121], v[198:201], v[166:169], v[118:121]
	v_mfma_f32_16x16x32_bf16 v[110:113], v[206:209], v[166:169], v[110:113]
	v_mfma_f32_16x16x32_bf16 v[102:105], v[198:201], v[174:177], v[102:105]
	v_mfma_f32_16x16x32_bf16 v[94:97], v[206:209], v[174:177], v[94:97]
	v_mfma_f32_16x16x32_bf16 v[86:89], v[198:201], v[182:185], v[86:89]
	v_mfma_f32_16x16x32_bf16 v[78:81], v[206:209], v[182:185], v[78:81]
	v_mfma_f32_16x16x32_bf16 v[74:77], v[198:201], v[190:193], v[74:77]
	v_mfma_f32_16x16x32_bf16 v[70:73], v[206:209], v[190:193], v[70:73]
	s_mov_b32 m0, s9
	v_lshl_add_u64 v[214:215], s[18:19], 0, v[138:139]
	s_barrier
	ds_read_b128 v[162:165], v149 offset:16384
	ds_read_b128 v[166:169], v149 offset:17408
	ds_read_b128 v[170:173], v149 offset:18432
	ds_read_b128 v[174:177], v149 offset:19456
	ds_read_b128 v[178:181], v149 offset:20480
	ds_read_b128 v[182:185], v149 offset:21504
	ds_read_b128 v[186:189], v149 offset:22528
	ds_read_b128 v[190:193], v149 offset:23552
	global_load_lds_dwordx4 v[214:215], off
	v_lshl_add_u64 v[216:217], s[18:19], 0, v[136:137]
	s_mov_b32 m0, s49
	s_nop 0
	global_load_lds_dwordx4 v[216:217], off
	s_barrier
	s_waitcnt lgkmcnt(0)
	s_waitcnt lgkmcnt(0)
	v_mfma_f32_16x16x32_bf16 v[66:69], v[144:147], v[162:165], v[66:69]
	v_mfma_f32_16x16x32_bf16 v[62:65], v[154:157], v[162:165], v[62:65]
	v_mfma_f32_16x16x32_bf16 v[58:61], v[144:147], v[170:173], v[58:61]
	v_mfma_f32_16x16x32_bf16 v[50:53], v[154:157], v[170:173], v[50:53]
	v_mfma_f32_16x16x32_bf16 v[42:45], v[144:147], v[178:181], v[42:45]
	v_mfma_f32_16x16x32_bf16 v[32:35], v[154:157], v[178:181], v[32:35]
	v_mfma_f32_16x16x32_bf16 v[24:27], v[144:147], v[186:189], v[24:27]
	v_mfma_f32_16x16x32_bf16 v[16:19], v[154:157], v[186:189], v[16:19]
	v_mfma_f32_16x16x32_bf16 v[66:69], v[150:153], v[166:169], v[66:69]
	v_mfma_f32_16x16x32_bf16 v[62:65], v[158:161], v[166:169], v[62:65]
	v_mfma_f32_16x16x32_bf16 v[58:61], v[150:153], v[174:177], v[58:61]
	v_mfma_f32_16x16x32_bf16 v[50:53], v[158:161], v[174:177], v[50:53]
	v_mfma_f32_16x16x32_bf16 v[42:45], v[150:153], v[182:185], v[42:45]
	v_mfma_f32_16x16x32_bf16 v[32:35], v[158:161], v[182:185], v[32:35]
	v_mfma_f32_16x16x32_bf16 v[24:27], v[150:153], v[190:193], v[24:27]
	v_mfma_f32_16x16x32_bf16 v[16:19], v[158:161], v[190:193], v[16:19]
	s_barrier
	s_add_u32 s84, s16, 0x40000
	s_addc_u32 s85, s17, 0
	s_add_i32 s83, s86, s45
	v_lshl_add_u64 v[144:145], s[84:85], 0, v[2:3]
	s_mov_b32 m0, s83
	s_nop 0
	global_load_lds_dwordx4 v[144:145], off
	v_lshl_add_u64 v[144:145], s[84:85], 0, v[134:135]
	s_add_i32 m0, s83, 0x2000
	s_nop 0
	global_load_lds_dwordx4 v[144:145], off
	s_waitcnt vmcnt(6)
	s_barrier
	v_mfma_f32_16x16x32_bf16 v[54:57], v[194:197], v[162:165], v[54:57]
	v_mfma_f32_16x16x32_bf16 v[46:49], v[202:205], v[162:165], v[46:49]
	v_mfma_f32_16x16x32_bf16 v[38:41], v[194:197], v[170:173], v[38:41]
	v_mfma_f32_16x16x32_bf16 v[28:31], v[202:205], v[170:173], v[28:31]
	v_mfma_f32_16x16x32_bf16 v[20:23], v[194:197], v[178:181], v[20:23]
	v_mfma_f32_16x16x32_bf16 v[12:15], v[202:205], v[178:181], v[12:15]
	v_mfma_f32_16x16x32_bf16 v[8:11], v[194:197], v[186:189], v[8:11]
	v_mfma_f32_16x16x32_bf16 v[4:7], v[202:205], v[186:189], v[4:7]
	v_mfma_f32_16x16x32_bf16 v[54:57], v[198:201], v[166:169], v[54:57]
	v_mfma_f32_16x16x32_bf16 v[46:49], v[206:209], v[166:169], v[46:49]
	v_mfma_f32_16x16x32_bf16 v[38:41], v[198:201], v[174:177], v[38:41]
	v_mfma_f32_16x16x32_bf16 v[28:31], v[206:209], v[174:177], v[28:31]
	v_mfma_f32_16x16x32_bf16 v[20:23], v[198:201], v[182:185], v[20:23]
	v_mfma_f32_16x16x32_bf16 v[12:15], v[206:209], v[182:185], v[12:15]
	v_mfma_f32_16x16x32_bf16 v[8:11], v[198:201], v[190:193], v[8:11]
	v_mfma_f32_16x16x32_bf16 v[4:7], v[206:209], v[190:193], v[4:7]
	s_add_i32 s83, 0, 0x18000
	v_add_u32_e32 v158, s83, v37
	s_barrier
	ds_read_b128 v[144:147], v158
	ds_read_b128 v[150:153], v158 offset:1024
	ds_read_b128 v[154:157], v158 offset:2048
	ds_read_b128 v[158:161], v158 offset:3072
	s_add_u32 s18, s18, 0x40000
	s_addc_u32 s19, s19, 0
	s_mov_b32 m0, s52
	v_lshl_add_u64 v[194:195], s[18:19], 0, v[138:139]
	ds_read_b128 v[162:165], v149 offset:32768
	ds_read_b128 v[166:169], v149 offset:33792
	ds_read_b128 v[170:173], v149 offset:34816
	ds_read_b128 v[174:177], v149 offset:35840
	ds_read_b128 v[178:181], v149 offset:36864
	ds_read_b128 v[182:185], v149 offset:37888
	ds_read_b128 v[186:189], v149 offset:38912
	ds_read_b128 v[190:193], v149 offset:39936
	global_load_lds_dwordx4 v[194:195], off
	v_lshl_add_u64 v[194:195], s[18:19], 0, v[136:137]
	s_mov_b32 m0, s53
	s_nop 0
	global_load_lds_dwordx4 v[194:195], off
	s_waitcnt lgkmcnt(8)
	s_barrier
	s_waitcnt lgkmcnt(0)
	s_waitcnt lgkmcnt(0)
	v_mfma_f32_16x16x32_bf16 v[130:133], v[144:147], v[162:165], v[130:133]
	v_mfma_f32_16x16x32_bf16 v[126:129], v[154:157], v[162:165], v[126:129]
	v_mfma_f32_16x16x32_bf16 v[122:125], v[144:147], v[170:173], v[122:125]
	v_mfma_f32_16x16x32_bf16 v[114:117], v[154:157], v[170:173], v[114:117]
	v_mfma_f32_16x16x32_bf16 v[106:109], v[144:147], v[178:181], v[106:109]
	v_mfma_f32_16x16x32_bf16 v[98:101], v[154:157], v[178:181], v[98:101]
	v_mfma_f32_16x16x32_bf16 v[90:93], v[144:147], v[186:189], v[90:93]
	v_mfma_f32_16x16x32_bf16 v[82:85], v[154:157], v[186:189], v[82:85]
	v_mfma_f32_16x16x32_bf16 v[130:133], v[150:153], v[166:169], v[130:133]
	v_mfma_f32_16x16x32_bf16 v[126:129], v[158:161], v[166:169], v[126:129]
	v_mfma_f32_16x16x32_bf16 v[122:125], v[150:153], v[174:177], v[122:125]
	v_mfma_f32_16x16x32_bf16 v[114:117], v[158:161], v[174:177], v[114:117]
	v_mfma_f32_16x16x32_bf16 v[106:109], v[150:153], v[182:185], v[106:109]
	v_mfma_f32_16x16x32_bf16 v[98:101], v[158:161], v[182:185], v[98:101]
	v_mfma_f32_16x16x32_bf16 v[90:93], v[150:153], v[190:193], v[90:93]
	v_mfma_f32_16x16x32_bf16 v[82:85], v[158:161], v[190:193], v[82:85]
	s_barrier
	s_add_i32 s18, 0, 0x1c000
	s_add_i32 s19, s83, s45
	v_add_u32_e32 v206, s18, v37
	v_lshl_add_u64 v[210:211], v[210:211], 0, s[24:25]
	s_mov_b32 m0, s19
	ds_read_b128 v[194:197], v206
	ds_read_b128 v[198:201], v206 offset:1024
	ds_read_b128 v[202:205], v206 offset:2048
	ds_read_b128 v[206:209], v206 offset:3072
	global_load_lds_dwordx4 v[210:211], off
	v_lshl_add_u64 v[210:211], v[212:213], 0, s[24:25]
	s_add_i32 m0, s19, 0x2000
	s_nop 0
	global_load_lds_dwordx4 v[210:211], off
	s_barrier
	s_waitcnt lgkmcnt(0)
	s_waitcnt lgkmcnt(0)
	v_mfma_f32_16x16x32_bf16 v[118:121], v[194:197], v[162:165], v[118:121]
	v_mfma_f32_16x16x32_bf16 v[110:113], v[202:205], v[162:165], v[110:113]
	v_mfma_f32_16x16x32_bf16 v[102:105], v[194:197], v[170:173], v[102:105]
	v_mfma_f32_16x16x32_bf16 v[94:97], v[202:205], v[170:173], v[94:97]
	v_mfma_f32_16x16x32_bf16 v[86:89], v[194:197], v[178:181], v[86:89]
	v_mfma_f32_16x16x32_bf16 v[78:81], v[202:205], v[178:181], v[78:81]
	v_mfma_f32_16x16x32_bf16 v[74:77], v[194:197], v[186:189], v[74:77]
	v_mfma_f32_16x16x32_bf16 v[70:73], v[202:205], v[186:189], v[70:73]
	v_mfma_f32_16x16x32_bf16 v[118:121], v[198:201], v[166:169], v[118:121]
	v_mfma_f32_16x16x32_bf16 v[110:113], v[206:209], v[166:169], v[110:113]
	v_mfma_f32_16x16x32_bf16 v[102:105], v[198:201], v[174:177], v[102:105]
	v_mfma_f32_16x16x32_bf16 v[94:97], v[206:209], v[174:177], v[94:97]
	v_mfma_f32_16x16x32_bf16 v[86:89], v[198:201], v[182:185], v[86:89]
	v_mfma_f32_16x16x32_bf16 v[78:81], v[206:209], v[182:185], v[78:81]
	v_mfma_f32_16x16x32_bf16 v[74:77], v[198:201], v[190:193], v[74:77]
	v_mfma_f32_16x16x32_bf16 v[70:73], v[206:209], v[190:193], v[70:73]
	s_mov_b32 m0, s55
	v_lshl_add_u64 v[210:211], v[214:215], 0, s[24:25]
	s_barrier
	ds_read_b128 v[162:165], v149 offset:49152
	ds_read_b128 v[166:169], v149 offset:50176
	ds_read_b128 v[170:173], v149 offset:51200
	ds_read_b128 v[174:177], v149 offset:52224
	ds_read_b128 v[178:181], v149 offset:53248
	ds_read_b128 v[182:185], v149 offset:54272
	ds_read_b128 v[186:189], v149 offset:55296
	ds_read_b128 v[190:193], v149 offset:56320
	global_load_lds_dwordx4 v[210:211], off
	v_lshl_add_u64 v[210:211], v[216:217], 0, s[24:25]
	s_mov_b32 m0, s74
	s_nop 0
	global_load_lds_dwordx4 v[210:211], off
	s_barrier
	s_waitcnt lgkmcnt(0)
	s_waitcnt lgkmcnt(0)
	v_mfma_f32_16x16x32_bf16 v[66:69], v[144:147], v[162:165], v[66:69]
	v_mfma_f32_16x16x32_bf16 v[62:65], v[154:157], v[162:165], v[62:65]
	v_mfma_f32_16x16x32_bf16 v[58:61], v[144:147], v[170:173], v[58:61]
	v_mfma_f32_16x16x32_bf16 v[50:53], v[154:157], v[170:173], v[50:53]
	v_mfma_f32_16x16x32_bf16 v[42:45], v[144:147], v[178:181], v[42:45]
	v_mfma_f32_16x16x32_bf16 v[32:35], v[154:157], v[178:181], v[32:35]
	v_mfma_f32_16x16x32_bf16 v[24:27], v[144:147], v[186:189], v[24:27]
	v_mfma_f32_16x16x32_bf16 v[16:19], v[154:157], v[186:189], v[16:19]
	v_mfma_f32_16x16x32_bf16 v[66:69], v[150:153], v[166:169], v[66:69]
	v_mfma_f32_16x16x32_bf16 v[62:65], v[158:161], v[166:169], v[62:65]
	v_mfma_f32_16x16x32_bf16 v[58:61], v[150:153], v[174:177], v[58:61]
	v_mfma_f32_16x16x32_bf16 v[50:53], v[158:161], v[174:177], v[50:53]
	v_mfma_f32_16x16x32_bf16 v[42:45], v[150:153], v[182:185], v[42:45]
	v_mfma_f32_16x16x32_bf16 v[32:35], v[158:161], v[182:185], v[32:35]
	v_mfma_f32_16x16x32_bf16 v[24:27], v[150:153], v[190:193], v[24:27]
	v_mfma_f32_16x16x32_bf16 v[16:19], v[158:161], v[190:193], v[16:19]
	s_barrier
	s_add_u32 s16, s16, 0x40080
	s_addc_u32 s17, s17, 0
	s_add_i32 s18, s18, s45
	v_lshl_add_u64 v[144:145], s[16:17], 0, v[2:3]
	s_mov_b32 m0, s18
	s_nop 0
	global_load_lds_dwordx4 v[144:145], off
	v_lshl_add_u64 v[144:145], s[16:17], 0, v[134:135]
	s_add_i32 m0, s18, 0x2000
	s_nop 0
	global_load_lds_dwordx4 v[144:145], off
	s_waitcnt vmcnt(6)
	s_barrier
	v_mfma_f32_16x16x32_bf16 v[54:57], v[194:197], v[162:165], v[54:57]
	v_mfma_f32_16x16x32_bf16 v[46:49], v[202:205], v[162:165], v[46:49]
	v_mfma_f32_16x16x32_bf16 v[38:41], v[194:197], v[170:173], v[38:41]
	v_mfma_f32_16x16x32_bf16 v[28:31], v[202:205], v[170:173], v[28:31]
	v_mfma_f32_16x16x32_bf16 v[20:23], v[194:197], v[178:181], v[20:23]
	v_mfma_f32_16x16x32_bf16 v[12:15], v[202:205], v[178:181], v[12:15]
	v_mfma_f32_16x16x32_bf16 v[8:11], v[194:197], v[186:189], v[8:11]
	v_mfma_f32_16x16x32_bf16 v[4:7], v[202:205], v[186:189], v[4:7]
	v_mfma_f32_16x16x32_bf16 v[54:57], v[198:201], v[166:169], v[54:57]
	v_mfma_f32_16x16x32_bf16 v[46:49], v[206:209], v[166:169], v[46:49]
	v_mfma_f32_16x16x32_bf16 v[38:41], v[198:201], v[174:177], v[38:41]
	v_mfma_f32_16x16x32_bf16 v[28:31], v[206:209], v[174:177], v[28:31]
	v_mfma_f32_16x16x32_bf16 v[20:23], v[198:201], v[182:185], v[20:23]
	v_mfma_f32_16x16x32_bf16 v[12:15], v[206:209], v[182:185], v[12:15]
	v_mfma_f32_16x16x32_bf16 v[8:11], v[198:201], v[190:193], v[8:11]
	v_mfma_f32_16x16x32_bf16 v[4:7], v[206:209], v[190:193], v[4:7]
	s_add_i32 s82, s82, 2
	s_add_u32 s14, s14, 0x100
	s_addc_u32 s15, s15, 0
	s_add_u32 s80, s80, 0x100
	s_addc_u32 s81, s81, 0
	s_cmp_gt_u32 s82, 13
	s_barrier
	s_cbranch_scc0 .LBB0_245
	v_lshl_or_b32 v146, s77, 8, v148
	v_lshl_add_u32 v152, s8, 8, v1
	v_ashrrev_i32_e32 v147, 31, v146
	v_mov_b64_e32 v[144:145], s[34:35]
	s_movk_i32 s1, 0x2c00
	v_mad_i64_i32 v[150:151], s[14:15], v152, s1, v[144:145]
	v_lshlrev_b64 v[146:147], 1, v[146:147]
	v_lshl_add_u64 v[150:151], v[150:151], 0, v[146:147]
	v_cvt_pk_bf16_f32 v130, v130, v131
	v_cvt_pk_bf16_f32 v131, v132, v133
	v_cvt_pk_bf16_f32 v132, v126, v127
	v_cvt_pk_bf16_f32 v133, v128, v129
	global_store_dwordx4 v[150:151], v[130:133], off
	v_cvt_pk_bf16_f32 v118, v118, v119
	v_cvt_pk_bf16_f32 v119, v120, v121
	v_cvt_pk_bf16_f32 v120, v110, v111
	v_or_b32_e32 v110, 16, v152
	v_mad_i64_i32 v[110:111], s[14:15], v110, s1, v[144:145]
	v_cvt_pk_bf16_f32 v121, v112, v113
	global_store_dwordx4 v[150:151], v[118:121], off offset:256
	s_and_b64 vcc, exec, s[4:5]
	s_mov_b32 s77, s0
	v_lshl_add_u64 v[118:119], v[110:111], 0, v[146:147]
	v_cvt_pk_bf16_f32 v110, v122, v123
	v_cvt_pk_bf16_f32 v111, v124, v125
	v_cvt_pk_bf16_f32 v112, v114, v115
	v_cvt_pk_bf16_f32 v113, v116, v117
	global_store_dwordx4 v[118:119], v[110:113], off
	v_cvt_pk_bf16_f32 v102, v102, v103
	v_cvt_pk_bf16_f32 v103, v104, v105
	v_cvt_pk_bf16_f32 v104, v94, v95
	v_or_b32_e32 v94, 32, v152
	v_mad_i64_i32 v[94:95], s[14:15], v94, s1, v[144:145]
	v_cvt_pk_bf16_f32 v105, v96, v97
	global_store_dwordx4 v[118:119], v[102:105], off offset:256
	s_mov_b32 s8, s6
	s_mov_b64 s[16:17], s[12:13]
	v_lshl_add_u64 v[102:103], v[94:95], 0, v[146:147]
	v_cvt_pk_bf16_f32 v94, v106, v107
	v_cvt_pk_bf16_f32 v95, v108, v109
	v_cvt_pk_bf16_f32 v96, v98, v99
	v_cvt_pk_bf16_f32 v97, v100, v101
	global_store_dwordx4 v[102:103], v[94:97], off
	v_cvt_pk_bf16_f32 v86, v86, v87
	v_cvt_pk_bf16_f32 v87, v88, v89
	v_cvt_pk_bf16_f32 v88, v78, v79
	v_or_b32_e32 v78, 48, v152
	v_mad_i64_i32 v[78:79], s[14:15], v78, s1, v[144:145]
	v_cvt_pk_bf16_f32 v89, v80, v81
	global_store_dwordx4 v[102:103], v[86:89], off offset:256
	s_nop 1
	v_lshl_add_u64 v[86:87], v[78:79], 0, v[146:147]
	v_cvt_pk_bf16_f32 v78, v90, v91
	v_cvt_pk_bf16_f32 v79, v92, v93
	v_cvt_pk_bf16_f32 v80, v82, v83
	v_cvt_pk_bf16_f32 v81, v84, v85
	global_store_dwordx4 v[86:87], v[78:81], off
	v_cvt_pk_bf16_f32 v74, v74, v75
	v_cvt_pk_bf16_f32 v75, v76, v77
	v_cvt_pk_bf16_f32 v76, v70, v71
	v_add_u32_e32 v70, 0x80, v152
	v_mad_i64_i32 v[70:71], s[14:15], v70, s1, v[144:145]
	v_lshl_add_u64 v[70:71], v[70:71], 0, v[146:147]
	v_cvt_pk_bf16_f32 v77, v72, v73
	global_store_dwordx4 v[86:87], v[74:77], off offset:256
	v_cvt_pk_bf16_f32 v66, v66, v67
	v_cvt_pk_bf16_f32 v67, v68, v69
	v_cvt_pk_bf16_f32 v68, v62, v63
	v_cvt_pk_bf16_f32 v69, v64, v65
	global_store_dwordx4 v[70:71], v[66:69], off
	v_cvt_pk_bf16_f32 v54, v54, v55
	v_cvt_pk_bf16_f32 v55, v56, v57
	v_cvt_pk_bf16_f32 v56, v46, v47
	v_add_u32_e32 v46, 0x90, v152
	v_mad_i64_i32 v[46:47], s[14:15], v46, s1, v[144:145]
	v_cvt_pk_bf16_f32 v57, v48, v49
	global_store_dwordx4 v[70:71], v[54:57], off offset:256
	s_nop 1
	v_lshl_add_u64 v[54:55], v[46:47], 0, v[146:147]
	v_cvt_pk_bf16_f32 v46, v58, v59
	v_cvt_pk_bf16_f32 v47, v60, v61
	v_cvt_pk_bf16_f32 v48, v50, v51
	v_cvt_pk_bf16_f32 v49, v52, v53
	global_store_dwordx4 v[54:55], v[46:49], off
	v_cvt_pk_bf16_f32 v38, v38, v39
	v_cvt_pk_bf16_f32 v39, v40, v41
	v_cvt_pk_bf16_f32 v40, v28, v29
	v_add_u32_e32 v28, 0xa0, v152
	v_mad_i64_i32 v[28:29], s[14:15], v28, s1, v[144:145]
	v_cvt_pk_bf16_f32 v41, v30, v31
	global_store_dwordx4 v[54:55], v[38:41], off offset:256
	s_nop 1
	v_lshl_add_u64 v[38:39], v[28:29], 0, v[146:147]
	v_cvt_pk_bf16_f32 v28, v42, v43
	v_cvt_pk_bf16_f32 v29, v44, v45
	v_cvt_pk_bf16_f32 v30, v32, v33
	v_cvt_pk_bf16_f32 v31, v34, v35
	global_store_dwordx4 v[38:39], v[28:31], off
	v_cvt_pk_bf16_f32 v20, v20, v21
	v_cvt_pk_bf16_f32 v21, v22, v23
	v_cvt_pk_bf16_f32 v22, v12, v13
	v_add_u32_e32 v12, 0xb0, v152
	v_mad_i64_i32 v[12:13], s[14:15], v12, s1, v[144:145]
	v_cvt_pk_bf16_f32 v23, v14, v15
	global_store_dwordx4 v[38:39], v[20:23], off offset:256
	s_mov_b64 s[14:15], s[10:11]
	s_nop 0
	v_lshl_add_u64 v[20:21], v[12:13], 0, v[146:147]
	v_cvt_pk_bf16_f32 v12, v24, v25
	v_cvt_pk_bf16_f32 v13, v26, v27
	v_cvt_pk_bf16_f32 v14, v16, v17
	v_cvt_pk_bf16_f32 v15, v18, v19
	global_store_dwordx4 v[20:21], v[12:15], off
	v_cvt_pk_bf16_f32 v8, v8, v9
	v_cvt_pk_bf16_f32 v9, v10, v11
	v_cvt_pk_bf16_f32 v10, v4, v5
	v_cvt_pk_bf16_f32 v11, v6, v7
	global_store_dwordx4 v[20:21], v[8:11], off offset:256
	s_cbranch_vccz .LBB0_242
	s_waitcnt vmcnt(0)
	s_cmpk_gt_u32 s27, 0xff
	s_cbranch_scc1 .LBB0_249
	s_barrier

.LBB0_355:
	s_add_u32 s44, s38, 0x100
	s_addc_u32 s45, s39, 0
	s_add_i32 s91, 0, 0x10000
	v_add_u32_e32 v2, s91, v1
	ds_read_b128 v[134:137], v2
	ds_read_b128 v[138:141], v2 offset:1024
	ds_read_b128 v[142:145], v2 offset:2048
	ds_read_b128 v[146:149], v2 offset:3072
	s_cmp_eq_u32 s90, 12
	s_cselect_b32 s49, s13, s45
	s_cselect_b32 s48, s86, s44
	s_cselect_b32 s47, s7, s89
	s_cselect_b32 s46, s87, s88
	v_lshl_add_u64 v[160:161], s[38:39], 0, v[162:163]
	s_add_i32 m0, s19, 0xc000
	ds_read_b128 v[156:159], v155
	ds_read_b128 v[166:169], v155 offset:1024
	ds_read_b128 v[170:173], v155 offset:2048
	ds_read_b128 v[174:177], v155 offset:3072
	ds_read_b128 v[178:181], v155 offset:4096
	ds_read_b128 v[182:185], v155 offset:5120
	ds_read_b128 v[186:189], v155 offset:6144
	ds_read_b128 v[190:193], v155 offset:7168
	global_load_lds_dwordx4 v[160:161], off
	v_lshl_add_u64 v[160:161], s[38:39], 0, v[164:165]
	s_add_i32 m0, s19, 0xe000
	s_nop 0
	global_load_lds_dwordx4 v[160:161], off
	s_waitcnt lgkmcnt(8)
	s_barrier
	s_waitcnt lgkmcnt(0)
	s_waitcnt lgkmcnt(0)
	v_mfma_f32_16x16x32_bf16 v[130:133], v[134:137], v[156:159], v[130:133]
	v_mfma_f32_16x16x32_bf16 v[126:129], v[142:145], v[156:159], v[126:129]
	v_mfma_f32_16x16x32_bf16 v[118:121], v[134:137], v[170:173], v[118:121]
	v_mfma_f32_16x16x32_bf16 v[110:113], v[142:145], v[170:173], v[110:113]
	v_mfma_f32_16x16x32_bf16 v[102:105], v[134:137], v[178:181], v[102:105]
	v_mfma_f32_16x16x32_bf16 v[94:97], v[142:145], v[178:181], v[94:97]
	v_mfma_f32_16x16x32_bf16 v[86:89], v[134:137], v[186:189], v[86:89]
	v_mfma_f32_16x16x32_bf16 v[78:81], v[142:145], v[186:189], v[78:81]
	v_mfma_f32_16x16x32_bf16 v[130:133], v[138:141], v[166:169], v[130:133]
	v_mfma_f32_16x16x32_bf16 v[126:129], v[146:149], v[166:169], v[126:129]
	v_mfma_f32_16x16x32_bf16 v[118:121], v[138:141], v[174:177], v[118:121]
	v_mfma_f32_16x16x32_bf16 v[110:113], v[146:149], v[174:177], v[110:113]
	v_mfma_f32_16x16x32_bf16 v[102:105], v[138:141], v[182:185], v[102:105]
	v_mfma_f32_16x16x32_bf16 v[94:97], v[146:149], v[182:185], v[94:97]
	v_mfma_f32_16x16x32_bf16 v[86:89], v[138:141], v[190:193], v[86:89]
	v_mfma_f32_16x16x32_bf16 v[78:81], v[146:149], v[190:193], v[78:81]
	s_barrier
	s_add_i32 s92, 0, 0x14000
	s_add_i32 s38, s91, s55
	v_add_u32_e32 v2, s92, v1
	v_lshl_add_u64 v[160:161], s[46:47], 0, v[150:151]
	s_mov_b32 m0, s38
	ds_read_b128 v[194:197], v2
	ds_read_b128 v[198:201], v2 offset:1024
	ds_read_b128 v[202:205], v2 offset:2048
	ds_read_b128 v[206:209], v2 offset:3072
	global_load_lds_dwordx4 v[160:161], off
	v_lshl_add_u64 v[210:211], s[46:47], 0, v[152:153]
	s_add_i32 m0, s38, 0x2000
	s_nop 0
	global_load_lds_dwordx4 v[210:211], off
	s_barrier
	s_waitcnt lgkmcnt(0)
	s_waitcnt lgkmcnt(0)
	v_mfma_f32_16x16x32_bf16 v[122:125], v[194:197], v[156:159], v[122:125]
	v_mfma_f32_16x16x32_bf16 v[114:117], v[202:205], v[156:159], v[114:117]
	v_mfma_f32_16x16x32_bf16 v[106:109], v[194:197], v[170:173], v[106:109]
	v_mfma_f32_16x16x32_bf16 v[98:101], v[202:205], v[170:173], v[98:101]
	v_mfma_f32_16x16x32_bf16 v[90:93], v[194:197], v[178:181], v[90:93]
	v_mfma_f32_16x16x32_bf16 v[82:85], v[202:205], v[178:181], v[82:85]
	v_mfma_f32_16x16x32_bf16 v[74:77], v[194:197], v[186:189], v[74:77]
	v_mfma_f32_16x16x32_bf16 v[70:73], v[202:205], v[186:189], v[70:73]
	v_mfma_f32_16x16x32_bf16 v[122:125], v[198:201], v[166:169], v[122:125]
	v_mfma_f32_16x16x32_bf16 v[114:117], v[206:209], v[166:169], v[114:117]
	v_mfma_f32_16x16x32_bf16 v[106:109], v[198:201], v[174:177], v[106:109]
	v_mfma_f32_16x16x32_bf16 v[98:101], v[206:209], v[174:177], v[98:101]
	v_mfma_f32_16x16x32_bf16 v[90:93], v[198:201], v[182:185], v[90:93]
	v_mfma_f32_16x16x32_bf16 v[82:85], v[206:209], v[182:185], v[82:85]
	v_mfma_f32_16x16x32_bf16 v[74:77], v[198:201], v[190:193], v[74:77]
	v_mfma_f32_16x16x32_bf16 v[70:73], v[206:209], v[190:193], v[70:73]
	s_mov_b32 m0, s19
	v_lshl_add_u64 v[212:213], s[48:49], 0, v[150:151]
	s_barrier
	ds_read_b128 v[156:159], v155 offset:16384
	ds_read_b128 v[166:169], v155 offset:17408
	ds_read_b128 v[170:173], v155 offset:18432
	ds_read_b128 v[174:177], v155 offset:19456
	ds_read_b128 v[178:181], v155 offset:20480
	ds_read_b128 v[182:185], v155 offset:21504
	ds_read_b128 v[186:189], v155 offset:22528
	ds_read_b128 v[190:193], v155 offset:23552
	global_load_lds_dwordx4 v[212:213], off
	v_lshl_add_u64 v[214:215], s[48:49], 0, v[152:153]
	s_mov_b32 m0, s76
	s_nop 0
	global_load_lds_dwordx4 v[214:215], off
	s_barrier
	s_waitcnt lgkmcnt(0)
	s_waitcnt lgkmcnt(0)
	v_mfma_f32_16x16x32_bf16 v[66:69], v[134:137], v[156:159], v[66:69]
	v_mfma_f32_16x16x32_bf16 v[62:65], v[142:145], v[156:159], v[62:65]
	v_mfma_f32_16x16x32_bf16 v[54:57], v[134:137], v[170:173], v[54:57]
	v_mfma_f32_16x16x32_bf16 v[46:49], v[142:145], v[170:173], v[46:49]
	v_mfma_f32_16x16x32_bf16 v[38:41], v[134:137], v[178:181], v[38:41]
	v_mfma_f32_16x16x32_bf16 v[28:31], v[142:145], v[178:181], v[28:31]
	v_mfma_f32_16x16x32_bf16 v[20:23], v[134:137], v[186:189], v[20:23]
	v_mfma_f32_16x16x32_bf16 v[12:15], v[142:145], v[186:189], v[12:15]
	v_mfma_f32_16x16x32_bf16 v[66:69], v[138:141], v[166:169], v[66:69]
	v_mfma_f32_16x16x32_bf16 v[62:65], v[146:149], v[166:169], v[62:65]
	v_mfma_f32_16x16x32_bf16 v[54:57], v[138:141], v[174:177], v[54:57]
	v_mfma_f32_16x16x32_bf16 v[46:49], v[146:149], v[174:177], v[46:49]
	v_mfma_f32_16x16x32_bf16 v[38:41], v[138:141], v[182:185], v[38:41]
	v_mfma_f32_16x16x32_bf16 v[28:31], v[146:149], v[182:185], v[28:31]
	v_mfma_f32_16x16x32_bf16 v[20:23], v[138:141], v[190:193], v[20:23]
	v_mfma_f32_16x16x32_bf16 v[12:15], v[146:149], v[190:193], v[12:15]
	s_barrier
	s_add_u32 s38, s46, 0x40000
	s_addc_u32 s39, s47, 0
	s_add_i32 s91, s92, s55
	v_lshl_add_u64 v[134:135], s[38:39], 0, v[150:151]
	s_mov_b32 m0, s91
	s_nop 0
	global_load_lds_dwordx4 v[134:135], off
	v_lshl_add_u64 v[134:135], s[38:39], 0, v[152:153]
	s_add_i32 m0, s91, 0x2000
	s_nop 0
	global_load_lds_dwordx4 v[134:135], off
	s_waitcnt vmcnt(6)
	s_barrier
	v_mfma_f32_16x16x32_bf16 v[58:61], v[194:197], v[156:159], v[58:61]
	v_mfma_f32_16x16x32_bf16 v[50:53], v[202:205], v[156:159], v[50:53]
	v_mfma_f32_16x16x32_bf16 v[42:45], v[194:197], v[170:173], v[42:45]
	v_mfma_f32_16x16x32_bf16 v[32:35], v[202:205], v[170:173], v[32:35]
	v_mfma_f32_16x16x32_bf16 v[24:27], v[194:197], v[178:181], v[24:27]
	v_mfma_f32_16x16x32_bf16 v[16:19], v[202:205], v[178:181], v[16:19]
	v_mfma_f32_16x16x32_bf16 v[8:11], v[194:197], v[186:189], v[8:11]
	v_mfma_f32_16x16x32_bf16 v[4:7], v[202:205], v[186:189], v[4:7]
	v_mfma_f32_16x16x32_bf16 v[58:61], v[198:201], v[166:169], v[58:61]
	v_mfma_f32_16x16x32_bf16 v[50:53], v[206:209], v[166:169], v[50:53]
	v_mfma_f32_16x16x32_bf16 v[42:45], v[198:201], v[174:177], v[42:45]
	v_mfma_f32_16x16x32_bf16 v[32:35], v[206:209], v[174:177], v[32:35]
	v_mfma_f32_16x16x32_bf16 v[24:27], v[198:201], v[182:185], v[24:27]
	v_mfma_f32_16x16x32_bf16 v[16:19], v[206:209], v[182:185], v[16:19]
	v_mfma_f32_16x16x32_bf16 v[8:11], v[198:201], v[190:193], v[8:11]
	v_mfma_f32_16x16x32_bf16 v[4:7], v[206:209], v[190:193], v[4:7]
	s_add_i32 s91, 0, 0x18000
	v_add_u32_e32 v2, s91, v1
	s_barrier
	ds_read_b128 v[134:137], v2
	ds_read_b128 v[138:141], v2 offset:1024
	ds_read_b128 v[142:145], v2 offset:2048
	ds_read_b128 v[146:149], v2 offset:3072
	s_add_u32 s38, s48, 0x40000
	s_addc_u32 s39, s49, 0
	s_mov_b32 m0, s77
	v_lshl_add_u64 v[194:195], s[38:39], 0, v[150:151]
	ds_read_b128 v[156:159], v155 offset:32768
	ds_read_b128 v[166:169], v155 offset:33792
	ds_read_b128 v[170:173], v155 offset:34816
	ds_read_b128 v[174:177], v155 offset:35840
	ds_read_b128 v[178:181], v155 offset:36864
	ds_read_b128 v[182:185], v155 offset:37888
	ds_read_b128 v[186:189], v155 offset:38912
	ds_read_b128 v[190:193], v155 offset:39936
	global_load_lds_dwordx4 v[194:195], off
	v_lshl_add_u64 v[194:195], s[38:39], 0, v[152:153]
	s_mov_b32 m0, s78
	s_nop 0
	global_load_lds_dwordx4 v[194:195], off
	s_waitcnt lgkmcnt(8)
	s_barrier
	s_waitcnt lgkmcnt(0)
	s_waitcnt lgkmcnt(0)
	v_mfma_f32_16x16x32_bf16 v[130:133], v[134:137], v[156:159], v[130:133]
	v_mfma_f32_16x16x32_bf16 v[126:129], v[142:145], v[156:159], v[126:129]
	v_mfma_f32_16x16x32_bf16 v[118:121], v[134:137], v[170:173], v[118:121]
	v_mfma_f32_16x16x32_bf16 v[110:113], v[142:145], v[170:173], v[110:113]
	v_mfma_f32_16x16x32_bf16 v[102:105], v[134:137], v[178:181], v[102:105]
	v_mfma_f32_16x16x32_bf16 v[94:97], v[142:145], v[178:181], v[94:97]
	v_mfma_f32_16x16x32_bf16 v[86:89], v[134:137], v[186:189], v[86:89]
	v_mfma_f32_16x16x32_bf16 v[78:81], v[142:145], v[186:189], v[78:81]
	v_mfma_f32_16x16x32_bf16 v[130:133], v[138:141], v[166:169], v[130:133]
	v_mfma_f32_16x16x32_bf16 v[126:129], v[146:149], v[166:169], v[126:129]
	v_mfma_f32_16x16x32_bf16 v[118:121], v[138:141], v[174:177], v[118:121]
	v_mfma_f32_16x16x32_bf16 v[110:113], v[146:149], v[174:177], v[110:113]
	v_mfma_f32_16x16x32_bf16 v[102:105], v[138:141], v[182:185], v[102:105]
	v_mfma_f32_16x16x32_bf16 v[94:97], v[146:149], v[182:185], v[94:97]
	v_mfma_f32_16x16x32_bf16 v[86:89], v[138:141], v[190:193], v[86:89]
	v_mfma_f32_16x16x32_bf16 v[78:81], v[146:149], v[190:193], v[78:81]
	s_barrier
	s_add_i32 s48, 0, 0x1c000
	s_add_i32 s38, s91, s55
	v_add_u32_e32 v2, s48, v1
	v_lshl_add_u64 v[160:161], v[160:161], 0, s[24:25]
	s_mov_b32 m0, s38
	ds_read_b128 v[194:197], v2
	ds_read_b128 v[198:201], v2 offset:1024
	ds_read_b128 v[202:205], v2 offset:2048
	ds_read_b128 v[206:209], v2 offset:3072
	global_load_lds_dwordx4 v[160:161], off
	v_lshl_add_u64 v[160:161], v[210:211], 0, s[24:25]
	s_add_i32 m0, s38, 0x2000
	s_nop 0
	global_load_lds_dwordx4 v[160:161], off
	s_barrier
	s_waitcnt lgkmcnt(0)
	s_waitcnt lgkmcnt(0)
	v_mfma_f32_16x16x32_bf16 v[122:125], v[194:197], v[156:159], v[122:125]
	v_mfma_f32_16x16x32_bf16 v[114:117], v[202:205], v[156:159], v[114:117]
	v_mfma_f32_16x16x32_bf16 v[106:109], v[194:197], v[170:173], v[106:109]
	v_mfma_f32_16x16x32_bf16 v[98:101], v[202:205], v[170:173], v[98:101]
	v_mfma_f32_16x16x32_bf16 v[90:93], v[194:197], v[178:181], v[90:93]
	v_mfma_f32_16x16x32_bf16 v[82:85], v[202:205], v[178:181], v[82:85]
	v_mfma_f32_16x16x32_bf16 v[74:77], v[194:197], v[186:189], v[74:77]
	v_mfma_f32_16x16x32_bf16 v[70:73], v[202:205], v[186:189], v[70:73]
	v_mfma_f32_16x16x32_bf16 v[122:125], v[198:201], v[166:169], v[122:125]
	v_mfma_f32_16x16x32_bf16 v[114:117], v[206:209], v[166:169], v[114:117]
	v_mfma_f32_16x16x32_bf16 v[106:109], v[198:201], v[174:177], v[106:109]
	v_mfma_f32_16x16x32_bf16 v[98:101], v[206:209], v[174:177], v[98:101]
	v_mfma_f32_16x16x32_bf16 v[90:93], v[198:201], v[182:185], v[90:93]
	v_mfma_f32_16x16x32_bf16 v[82:85], v[206:209], v[182:185], v[82:85]
	v_mfma_f32_16x16x32_bf16 v[74:77], v[198:201], v[190:193], v[74:77]
	v_mfma_f32_16x16x32_bf16 v[70:73], v[206:209], v[190:193], v[70:73]
	s_mov_b32 m0, s81
	v_lshl_add_u64 v[160:161], v[212:213], 0, s[24:25]
	s_barrier
	ds_read_b128 v[156:159], v155 offset:49152
	ds_read_b128 v[166:169], v155 offset:50176
	ds_read_b128 v[170:173], v155 offset:51200
	ds_read_b128 v[174:177], v155 offset:52224
	ds_read_b128 v[178:181], v155 offset:53248
	ds_read_b128 v[182:185], v155 offset:54272
	ds_read_b128 v[186:189], v155 offset:55296
	ds_read_b128 v[190:193], v155 offset:56320
	global_load_lds_dwordx4 v[160:161], off
	v_lshl_add_u64 v[160:161], v[214:215], 0, s[24:25]
	s_mov_b32 m0, s82
	s_nop 0
	global_load_lds_dwordx4 v[160:161], off
	s_barrier
	s_waitcnt lgkmcnt(0)
	s_waitcnt lgkmcnt(0)
	v_mfma_f32_16x16x32_bf16 v[66:69], v[134:137], v[156:159], v[66:69]
	v_mfma_f32_16x16x32_bf16 v[62:65], v[142:145], v[156:159], v[62:65]
	v_mfma_f32_16x16x32_bf16 v[54:57], v[134:137], v[170:173], v[54:57]
	v_mfma_f32_16x16x32_bf16 v[46:49], v[142:145], v[170:173], v[46:49]
	v_mfma_f32_16x16x32_bf16 v[38:41], v[134:137], v[178:181], v[38:41]
	v_mfma_f32_16x16x32_bf16 v[28:31], v[142:145], v[178:181], v[28:31]
	v_mfma_f32_16x16x32_bf16 v[20:23], v[134:137], v[186:189], v[20:23]
	v_mfma_f32_16x16x32_bf16 v[12:15], v[142:145], v[186:189], v[12:15]
	v_mfma_f32_16x16x32_bf16 v[66:69], v[138:141], v[166:169], v[66:69]
	v_mfma_f32_16x16x32_bf16 v[62:65], v[146:149], v[166:169], v[62:65]
	v_mfma_f32_16x16x32_bf16 v[54:57], v[138:141], v[174:177], v[54:57]
	v_mfma_f32_16x16x32_bf16 v[46:49], v[146:149], v[174:177], v[46:49]
	v_mfma_f32_16x16x32_bf16 v[38:41], v[138:141], v[182:185], v[38:41]
	v_mfma_f32_16x16x32_bf16 v[28:31], v[146:149], v[182:185], v[28:31]
	v_mfma_f32_16x16x32_bf16 v[20:23], v[138:141], v[190:193], v[20:23]
	v_mfma_f32_16x16x32_bf16 v[12:15], v[146:149], v[190:193], v[12:15]
	s_barrier
	s_add_u32 s38, s46, 0x40080
	s_addc_u32 s39, s47, 0
	s_add_i32 s46, s48, s55
	v_lshl_add_u64 v[134:135], s[38:39], 0, v[150:151]
	s_mov_b32 m0, s46
	s_nop 0
	global_load_lds_dwordx4 v[134:135], off
	v_lshl_add_u64 v[134:135], s[38:39], 0, v[152:153]
	s_add_i32 m0, s46, 0x2000
	s_nop 0
	global_load_lds_dwordx4 v[134:135], off
	s_waitcnt vmcnt(6)
	s_barrier
	v_mfma_f32_16x16x32_bf16 v[58:61], v[194:197], v[156:159], v[58:61]
	v_mfma_f32_16x16x32_bf16 v[50:53], v[202:205], v[156:159], v[50:53]
	v_mfma_f32_16x16x32_bf16 v[42:45], v[194:197], v[170:173], v[42:45]
	v_mfma_f32_16x16x32_bf16 v[32:35], v[202:205], v[170:173], v[32:35]
	v_mfma_f32_16x16x32_bf16 v[24:27], v[194:197], v[178:181], v[24:27]
	v_mfma_f32_16x16x32_bf16 v[16:19], v[202:205], v[178:181], v[16:19]
	v_mfma_f32_16x16x32_bf16 v[8:11], v[194:197], v[186:189], v[8:11]
	v_mfma_f32_16x16x32_bf16 v[4:7], v[202:205], v[186:189], v[4:7]
	v_mfma_f32_16x16x32_bf16 v[58:61], v[198:201], v[166:169], v[58:61]
	v_mfma_f32_16x16x32_bf16 v[50:53], v[206:209], v[166:169], v[50:53]
	v_mfma_f32_16x16x32_bf16 v[42:45], v[198:201], v[174:177], v[42:45]
	v_mfma_f32_16x16x32_bf16 v[32:35], v[206:209], v[174:177], v[32:35]
	v_mfma_f32_16x16x32_bf16 v[24:27], v[198:201], v[182:185], v[24:27]
	v_mfma_f32_16x16x32_bf16 v[16:19], v[206:209], v[182:185], v[16:19]
	v_mfma_f32_16x16x32_bf16 v[8:11], v[198:201], v[190:193], v[8:11]
	v_mfma_f32_16x16x32_bf16 v[4:7], v[206:209], v[190:193], v[4:7]
	s_add_i32 s90, s90, 2
	s_add_u32 s88, s88, 0x100
	s_addc_u32 s89, s89, 0
	s_cmp_gt_u32 s90, 13
	s_mov_b64 s[38:39], s[44:45]
	s_barrier
	s_cbranch_scc0 .LBB0_355
	v_readlane_b32 s38, v254, 8
	v_readlane_b32 s39, v254, 9
	s_lshl_b32 s46, s18, 8
	s_mov_b64 s[48:49], -1
	s_and_b64 vcc, exec, s[38:39]
	s_cbranch_vccz .LBB0_358
	s_ashr_i32 s47, s46, 31
	s_lshl_b64 s[44:45], s[46:47], 12
	s_add_u32 s38, s0, s44
	s_addc_u32 s39, s1, s45
	s_mov_b64 s[48:49], 0

.LBB0_518:
	s_add_u32 s16, s14, 0x100
	s_addc_u32 s17, s15, 0
	s_add_i32 s79, 0, 0x10000
	v_add_u32_e32 v158, s79, v37
	ds_read_b128 v[144:147], v158
	ds_read_b128 v[150:153], v158 offset:1024
	ds_read_b128 v[154:157], v158 offset:2048
	ds_read_b128 v[158:161], v158 offset:3072
	s_cmp_eq_u32 s78, 2
	s_cselect_b32 s43, s1, s17
	s_cselect_b32 s42, s0, s16
	s_cselect_b32 s19, s7, s77
	s_cselect_b32 s18, s6, s76
	v_lshl_add_u64 v[194:195], s[14:15], 0, v[140:141]
	s_add_i32 m0, s48, 0xc000
	ds_read_b128 v[162:165], v149
	ds_read_b128 v[166:169], v149 offset:1024
	ds_read_b128 v[170:173], v149 offset:2048
	ds_read_b128 v[174:177], v149 offset:3072
	ds_read_b128 v[178:181], v149 offset:4096
	ds_read_b128 v[182:185], v149 offset:5120
	ds_read_b128 v[186:189], v149 offset:6144
	ds_read_b128 v[190:193], v149 offset:7168
	global_load_lds_dwordx4 v[194:195], off
	v_lshl_add_u64 v[194:195], s[14:15], 0, v[142:143]
	s_add_i32 m0, s48, 0xe000
	s_nop 0
	global_load_lds_dwordx4 v[194:195], off
	s_waitcnt lgkmcnt(8)
	s_barrier
	s_waitcnt lgkmcnt(0)
	s_waitcnt lgkmcnt(0)
	v_mfma_f32_16x16x32_bf16 v[130:133], v[144:147], v[162:165], v[130:133]
	v_mfma_f32_16x16x32_bf16 v[126:129], v[154:157], v[162:165], v[126:129]
	v_mfma_f32_16x16x32_bf16 v[122:125], v[144:147], v[170:173], v[122:125]
	v_mfma_f32_16x16x32_bf16 v[114:117], v[154:157], v[170:173], v[114:117]
	v_mfma_f32_16x16x32_bf16 v[106:109], v[144:147], v[178:181], v[106:109]
	v_mfma_f32_16x16x32_bf16 v[98:101], v[154:157], v[178:181], v[98:101]
	v_mfma_f32_16x16x32_bf16 v[90:93], v[144:147], v[186:189], v[90:93]
	v_mfma_f32_16x16x32_bf16 v[82:85], v[154:157], v[186:189], v[82:85]
	v_mfma_f32_16x16x32_bf16 v[130:133], v[150:153], v[166:169], v[130:133]
	v_mfma_f32_16x16x32_bf16 v[126:129], v[158:161], v[166:169], v[126:129]
	v_mfma_f32_16x16x32_bf16 v[122:125], v[150:153], v[174:177], v[122:125]
	v_mfma_f32_16x16x32_bf16 v[114:117], v[158:161], v[174:177], v[114:117]
	v_mfma_f32_16x16x32_bf16 v[106:109], v[150:153], v[182:185], v[106:109]
	v_mfma_f32_16x16x32_bf16 v[98:101], v[158:161], v[182:185], v[98:101]
	v_mfma_f32_16x16x32_bf16 v[90:93], v[150:153], v[190:193], v[90:93]
	v_mfma_f32_16x16x32_bf16 v[82:85], v[158:161], v[190:193], v[82:85]
	s_barrier
	s_add_i32 s80, 0, 0x14000
	s_add_i32 s14, s79, s44
	v_add_u32_e32 v206, s80, v37
	v_lshl_add_u64 v[210:211], s[18:19], 0, v[2:3]
	s_mov_b32 m0, s14
	ds_read_b128 v[194:197], v206
	ds_read_b128 v[198:201], v206 offset:1024
	ds_read_b128 v[202:205], v206 offset:2048
	ds_read_b128 v[206:209], v206 offset:3072
	global_load_lds_dwordx4 v[210:211], off
	v_lshl_add_u64 v[212:213], s[18:19], 0, v[134:135]
	s_add_i32 m0, s14, 0x2000
	s_nop 0
	global_load_lds_dwordx4 v[212:213], off
	s_barrier
	s_waitcnt lgkmcnt(0)
	s_waitcnt lgkmcnt(0)
	v_mfma_f32_16x16x32_bf16 v[118:121], v[194:197], v[162:165], v[118:121]
	v_mfma_f32_16x16x32_bf16 v[110:113], v[202:205], v[162:165], v[110:113]
	v_mfma_f32_16x16x32_bf16 v[102:105], v[194:197], v[170:173], v[102:105]
	v_mfma_f32_16x16x32_bf16 v[94:97], v[202:205], v[170:173], v[94:97]
	v_mfma_f32_16x16x32_bf16 v[86:89], v[194:197], v[178:181], v[86:89]
	v_mfma_f32_16x16x32_bf16 v[78:81], v[202:205], v[178:181], v[78:81]
	v_mfma_f32_16x16x32_bf16 v[74:77], v[194:197], v[186:189], v[74:77]
	v_mfma_f32_16x16x32_bf16 v[70:73], v[202:205], v[186:189], v[70:73]
	v_mfma_f32_16x16x32_bf16 v[118:121], v[198:201], v[166:169], v[118:121]
	v_mfma_f32_16x16x32_bf16 v[110:113], v[206:209], v[166:169], v[110:113]
	v_mfma_f32_16x16x32_bf16 v[102:105], v[198:201], v[174:177], v[102:105]
	v_mfma_f32_16x16x32_bf16 v[94:97], v[206:209], v[174:177], v[94:97]
	v_mfma_f32_16x16x32_bf16 v[86:89], v[198:201], v[182:185], v[86:89]
	v_mfma_f32_16x16x32_bf16 v[78:81], v[206:209], v[182:185], v[78:81]
	v_mfma_f32_16x16x32_bf16 v[74:77], v[198:201], v[190:193], v[74:77]
	v_mfma_f32_16x16x32_bf16 v[70:73], v[206:209], v[190:193], v[70:73]
	s_mov_b32 m0, s48
	v_lshl_add_u64 v[214:215], s[42:43], 0, v[138:139]
	s_barrier
	ds_read_b128 v[162:165], v149 offset:16384
	ds_read_b128 v[166:169], v149 offset:17408
	ds_read_b128 v[170:173], v149 offset:18432
	ds_read_b128 v[174:177], v149 offset:19456
	ds_read_b128 v[178:181], v149 offset:20480
	ds_read_b128 v[182:185], v149 offset:21504
	ds_read_b128 v[186:189], v149 offset:22528
	ds_read_b128 v[190:193], v149 offset:23552
	global_load_lds_dwordx4 v[214:215], off
	v_lshl_add_u64 v[216:217], s[42:43], 0, v[136:137]
	s_mov_b32 m0, s49
	s_nop 0
	global_load_lds_dwordx4 v[216:217], off
	s_barrier
	s_waitcnt lgkmcnt(0)
	s_waitcnt lgkmcnt(0)
	v_mfma_f32_16x16x32_bf16 v[66:69], v[144:147], v[162:165], v[66:69]
	v_mfma_f32_16x16x32_bf16 v[62:65], v[154:157], v[162:165], v[62:65]
	v_mfma_f32_16x16x32_bf16 v[58:61], v[144:147], v[170:173], v[58:61]
	v_mfma_f32_16x16x32_bf16 v[50:53], v[154:157], v[170:173], v[50:53]
	v_mfma_f32_16x16x32_bf16 v[42:45], v[144:147], v[178:181], v[42:45]
	v_mfma_f32_16x16x32_bf16 v[32:35], v[154:157], v[178:181], v[32:35]
	v_mfma_f32_16x16x32_bf16 v[24:27], v[144:147], v[186:189], v[24:27]
	v_mfma_f32_16x16x32_bf16 v[16:19], v[154:157], v[186:189], v[16:19]
	v_mfma_f32_16x16x32_bf16 v[66:69], v[150:153], v[166:169], v[66:69]
	v_mfma_f32_16x16x32_bf16 v[62:65], v[158:161], v[166:169], v[62:65]
	v_mfma_f32_16x16x32_bf16 v[58:61], v[150:153], v[174:177], v[58:61]
	v_mfma_f32_16x16x32_bf16 v[50:53], v[158:161], v[174:177], v[50:53]
	v_mfma_f32_16x16x32_bf16 v[42:45], v[150:153], v[182:185], v[42:45]
	v_mfma_f32_16x16x32_bf16 v[32:35], v[158:161], v[182:185], v[32:35]
	v_mfma_f32_16x16x32_bf16 v[24:27], v[150:153], v[190:193], v[24:27]
	v_mfma_f32_16x16x32_bf16 v[16:19], v[158:161], v[190:193], v[16:19]
	s_barrier
	s_add_u32 s14, s18, 0x18000
	s_addc_u32 s15, s19, 0
	s_add_i32 s79, s80, s44
	v_lshl_add_u64 v[144:145], s[14:15], 0, v[2:3]
	s_mov_b32 m0, s79
	s_nop 0
	global_load_lds_dwordx4 v[144:145], off
	v_lshl_add_u64 v[144:145], s[14:15], 0, v[134:135]
	s_add_i32 m0, s79, 0x2000
	s_nop 0
	global_load_lds_dwordx4 v[144:145], off
	s_waitcnt vmcnt(6)
	s_barrier
	v_mfma_f32_16x16x32_bf16 v[54:57], v[194:197], v[162:165], v[54:57]
	v_mfma_f32_16x16x32_bf16 v[46:49], v[202:205], v[162:165], v[46:49]
	v_mfma_f32_16x16x32_bf16 v[38:41], v[194:197], v[170:173], v[38:41]
	v_mfma_f32_16x16x32_bf16 v[28:31], v[202:205], v[170:173], v[28:31]
	v_mfma_f32_16x16x32_bf16 v[20:23], v[194:197], v[178:181], v[20:23]
	v_mfma_f32_16x16x32_bf16 v[12:15], v[202:205], v[178:181], v[12:15]
	v_mfma_f32_16x16x32_bf16 v[8:11], v[194:197], v[186:189], v[8:11]
	v_mfma_f32_16x16x32_bf16 v[4:7], v[202:205], v[186:189], v[4:7]
	v_mfma_f32_16x16x32_bf16 v[54:57], v[198:201], v[166:169], v[54:57]
	v_mfma_f32_16x16x32_bf16 v[46:49], v[206:209], v[166:169], v[46:49]
	v_mfma_f32_16x16x32_bf16 v[38:41], v[198:201], v[174:177], v[38:41]
	v_mfma_f32_16x16x32_bf16 v[28:31], v[206:209], v[174:177], v[28:31]
	v_mfma_f32_16x16x32_bf16 v[20:23], v[198:201], v[182:185], v[20:23]
	v_mfma_f32_16x16x32_bf16 v[12:15], v[206:209], v[182:185], v[12:15]
	v_mfma_f32_16x16x32_bf16 v[8:11], v[198:201], v[190:193], v[8:11]
	v_mfma_f32_16x16x32_bf16 v[4:7], v[206:209], v[190:193], v[4:7]
	s_add_i32 s79, 0, 0x18000
	v_add_u32_e32 v158, s79, v37
	s_barrier
	ds_read_b128 v[144:147], v158
	ds_read_b128 v[150:153], v158 offset:1024
	ds_read_b128 v[154:157], v158 offset:2048
	ds_read_b128 v[158:161], v158 offset:3072
	s_add_u32 s14, s42, 0x18000
	s_addc_u32 s15, s43, 0
	s_mov_b32 m0, s50
	v_lshl_add_u64 v[194:195], s[14:15], 0, v[138:139]
	ds_read_b128 v[162:165], v149 offset:32768
	ds_read_b128 v[166:169], v149 offset:33792
	ds_read_b128 v[170:173], v149 offset:34816
	ds_read_b128 v[174:177], v149 offset:35840
	ds_read_b128 v[178:181], v149 offset:36864
	ds_read_b128 v[182:185], v149 offset:37888
	ds_read_b128 v[186:189], v149 offset:38912
	ds_read_b128 v[190:193], v149 offset:39936
	global_load_lds_dwordx4 v[194:195], off
	v_lshl_add_u64 v[194:195], s[14:15], 0, v[136:137]
	s_mov_b32 m0, s51
	s_nop 0
	global_load_lds_dwordx4 v[194:195], off
	s_waitcnt lgkmcnt(8)
	s_barrier
	s_waitcnt lgkmcnt(0)
	s_waitcnt lgkmcnt(0)
	v_mfma_f32_16x16x32_bf16 v[130:133], v[144:147], v[162:165], v[130:133]
	v_mfma_f32_16x16x32_bf16 v[126:129], v[154:157], v[162:165], v[126:129]
	v_mfma_f32_16x16x32_bf16 v[122:125], v[144:147], v[170:173], v[122:125]
	v_mfma_f32_16x16x32_bf16 v[114:117], v[154:157], v[170:173], v[114:117]
	v_mfma_f32_16x16x32_bf16 v[106:109], v[144:147], v[178:181], v[106:109]
	v_mfma_f32_16x16x32_bf16 v[98:101], v[154:157], v[178:181], v[98:101]
	v_mfma_f32_16x16x32_bf16 v[90:93], v[144:147], v[186:189], v[90:93]
	v_mfma_f32_16x16x32_bf16 v[82:85], v[154:157], v[186:189], v[82:85]
	v_mfma_f32_16x16x32_bf16 v[130:133], v[150:153], v[166:169], v[130:133]
	v_mfma_f32_16x16x32_bf16 v[126:129], v[158:161], v[166:169], v[126:129]
	v_mfma_f32_16x16x32_bf16 v[122:125], v[150:153], v[174:177], v[122:125]
	v_mfma_f32_16x16x32_bf16 v[114:117], v[158:161], v[174:177], v[114:117]
	v_mfma_f32_16x16x32_bf16 v[106:109], v[150:153], v[182:185], v[106:109]
	v_mfma_f32_16x16x32_bf16 v[98:101], v[158:161], v[182:185], v[98:101]
	v_mfma_f32_16x16x32_bf16 v[90:93], v[150:153], v[190:193], v[90:93]
	v_mfma_f32_16x16x32_bf16 v[82:85], v[158:161], v[190:193], v[82:85]
	s_barrier
	s_add_i32 s42, 0, 0x1c000
	s_add_i32 s14, s79, s44
	v_add_u32_e32 v206, s42, v37
	v_lshl_add_u64 v[210:211], v[210:211], 0, s[24:25]
	s_mov_b32 m0, s14
	ds_read_b128 v[194:197], v206
	ds_read_b128 v[198:201], v206 offset:1024
	ds_read_b128 v[202:205], v206 offset:2048
	ds_read_b128 v[206:209], v206 offset:3072
	global_load_lds_dwordx4 v[210:211], off
	v_lshl_add_u64 v[210:211], v[212:213], 0, s[24:25]
	s_add_i32 m0, s14, 0x2000
	s_nop 0
	global_load_lds_dwordx4 v[210:211], off
	s_barrier
	s_waitcnt lgkmcnt(0)
	s_waitcnt lgkmcnt(0)
	v_mfma_f32_16x16x32_bf16 v[118:121], v[194:197], v[162:165], v[118:121]
	v_mfma_f32_16x16x32_bf16 v[110:113], v[202:205], v[162:165], v[110:113]
	v_mfma_f32_16x16x32_bf16 v[102:105], v[194:197], v[170:173], v[102:105]
	v_mfma_f32_16x16x32_bf16 v[94:97], v[202:205], v[170:173], v[94:97]
	v_mfma_f32_16x16x32_bf16 v[86:89], v[194:197], v[178:181], v[86:89]
	v_mfma_f32_16x16x32_bf16 v[78:81], v[202:205], v[178:181], v[78:81]
	v_mfma_f32_16x16x32_bf16 v[74:77], v[194:197], v[186:189], v[74:77]
	v_mfma_f32_16x16x32_bf16 v[70:73], v[202:205], v[186:189], v[70:73]
	v_mfma_f32_16x16x32_bf16 v[118:121], v[198:201], v[166:169], v[118:121]
	v_mfma_f32_16x16x32_bf16 v[110:113], v[206:209], v[166:169], v[110:113]
	v_mfma_f32_16x16x32_bf16 v[102:105], v[198:201], v[174:177], v[102:105]
	v_mfma_f32_16x16x32_bf16 v[94:97], v[206:209], v[174:177], v[94:97]
	v_mfma_f32_16x16x32_bf16 v[86:89], v[198:201], v[182:185], v[86:89]
	v_mfma_f32_16x16x32_bf16 v[78:81], v[206:209], v[182:185], v[78:81]
	v_mfma_f32_16x16x32_bf16 v[74:77], v[198:201], v[190:193], v[74:77]
	v_mfma_f32_16x16x32_bf16 v[70:73], v[206:209], v[190:193], v[70:73]
	s_mov_b32 m0, s52
	v_lshl_add_u64 v[210:211], v[214:215], 0, s[24:25]
	s_barrier
	ds_read_b128 v[162:165], v149 offset:49152
	ds_read_b128 v[166:169], v149 offset:50176
	ds_read_b128 v[170:173], v149 offset:51200
	ds_read_b128 v[174:177], v149 offset:52224
	ds_read_b128 v[178:181], v149 offset:53248
	ds_read_b128 v[182:185], v149 offset:54272
	ds_read_b128 v[186:189], v149 offset:55296
	ds_read_b128 v[190:193], v149 offset:56320
	global_load_lds_dwordx4 v[210:211], off
	v_lshl_add_u64 v[210:211], v[216:217], 0, s[24:25]
	s_mov_b32 m0, s53
	s_nop 0
	global_load_lds_dwordx4 v[210:211], off
	s_barrier
	s_waitcnt lgkmcnt(0)
	s_waitcnt lgkmcnt(0)
	v_mfma_f32_16x16x32_bf16 v[66:69], v[144:147], v[162:165], v[66:69]
	v_mfma_f32_16x16x32_bf16 v[62:65], v[154:157], v[162:165], v[62:65]
	v_mfma_f32_16x16x32_bf16 v[58:61], v[144:147], v[170:173], v[58:61]
	v_mfma_f32_16x16x32_bf16 v[50:53], v[154:157], v[170:173], v[50:53]
	v_mfma_f32_16x16x32_bf16 v[42:45], v[144:147], v[178:181], v[42:45]
	v_mfma_f32_16x16x32_bf16 v[32:35], v[154:157], v[178:181], v[32:35]
	v_mfma_f32_16x16x32_bf16 v[24:27], v[144:147], v[186:189], v[24:27]
	v_mfma_f32_16x16x32_bf16 v[16:19], v[154:157], v[186:189], v[16:19]
	v_mfma_f32_16x16x32_bf16 v[66:69], v[150:153], v[166:169], v[66:69]
	v_mfma_f32_16x16x32_bf16 v[62:65], v[158:161], v[166:169], v[62:65]
	v_mfma_f32_16x16x32_bf16 v[58:61], v[150:153], v[174:177], v[58:61]
	v_mfma_f32_16x16x32_bf16 v[50:53], v[158:161], v[174:177], v[50:53]
	v_mfma_f32_16x16x32_bf16 v[42:45], v[150:153], v[182:185], v[42:45]
	v_mfma_f32_16x16x32_bf16 v[32:35], v[158:161], v[182:185], v[32:35]
	v_mfma_f32_16x16x32_bf16 v[24:27], v[150:153], v[190:193], v[24:27]
	v_mfma_f32_16x16x32_bf16 v[16:19], v[158:161], v[190:193], v[16:19]
	s_barrier
	s_add_u32 s14, s18, 0x18080
	s_addc_u32 s15, s19, 0
	s_add_i32 s18, s42, s44
	v_lshl_add_u64 v[144:145], s[14:15], 0, v[2:3]
	s_mov_b32 m0, s18
	s_nop 0
	global_load_lds_dwordx4 v[144:145], off
	v_lshl_add_u64 v[144:145], s[14:15], 0, v[134:135]
	s_add_i32 m0, s18, 0x2000
	s_nop 0
	global_load_lds_dwordx4 v[144:145], off
	s_waitcnt vmcnt(6)
	s_barrier
	v_mfma_f32_16x16x32_bf16 v[54:57], v[194:197], v[162:165], v[54:57]
	v_mfma_f32_16x16x32_bf16 v[46:49], v[202:205], v[162:165], v[46:49]
	v_mfma_f32_16x16x32_bf16 v[38:41], v[194:197], v[170:173], v[38:41]
	v_mfma_f32_16x16x32_bf16 v[28:31], v[202:205], v[170:173], v[28:31]
	v_mfma_f32_16x16x32_bf16 v[20:23], v[194:197], v[178:181], v[20:23]
	v_mfma_f32_16x16x32_bf16 v[12:15], v[202:205], v[178:181], v[12:15]
	v_mfma_f32_16x16x32_bf16 v[8:11], v[194:197], v[186:189], v[8:11]
	v_mfma_f32_16x16x32_bf16 v[4:7], v[202:205], v[186:189], v[4:7]
	v_mfma_f32_16x16x32_bf16 v[54:57], v[198:201], v[166:169], v[54:57]
	v_mfma_f32_16x16x32_bf16 v[46:49], v[206:209], v[166:169], v[46:49]
	v_mfma_f32_16x16x32_bf16 v[38:41], v[198:201], v[174:177], v[38:41]
	v_mfma_f32_16x16x32_bf16 v[28:31], v[206:209], v[174:177], v[28:31]
	v_mfma_f32_16x16x32_bf16 v[20:23], v[198:201], v[182:185], v[20:23]
	v_mfma_f32_16x16x32_bf16 v[12:15], v[206:209], v[182:185], v[12:15]
	v_mfma_f32_16x16x32_bf16 v[8:11], v[198:201], v[190:193], v[8:11]
	v_mfma_f32_16x16x32_bf16 v[4:7], v[206:209], v[190:193], v[4:7]
	s_add_i32 s78, s78, 2
	s_add_u32 s76, s76, 0x100
	s_addc_u32 s77, s77, 0
	s_cmp_gt_u32 s78, 3
	s_mov_b64 s[14:15], s[16:17]
	s_barrier
	s_cbranch_scc0 .LBB0_518
	v_lshl_or_b32 v146, s75, 8, v148
	v_lshl_add_u32 v152, s74, 8, v1
	v_ashrrev_i32_e32 v147, 31, v146
	v_mov_b64_e32 v[144:145], s[10:11]
	s_movk_i32 s16, 0xc00
	v_mad_i64_i32 v[150:151], s[14:15], v152, s16, v[144:145]
	v_lshlrev_b64 v[146:147], 1, v[146:147]
	v_lshl_add_u64 v[150:151], v[150:151], 0, v[146:147]
	v_cvt_pk_bf16_f32 v130, v130, v131
	v_cvt_pk_bf16_f32 v131, v132, v133
	v_cvt_pk_bf16_f32 v132, v126, v127
	v_cvt_pk_bf16_f32 v133, v128, v129
	global_store_dwordx4 v[150:151], v[130:133], off
	v_cvt_pk_bf16_f32 v118, v118, v119
	v_cvt_pk_bf16_f32 v119, v120, v121
	v_cvt_pk_bf16_f32 v120, v110, v111
	v_or_b32_e32 v110, 16, v152
	v_mad_i64_i32 v[110:111], s[14:15], v110, s16, v[144:145]
	v_cvt_pk_bf16_f32 v121, v112, v113
	global_store_dwordx4 v[150:151], v[118:121], off offset:256
	v_readlane_b32 s76, v254, 27
	s_and_b64 vcc, exec, s[4:5]
	v_lshl_add_u64 v[118:119], v[110:111], 0, v[146:147]
	v_cvt_pk_bf16_f32 v110, v122, v123
	v_cvt_pk_bf16_f32 v111, v124, v125
	v_cvt_pk_bf16_f32 v112, v114, v115
	v_cvt_pk_bf16_f32 v113, v116, v117
	global_store_dwordx4 v[118:119], v[110:113], off
	v_cvt_pk_bf16_f32 v102, v102, v103
	v_cvt_pk_bf16_f32 v103, v104, v105
	v_cvt_pk_bf16_f32 v104, v94, v95
	v_or_b32_e32 v94, 32, v152
	v_mad_i64_i32 v[94:95], s[14:15], v94, s16, v[144:145]
	v_cvt_pk_bf16_f32 v105, v96, v97
	global_store_dwordx4 v[118:119], v[102:105], off offset:256
	s_mov_b32 s75, s56
	s_mov_b32 s74, s57
	v_lshl_add_u64 v[102:103], v[94:95], 0, v[146:147]
	v_cvt_pk_bf16_f32 v94, v106, v107
	v_cvt_pk_bf16_f32 v95, v108, v109
	v_cvt_pk_bf16_f32 v96, v98, v99
	v_cvt_pk_bf16_f32 v97, v100, v101
	global_store_dwordx4 v[102:103], v[94:97], off
	v_cvt_pk_bf16_f32 v86, v86, v87
	v_cvt_pk_bf16_f32 v87, v88, v89
	v_cvt_pk_bf16_f32 v88, v78, v79
	v_or_b32_e32 v78, 48, v152
	v_mad_i64_i32 v[78:79], s[14:15], v78, s16, v[144:145]
	v_cvt_pk_bf16_f32 v89, v80, v81
	global_store_dwordx4 v[102:103], v[86:89], off offset:256
	v_readlane_b32 s77, v254, 28
	s_nop 0
	v_lshl_add_u64 v[86:87], v[78:79], 0, v[146:147]
	v_cvt_pk_bf16_f32 v78, v90, v91
	v_cvt_pk_bf16_f32 v79, v92, v93
	v_cvt_pk_bf16_f32 v80, v82, v83
	v_cvt_pk_bf16_f32 v81, v84, v85
	global_store_dwordx4 v[86:87], v[78:81], off
	v_cvt_pk_bf16_f32 v74, v74, v75
	v_cvt_pk_bf16_f32 v75, v76, v77
	v_cvt_pk_bf16_f32 v76, v70, v71
	v_add_u32_e32 v70, 0x80, v152
	v_mad_i64_i32 v[70:71], s[14:15], v70, s16, v[144:145]
	v_lshl_add_u64 v[70:71], v[70:71], 0, v[146:147]
	v_cvt_pk_bf16_f32 v77, v72, v73
	global_store_dwordx4 v[86:87], v[74:77], off offset:256
	v_cvt_pk_bf16_f32 v66, v66, v67
	v_cvt_pk_bf16_f32 v67, v68, v69
	v_cvt_pk_bf16_f32 v68, v62, v63
	v_cvt_pk_bf16_f32 v69, v64, v65
	global_store_dwordx4 v[70:71], v[66:69], off
	v_cvt_pk_bf16_f32 v54, v54, v55
	v_cvt_pk_bf16_f32 v55, v56, v57
	v_cvt_pk_bf16_f32 v56, v46, v47
	v_add_u32_e32 v46, 0x90, v152
	v_mad_i64_i32 v[46:47], s[14:15], v46, s16, v[144:145]
	v_cvt_pk_bf16_f32 v57, v48, v49
	global_store_dwordx4 v[70:71], v[54:57], off offset:256
	s_nop 1
	v_lshl_add_u64 v[54:55], v[46:47], 0, v[146:147]
	v_cvt_pk_bf16_f32 v46, v58, v59
	v_cvt_pk_bf16_f32 v47, v60, v61
	v_cvt_pk_bf16_f32 v48, v50, v51
	v_cvt_pk_bf16_f32 v49, v52, v53
	global_store_dwordx4 v[54:55], v[46:49], off
	v_cvt_pk_bf16_f32 v38, v38, v39
	v_cvt_pk_bf16_f32 v39, v40, v41
	v_cvt_pk_bf16_f32 v40, v28, v29
	v_add_u32_e32 v28, 0xa0, v152
	v_mad_i64_i32 v[28:29], s[14:15], v28, s16, v[144:145]
	v_cvt_pk_bf16_f32 v41, v30, v31
	global_store_dwordx4 v[54:55], v[38:41], off offset:256
	s_nop 1
	v_lshl_add_u64 v[38:39], v[28:29], 0, v[146:147]
	v_cvt_pk_bf16_f32 v28, v42, v43
	v_cvt_pk_bf16_f32 v29, v44, v45
	v_cvt_pk_bf16_f32 v30, v32, v33
	v_cvt_pk_bf16_f32 v31, v34, v35
	global_store_dwordx4 v[38:39], v[28:31], off
	v_cvt_pk_bf16_f32 v20, v20, v21
	v_cvt_pk_bf16_f32 v21, v22, v23
	v_cvt_pk_bf16_f32 v22, v12, v13
	v_add_u32_e32 v12, 0xb0, v152
	v_mad_i64_i32 v[12:13], s[14:15], v12, s16, v[144:145]
	v_cvt_pk_bf16_f32 v23, v14, v15
	global_store_dwordx4 v[38:39], v[20:23], off offset:256
	s_mov_b64 s[16:17], s[6:7]
	s_mov_b64 s[14:15], s[0:1]
	v_lshl_add_u64 v[20:21], v[12:13], 0, v[146:147]
	v_cvt_pk_bf16_f32 v12, v24, v25
	v_cvt_pk_bf16_f32 v13, v26, v27
	v_cvt_pk_bf16_f32 v14, v16, v17
	v_cvt_pk_bf16_f32 v15, v18, v19
	global_store_dwordx4 v[20:21], v[12:15], off
	v_cvt_pk_bf16_f32 v8, v8, v9
	v_cvt_pk_bf16_f32 v9, v10, v11
	v_cvt_pk_bf16_f32 v10, v4, v5
	v_cvt_pk_bf16_f32 v11, v6, v7
	global_store_dwordx4 v[20:21], v[8:11], off offset:256
	s_cbranch_vccz .LBB0_511
	s_waitcnt vmcnt(0)
	s_cmpk_gt_u32 s27, 0xff
	s_mov_b64 s[52:53], s[82:83]
	s_mov_b64 s[54:55], s[84:85]
	s_cbranch_scc1 .LBB0_522
	s_barrier

.LBB0_530:
	s_add_u32 s49, s42, s48
	s_addc_u32 s57, s43, 0
	s_add_u32 s52, s49, 0x100
	s_addc_u32 s53, s57, 0
	s_and_b64 s[50:51], s[46:47], exec
	s_cselect_b32 s53, s7, s53
	s_cselect_b32 s52, s86, s52
	s_add_u32 s48, s18, s48
	s_addc_u32 s50, s19, 0
	s_add_u32 s48, s48, 0x100
	s_addc_u32 s50, s50, 0
	s_add_i32 s94, 0, 0x10000
	s_and_b64 s[46:47], s[46:47], exec
	s_cselect_b32 s55, s1, s50
	s_cselect_b32 s54, s87, s48
	s_add_u32 s56, s49, 0x10080
	s_addc_u32 s57, s57, 0
	s_add_i32 vcc_lo, s94, s74
	s_add_i32 m0, s17, 0xc000
	s_add_i32 vcc_hi, s17, 0xe000
	s_add_i32 s97, 0, 0x14000
	s_add_i32 s96, vcc_lo, 0x2000
	s_add_u32 s50, s54, 0x10000
	v_add_u32_e32 v140, s94, v37
	s_addc_u32 s51, s55, 0
	s_add_i32 s93, s97, s74
	ds_read_b128 v[144:147], v140
	ds_read_b128 v[148:151], v140 offset:1024
	ds_read_b128 v[152:155], v140 offset:2048
	ds_read_b128 v[156:159], v140 offset:3072
	s_add_i32 s92, s93, 0x2000
	s_add_i32 s91, 0, 0x18000
	s_add_u32 s48, s52, 0x10000
	s_addc_u32 s49, s53, 0
	s_add_i32 s90, s91, s74
	s_add_i32 s89, 0, 0x1c000
	s_add_i32 s88, s90, 0x2000
	s_add_u32 s46, s54, 0x10080
	s_addc_u32 s47, s55, 0
	s_add_i32 s95, s89, s74
	s_add_i32 s94, s95, 0x2000
	v_lshl_add_u64 v[140:141], s[56:57], 0, v[138:139]
	ds_read_b128 v[160:163], v143
	ds_read_b128 v[164:167], v143 offset:1024
	ds_read_b128 v[168:171], v143 offset:2048
	ds_read_b128 v[172:175], v143 offset:3072
	ds_read_b128 v[176:179], v143 offset:4096
	ds_read_b128 v[180:183], v143 offset:5120
	ds_read_b128 v[184:187], v143 offset:6144
	ds_read_b128 v[188:191], v143 offset:7168
	global_load_lds_dwordx4 v[140:141], off
	v_lshl_add_u64 v[140:141], s[56:57], 0, v[136:137]
	s_mov_b32 m0, vcc_hi
	s_nop 0
	global_load_lds_dwordx4 v[140:141], off
	s_waitcnt lgkmcnt(8)
	s_barrier
	s_waitcnt lgkmcnt(0)
	s_waitcnt lgkmcnt(0)
	v_mfma_f32_16x16x32_bf16 v[130:133], v[144:147], v[160:163], v[130:133]
	v_mfma_f32_16x16x32_bf16 v[126:129], v[152:155], v[160:163], v[126:129]
	v_mfma_f32_16x16x32_bf16 v[122:125], v[144:147], v[168:171], v[122:125]
	v_mfma_f32_16x16x32_bf16 v[114:117], v[152:155], v[168:171], v[114:117]
	v_mfma_f32_16x16x32_bf16 v[106:109], v[144:147], v[176:179], v[106:109]
	v_mfma_f32_16x16x32_bf16 v[98:101], v[152:155], v[176:179], v[98:101]
	v_mfma_f32_16x16x32_bf16 v[90:93], v[144:147], v[184:187], v[90:93]
	v_mfma_f32_16x16x32_bf16 v[82:85], v[152:155], v[184:187], v[82:85]
	v_mfma_f32_16x16x32_bf16 v[130:133], v[148:151], v[164:167], v[130:133]
	v_mfma_f32_16x16x32_bf16 v[126:129], v[156:159], v[164:167], v[126:129]
	v_mfma_f32_16x16x32_bf16 v[122:125], v[148:151], v[172:175], v[122:125]
	v_mfma_f32_16x16x32_bf16 v[114:117], v[156:159], v[172:175], v[114:117]
	v_mfma_f32_16x16x32_bf16 v[106:109], v[148:151], v[180:183], v[106:109]
	v_mfma_f32_16x16x32_bf16 v[98:101], v[156:159], v[180:183], v[98:101]
	v_mfma_f32_16x16x32_bf16 v[90:93], v[148:151], v[188:191], v[90:93]
	v_mfma_f32_16x16x32_bf16 v[82:85], v[156:159], v[188:191], v[82:85]
	s_barrier
	v_add_u32_e32 v140, s97, v37
	s_mov_b32 m0, vcc_lo
	ds_read_b128 v[192:195], v140
	ds_read_b128 v[196:199], v140 offset:1024
	ds_read_b128 v[200:203], v140 offset:2048
	ds_read_b128 v[204:207], v140 offset:3072
	v_lshl_add_u64 v[140:141], s[54:55], 0, v[2:3]
	global_load_lds_dwordx4 v[140:141], off
	v_lshl_add_u64 v[208:209], s[54:55], 0, v[134:135]
	s_mov_b32 m0, s96
	s_nop 0
	global_load_lds_dwordx4 v[208:209], off
	s_barrier
	s_waitcnt lgkmcnt(0)
	s_waitcnt lgkmcnt(0)
	v_mfma_f32_16x16x32_bf16 v[118:121], v[192:195], v[160:163], v[118:121]
	v_mfma_f32_16x16x32_bf16 v[110:113], v[200:203], v[160:163], v[110:113]
	v_mfma_f32_16x16x32_bf16 v[102:105], v[192:195], v[168:171], v[102:105]
	v_mfma_f32_16x16x32_bf16 v[94:97], v[200:203], v[168:171], v[94:97]
	v_mfma_f32_16x16x32_bf16 v[86:89], v[192:195], v[176:179], v[86:89]
	v_mfma_f32_16x16x32_bf16 v[78:81], v[200:203], v[176:179], v[78:81]
	v_mfma_f32_16x16x32_bf16 v[74:77], v[192:195], v[184:187], v[74:77]
	v_mfma_f32_16x16x32_bf16 v[70:73], v[200:203], v[184:187], v[70:73]
	v_mfma_f32_16x16x32_bf16 v[118:121], v[196:199], v[164:167], v[118:121]
	v_mfma_f32_16x16x32_bf16 v[110:113], v[204:207], v[164:167], v[110:113]
	v_mfma_f32_16x16x32_bf16 v[102:105], v[196:199], v[172:175], v[102:105]
	v_mfma_f32_16x16x32_bf16 v[94:97], v[204:207], v[172:175], v[94:97]
	v_mfma_f32_16x16x32_bf16 v[86:89], v[196:199], v[180:183], v[86:89]
	v_mfma_f32_16x16x32_bf16 v[78:81], v[204:207], v[180:183], v[78:81]
	v_mfma_f32_16x16x32_bf16 v[74:77], v[196:199], v[188:191], v[74:77]
	v_mfma_f32_16x16x32_bf16 v[70:73], v[204:207], v[188:191], v[70:73]
	s_mov_b32 m0, s17
	v_lshl_add_u64 v[210:211], s[52:53], 0, v[138:139]
	s_barrier
	ds_read_b128 v[160:163], v143 offset:16384
	ds_read_b128 v[164:167], v143 offset:17408
	ds_read_b128 v[168:171], v143 offset:18432
	ds_read_b128 v[172:175], v143 offset:19456
	ds_read_b128 v[176:179], v143 offset:20480
	ds_read_b128 v[180:183], v143 offset:21504
	ds_read_b128 v[184:187], v143 offset:22528
	ds_read_b128 v[188:191], v143 offset:23552
	global_load_lds_dwordx4 v[210:211], off
	v_lshl_add_u64 v[212:213], s[52:53], 0, v[136:137]
	s_mov_b32 m0, s78
	s_nop 0
	global_load_lds_dwordx4 v[212:213], off
	s_barrier
	s_waitcnt lgkmcnt(0)
	s_waitcnt lgkmcnt(0)
	v_mfma_f32_16x16x32_bf16 v[66:69], v[144:147], v[160:163], v[66:69]
	v_mfma_f32_16x16x32_bf16 v[62:65], v[152:155], v[160:163], v[62:65]
	v_mfma_f32_16x16x32_bf16 v[58:61], v[144:147], v[168:171], v[58:61]
	v_mfma_f32_16x16x32_bf16 v[50:53], v[152:155], v[168:171], v[50:53]
	v_mfma_f32_16x16x32_bf16 v[42:45], v[144:147], v[176:179], v[42:45]
	v_mfma_f32_16x16x32_bf16 v[32:35], v[152:155], v[176:179], v[32:35]
	v_mfma_f32_16x16x32_bf16 v[24:27], v[144:147], v[184:187], v[24:27]
	v_mfma_f32_16x16x32_bf16 v[16:19], v[152:155], v[184:187], v[16:19]
	v_mfma_f32_16x16x32_bf16 v[66:69], v[148:151], v[164:167], v[66:69]
	v_mfma_f32_16x16x32_bf16 v[62:65], v[156:159], v[164:167], v[62:65]
	v_mfma_f32_16x16x32_bf16 v[58:61], v[148:151], v[172:175], v[58:61]
	v_mfma_f32_16x16x32_bf16 v[50:53], v[156:159], v[172:175], v[50:53]
	v_mfma_f32_16x16x32_bf16 v[42:45], v[148:151], v[180:183], v[42:45]
	v_mfma_f32_16x16x32_bf16 v[32:35], v[156:159], v[180:183], v[32:35]
	v_mfma_f32_16x16x32_bf16 v[24:27], v[148:151], v[188:191], v[24:27]
	v_mfma_f32_16x16x32_bf16 v[16:19], v[156:159], v[188:191], v[16:19]
	s_barrier
	s_mov_b32 m0, s93
	v_lshl_add_u64 v[144:145], s[50:51], 0, v[2:3]
	global_load_lds_dwordx4 v[144:145], off
	v_lshl_add_u64 v[144:145], s[50:51], 0, v[134:135]
	s_mov_b32 m0, s92
	s_nop 0
	global_load_lds_dwordx4 v[144:145], off
	s_waitcnt vmcnt(6)
	s_barrier
	v_mfma_f32_16x16x32_bf16 v[54:57], v[192:195], v[160:163], v[54:57]
	v_mfma_f32_16x16x32_bf16 v[46:49], v[200:203], v[160:163], v[46:49]
	v_mfma_f32_16x16x32_bf16 v[38:41], v[192:195], v[168:171], v[38:41]
	v_mfma_f32_16x16x32_bf16 v[28:31], v[200:203], v[168:171], v[28:31]
	v_mfma_f32_16x16x32_bf16 v[20:23], v[192:195], v[176:179], v[20:23]
	v_mfma_f32_16x16x32_bf16 v[12:15], v[200:203], v[176:179], v[12:15]
	v_mfma_f32_16x16x32_bf16 v[8:11], v[192:195], v[184:187], v[8:11]
	v_mfma_f32_16x16x32_bf16 v[4:7], v[200:203], v[184:187], v[4:7]
	v_mfma_f32_16x16x32_bf16 v[54:57], v[196:199], v[164:167], v[54:57]
	v_mfma_f32_16x16x32_bf16 v[46:49], v[204:207], v[164:167], v[46:49]
	v_mfma_f32_16x16x32_bf16 v[38:41], v[196:199], v[172:175], v[38:41]
	v_mfma_f32_16x16x32_bf16 v[28:31], v[204:207], v[172:175], v[28:31]
	v_mfma_f32_16x16x32_bf16 v[20:23], v[196:199], v[180:183], v[20:23]
	v_mfma_f32_16x16x32_bf16 v[12:15], v[204:207], v[180:183], v[12:15]
	v_mfma_f32_16x16x32_bf16 v[8:11], v[196:199], v[188:191], v[8:11]
	v_mfma_f32_16x16x32_bf16 v[4:7], v[204:207], v[188:191], v[4:7]
	v_add_u32_e32 v156, s91, v37
	s_barrier
	ds_read_b128 v[144:147], v156
	ds_read_b128 v[148:151], v156 offset:1024
	ds_read_b128 v[152:155], v156 offset:2048
	ds_read_b128 v[156:159], v156 offset:3072
	s_mov_b32 m0, s79
	v_lshl_add_u64 v[192:193], s[48:49], 0, v[138:139]
	ds_read_b128 v[160:163], v143 offset:32768
	ds_read_b128 v[164:167], v143 offset:33792
	ds_read_b128 v[168:171], v143 offset:34816
	ds_read_b128 v[172:175], v143 offset:35840
	ds_read_b128 v[176:179], v143 offset:36864
	ds_read_b128 v[180:183], v143 offset:37888
	ds_read_b128 v[184:187], v143 offset:38912
	ds_read_b128 v[188:191], v143 offset:39936
	global_load_lds_dwordx4 v[192:193], off
	v_lshl_add_u64 v[192:193], s[48:49], 0, v[136:137]
	s_mov_b32 m0, s80
	s_nop 0
	global_load_lds_dwordx4 v[192:193], off
	s_waitcnt lgkmcnt(8)
	s_barrier
	s_waitcnt lgkmcnt(0)
	s_waitcnt lgkmcnt(0)
	v_mfma_f32_16x16x32_bf16 v[130:133], v[144:147], v[160:163], v[130:133]
	v_mfma_f32_16x16x32_bf16 v[126:129], v[152:155], v[160:163], v[126:129]
	v_mfma_f32_16x16x32_bf16 v[122:125], v[144:147], v[168:171], v[122:125]
	v_mfma_f32_16x16x32_bf16 v[114:117], v[152:155], v[168:171], v[114:117]
	v_mfma_f32_16x16x32_bf16 v[106:109], v[144:147], v[176:179], v[106:109]
	v_mfma_f32_16x16x32_bf16 v[98:101], v[152:155], v[176:179], v[98:101]
	v_mfma_f32_16x16x32_bf16 v[90:93], v[144:147], v[184:187], v[90:93]
	v_mfma_f32_16x16x32_bf16 v[82:85], v[152:155], v[184:187], v[82:85]
	v_mfma_f32_16x16x32_bf16 v[130:133], v[148:151], v[164:167], v[130:133]
	v_mfma_f32_16x16x32_bf16 v[126:129], v[156:159], v[164:167], v[126:129]
	v_mfma_f32_16x16x32_bf16 v[122:125], v[148:151], v[172:175], v[122:125]
	v_mfma_f32_16x16x32_bf16 v[114:117], v[156:159], v[172:175], v[114:117]
	v_mfma_f32_16x16x32_bf16 v[106:109], v[148:151], v[180:183], v[106:109]
	v_mfma_f32_16x16x32_bf16 v[98:101], v[156:159], v[180:183], v[98:101]
	v_mfma_f32_16x16x32_bf16 v[90:93], v[148:151], v[188:191], v[90:93]
	v_mfma_f32_16x16x32_bf16 v[82:85], v[156:159], v[188:191], v[82:85]
	s_barrier
	s_mov_b32 m0, s90
	v_add_u32_e32 v204, s89, v37
	v_lshl_add_u64 v[140:141], v[140:141], 0, s[24:25]
	ds_read_b128 v[192:195], v204
	ds_read_b128 v[196:199], v204 offset:1024
	ds_read_b128 v[200:203], v204 offset:2048
	ds_read_b128 v[204:207], v204 offset:3072
	global_load_lds_dwordx4 v[140:141], off
	v_lshl_add_u64 v[140:141], v[208:209], 0, s[24:25]
	s_mov_b32 m0, s88
	s_nop 0
	global_load_lds_dwordx4 v[140:141], off
	s_barrier
	s_waitcnt lgkmcnt(0)
	s_waitcnt lgkmcnt(0)
	v_mfma_f32_16x16x32_bf16 v[118:121], v[192:195], v[160:163], v[118:121]
	v_mfma_f32_16x16x32_bf16 v[110:113], v[200:203], v[160:163], v[110:113]
	v_mfma_f32_16x16x32_bf16 v[102:105], v[192:195], v[168:171], v[102:105]
	v_mfma_f32_16x16x32_bf16 v[94:97], v[200:203], v[168:171], v[94:97]
	v_mfma_f32_16x16x32_bf16 v[86:89], v[192:195], v[176:179], v[86:89]
	v_mfma_f32_16x16x32_bf16 v[78:81], v[200:203], v[176:179], v[78:81]
	v_mfma_f32_16x16x32_bf16 v[74:77], v[192:195], v[184:187], v[74:77]
	v_mfma_f32_16x16x32_bf16 v[70:73], v[200:203], v[184:187], v[70:73]
	v_mfma_f32_16x16x32_bf16 v[118:121], v[196:199], v[164:167], v[118:121]
	v_mfma_f32_16x16x32_bf16 v[110:113], v[204:207], v[164:167], v[110:113]
	v_mfma_f32_16x16x32_bf16 v[102:105], v[196:199], v[172:175], v[102:105]
	v_mfma_f32_16x16x32_bf16 v[94:97], v[204:207], v[172:175], v[94:97]
	v_mfma_f32_16x16x32_bf16 v[86:89], v[196:199], v[180:183], v[86:89]
	v_mfma_f32_16x16x32_bf16 v[78:81], v[204:207], v[180:183], v[78:81]
	v_mfma_f32_16x16x32_bf16 v[74:77], v[196:199], v[188:191], v[74:77]
	v_mfma_f32_16x16x32_bf16 v[70:73], v[204:207], v[188:191], v[70:73]
	s_mov_b32 m0, s81
	v_lshl_add_u64 v[140:141], v[210:211], 0, s[24:25]
	s_barrier
	ds_read_b128 v[160:163], v143 offset:49152
	ds_read_b128 v[164:167], v143 offset:50176
	ds_read_b128 v[168:171], v143 offset:51200
	ds_read_b128 v[172:175], v143 offset:52224
	ds_read_b128 v[176:179], v143 offset:53248
	ds_read_b128 v[180:183], v143 offset:54272
	ds_read_b128 v[184:187], v143 offset:55296
	ds_read_b128 v[188:191], v143 offset:56320
	global_load_lds_dwordx4 v[140:141], off
	v_lshl_add_u64 v[140:141], v[212:213], 0, s[24:25]
	s_mov_b32 m0, s82
	s_nop 0
	global_load_lds_dwordx4 v[140:141], off
	s_barrier
	s_waitcnt lgkmcnt(0)
	s_waitcnt lgkmcnt(0)
	v_mfma_f32_16x16x32_bf16 v[66:69], v[144:147], v[160:163], v[66:69]
	v_mfma_f32_16x16x32_bf16 v[62:65], v[152:155], v[160:163], v[62:65]
	v_mfma_f32_16x16x32_bf16 v[58:61], v[144:147], v[168:171], v[58:61]
	v_mfma_f32_16x16x32_bf16 v[50:53], v[152:155], v[168:171], v[50:53]
	v_mfma_f32_16x16x32_bf16 v[42:45], v[144:147], v[176:179], v[42:45]
	v_mfma_f32_16x16x32_bf16 v[32:35], v[152:155], v[176:179], v[32:35]
	v_mfma_f32_16x16x32_bf16 v[24:27], v[144:147], v[184:187], v[24:27]
	v_mfma_f32_16x16x32_bf16 v[16:19], v[152:155], v[184:187], v[16:19]
	v_mfma_f32_16x16x32_bf16 v[66:69], v[148:151], v[164:167], v[66:69]
	v_mfma_f32_16x16x32_bf16 v[62:65], v[156:159], v[164:167], v[62:65]
	v_mfma_f32_16x16x32_bf16 v[58:61], v[148:151], v[172:175], v[58:61]
	v_mfma_f32_16x16x32_bf16 v[50:53], v[156:159], v[172:175], v[50:53]
	v_mfma_f32_16x16x32_bf16 v[42:45], v[148:151], v[180:183], v[42:45]
	v_mfma_f32_16x16x32_bf16 v[32:35], v[156:159], v[180:183], v[32:35]
	v_mfma_f32_16x16x32_bf16 v[24:27], v[148:151], v[188:191], v[24:27]
	v_mfma_f32_16x16x32_bf16 v[16:19], v[156:159], v[188:191], v[16:19]
	s_barrier
	s_mov_b32 m0, s95
	v_lshl_add_u64 v[140:141], s[46:47], 0, v[2:3]
	global_load_lds_dwordx4 v[140:141], off
	v_lshl_add_u64 v[140:141], s[46:47], 0, v[134:135]
	s_mov_b32 m0, s94
	s_nop 0
	global_load_lds_dwordx4 v[140:141], off
	s_waitcnt vmcnt(6)
	s_barrier
	v_mfma_f32_16x16x32_bf16 v[54:57], v[192:195], v[160:163], v[54:57]
	v_mfma_f32_16x16x32_bf16 v[46:49], v[200:203], v[160:163], v[46:49]
	v_mfma_f32_16x16x32_bf16 v[38:41], v[192:195], v[168:171], v[38:41]
	v_mfma_f32_16x16x32_bf16 v[28:31], v[200:203], v[168:171], v[28:31]
	v_mfma_f32_16x16x32_bf16 v[20:23], v[192:195], v[176:179], v[20:23]
	v_mfma_f32_16x16x32_bf16 v[12:15], v[200:203], v[176:179], v[12:15]
	v_mfma_f32_16x16x32_bf16 v[8:11], v[192:195], v[184:187], v[8:11]
	v_mfma_f32_16x16x32_bf16 v[4:7], v[200:203], v[184:187], v[4:7]
	v_mfma_f32_16x16x32_bf16 v[54:57], v[196:199], v[164:167], v[54:57]
	v_mfma_f32_16x16x32_bf16 v[46:49], v[204:207], v[164:167], v[46:49]
	v_mfma_f32_16x16x32_bf16 v[38:41], v[196:199], v[172:175], v[38:41]
	v_mfma_f32_16x16x32_bf16 v[28:31], v[204:207], v[172:175], v[28:31]
	v_mfma_f32_16x16x32_bf16 v[20:23], v[196:199], v[180:183], v[20:23]
	v_mfma_f32_16x16x32_bf16 v[12:15], v[204:207], v[180:183], v[12:15]
	v_mfma_f32_16x16x32_bf16 v[8:11], v[196:199], v[188:191], v[8:11]
	v_mfma_f32_16x16x32_bf16 v[4:7], v[204:207], v[188:191], v[4:7]
	s_movk_i32 s48, 0x100
	s_andn2_b64 vcc, exec, s[44:45]
	s_mov_b64 s[46:47], -1
	s_mov_b64 s[44:45], 0
	s_barrier
	s_cbranch_vccz .LBB0_530
	v_lshl_add_u32 v144, s16, 8, v1
	v_lshl_or_b32 v140, s85, 8, v142
	v_ashrrev_i32_e32 v145, 31, v144
	v_ashrrev_i32_e32 v141, 31, v140
	v_lshlrev_b64 v[146:147], 12, v[144:145]
	v_lshl_add_u64 v[146:147], s[8:9], 0, v[146:147]
	v_lshlrev_b64 v[148:149], 1, v[140:141]
	v_lshl_add_u64 v[140:141], v[146:147], 0, v[148:149]
	v_cvt_pk_bf16_f32 v130, v130, v131
	v_cvt_pk_bf16_f32 v131, v132, v133
	v_cvt_pk_bf16_f32 v132, v126, v127
	v_cvt_pk_bf16_f32 v133, v128, v129
	global_store_dwordx4 v[140:141], v[130:133], off
	v_cvt_pk_bf16_f32 v118, v118, v119
	v_cvt_pk_bf16_f32 v119, v120, v121
	v_cvt_pk_bf16_f32 v120, v110, v111
	v_or_b32_e32 v110, 16, v144
	v_ashrrev_i32_e32 v111, 31, v110
	v_lshlrev_b64 v[110:111], 12, v[110:111]
	v_lshl_add_u64 v[110:111], s[8:9], 0, v[110:111]
	v_cvt_pk_bf16_f32 v121, v112, v113
	global_store_dwordx4 v[140:141], v[118:121], off offset:256
	s_mov_b32 s1, 0x80000
	s_mov_b64 s[18:19], 0x80000
	v_lshl_add_u64 v[118:119], v[110:111], 0, v[148:149]
	v_cvt_pk_bf16_f32 v110, v122, v123
	v_cvt_pk_bf16_f32 v111, v124, v125
	v_cvt_pk_bf16_f32 v112, v114, v115
	v_cvt_pk_bf16_f32 v113, v116, v117
	global_store_dwordx4 v[118:119], v[110:113], off
	v_cvt_pk_bf16_f32 v102, v102, v103
	v_cvt_pk_bf16_f32 v103, v104, v105
	v_cvt_pk_bf16_f32 v104, v94, v95
	v_or_b32_e32 v94, 32, v144
	v_ashrrev_i32_e32 v95, 31, v94
	v_lshlrev_b64 v[94:95], 12, v[94:95]
	v_lshl_add_u64 v[94:95], s[8:9], 0, v[94:95]
	v_cvt_pk_bf16_f32 v105, v96, v97
	global_store_dwordx4 v[118:119], v[102:105], off offset:256
	s_mov_b32 s85, s0
	s_mov_b32 s16, s6
	v_lshl_add_u64 v[102:103], v[94:95], 0, v[148:149]
	v_cvt_pk_bf16_f32 v94, v106, v107
	v_cvt_pk_bf16_f32 v95, v108, v109
	v_cvt_pk_bf16_f32 v96, v98, v99
	v_cvt_pk_bf16_f32 v97, v100, v101
	global_store_dwordx4 v[102:103], v[94:97], off
	v_cvt_pk_bf16_f32 v86, v86, v87
	v_cvt_pk_bf16_f32 v87, v88, v89
	v_cvt_pk_bf16_f32 v88, v78, v79
	v_or_b32_e32 v78, 48, v144
	v_ashrrev_i32_e32 v79, 31, v78
	v_lshlrev_b64 v[78:79], 12, v[78:79]
	v_lshl_add_u64 v[78:79], s[8:9], 0, v[78:79]
	v_cvt_pk_bf16_f32 v89, v80, v81
	global_store_dwordx4 v[102:103], v[86:89], off offset:256
	s_mov_b64 s[42:43], s[10:11]
	s_nop 0
	v_lshl_add_u64 v[86:87], v[78:79], 0, v[148:149]
	v_cvt_pk_bf16_f32 v78, v90, v91
	v_cvt_pk_bf16_f32 v79, v92, v93
	v_cvt_pk_bf16_f32 v80, v82, v83
	v_cvt_pk_bf16_f32 v81, v84, v85
	global_store_dwordx4 v[86:87], v[78:81], off
	v_cvt_pk_bf16_f32 v74, v74, v75
	v_cvt_pk_bf16_f32 v75, v76, v77
	v_cvt_pk_bf16_f32 v76, v70, v71
	v_cvt_pk_bf16_f32 v77, v72, v73
	global_store_dwordx4 v[86:87], v[74:77], off offset:256
	v_cvt_pk_bf16_f32 v66, v66, v67
	v_cvt_pk_bf16_f32 v67, v68, v69
	v_cvt_pk_bf16_f32 v68, v62, v63
	v_add_co_u32_e32 v62, vcc, s1, v140
	v_lshl_add_u64 v[70:71], v[140:141], 0, s[18:19]
	s_nop 0
	v_addc_co_u32_e32 v63, vcc, 0, v141, vcc
	s_mov_b32 s1, 0x90000
	v_cvt_pk_bf16_f32 v69, v64, v65
	global_store_dwordx4 v[62:63], v[66:69], off
	v_cvt_pk_bf16_f32 v54, v54, v55
	v_cvt_pk_bf16_f32 v55, v56, v57
	v_cvt_pk_bf16_f32 v56, v46, v47
	v_cvt_pk_bf16_f32 v57, v48, v49
	global_store_dwordx4 v[70:71], v[54:57], off offset:256
	s_mov_b64 s[18:19], 0x90000
	v_cvt_pk_bf16_f32 v46, v58, v59
	v_cvt_pk_bf16_f32 v47, v60, v61
	v_cvt_pk_bf16_f32 v48, v50, v51
	v_add_co_u32_e32 v50, vcc, s1, v140
	v_lshl_add_u64 v[54:55], v[140:141], 0, s[18:19]
	s_nop 0
	v_addc_co_u32_e32 v51, vcc, 0, v141, vcc
	s_mov_b32 s1, 0xa0000
	v_cvt_pk_bf16_f32 v49, v52, v53
	global_store_dwordx4 v[50:51], v[46:49], off
	v_cvt_pk_bf16_f32 v38, v38, v39
	v_cvt_pk_bf16_f32 v39, v40, v41
	v_cvt_pk_bf16_f32 v40, v28, v29
	v_cvt_pk_bf16_f32 v41, v30, v31
	global_store_dwordx4 v[54:55], v[38:41], off offset:256
	s_mov_b64 s[18:19], 0xa0000
	v_cvt_pk_bf16_f32 v28, v42, v43
	v_cvt_pk_bf16_f32 v29, v44, v45
	v_cvt_pk_bf16_f32 v30, v32, v33
	v_add_co_u32_e32 v32, vcc, s1, v140
	v_lshl_add_u64 v[38:39], v[140:141], 0, s[18:19]
	s_nop 0
	v_addc_co_u32_e32 v33, vcc, 0, v141, vcc
	s_mov_b32 s1, 0xb0000
	v_cvt_pk_bf16_f32 v31, v34, v35
	global_store_dwordx4 v[32:33], v[28:31], off
	v_cvt_pk_bf16_f32 v20, v20, v21
	v_cvt_pk_bf16_f32 v21, v22, v23
	v_cvt_pk_bf16_f32 v22, v12, v13
	v_cvt_pk_bf16_f32 v23, v14, v15
	global_store_dwordx4 v[38:39], v[20:23], off offset:256
	v_cvt_pk_bf16_f32 v12, v24, v25
	v_cvt_pk_bf16_f32 v13, v26, v27
	v_cvt_pk_bf16_f32 v14, v16, v17
	v_add_co_u32_e32 v16, vcc, s1, v140
	s_nop 0
	v_lshl_add_u64 v[20:21], v[140:141], 0, s[40:41]
	v_addc_co_u32_e32 v17, vcc, 0, v141, vcc
	s_and_b64 vcc, exec, s[4:5]
	s_mov_b64 s[18:19], s[14:15]
	v_cvt_pk_bf16_f32 v15, v18, v19
	global_store_dwordx4 v[16:17], v[12:15], off
	v_cvt_pk_bf16_f32 v8, v8, v9
	v_cvt_pk_bf16_f32 v9, v10, v11
	v_cvt_pk_bf16_f32 v10, v4, v5
	v_cvt_pk_bf16_f32 v11, v6, v7
	global_store_dwordx4 v[20:21], v[8:11], off offset:256
	s_cbranch_vccz .LBB0_527
	s_waitcnt vmcnt(0)
	s_cmpk_gt_u32 s27, 0xff
	s_cbranch_scc1 .LBB0_534
	s_barrier

.LBB0_799:
	s_add_u32 s18, s16, 0xfffc0080
	s_addc_u32 s19, s17, -1
	s_add_i32 s55, 0, 0x10000
	v_add_u32_e32 v158, s55, v37
	ds_read_b128 v[144:147], v158
	ds_read_b128 v[150:153], v158 offset:1024
	ds_read_b128 v[154:157], v158 offset:2048
	ds_read_b128 v[162:165], v158 offset:3072
	s_cmp_eq_u32 s54, 4
	s_cselect_b32 s37, s7, s19
	s_cselect_b32 s36, s9, s18
	s_cselect_b32 s19, s1, s53
	s_cselect_b32 s18, s51, s52
	v_lshl_add_u64 v[158:159], s[16:17], 0, v[140:141]
	s_add_i32 m0, s11, 0xc000
	ds_read_b128 v[166:169], v149
	ds_read_b128 v[170:173], v149 offset:1024
	ds_read_b128 v[174:177], v149 offset:2048
	ds_read_b128 v[178:181], v149 offset:3072
	ds_read_b128 v[182:185], v149 offset:4096
	ds_read_b128 v[186:189], v149 offset:5120
	ds_read_b128 v[190:193], v149 offset:6144
	ds_read_b128 v[194:197], v149 offset:7168
	global_load_lds_dwordx4 v[158:159], off
	v_lshl_add_u64 v[158:159], s[16:17], 0, v[142:143]
	s_add_i32 m0, s11, 0xe000
	s_nop 0
	global_load_lds_dwordx4 v[158:159], off
	s_waitcnt lgkmcnt(8)
	s_barrier
	s_waitcnt lgkmcnt(0)
	s_waitcnt lgkmcnt(0)
	v_mfma_f32_16x16x32_bf16 v[130:133], v[144:147], v[166:169], v[130:133]
	v_mfma_f32_16x16x32_bf16 v[126:129], v[154:157], v[166:169], v[126:129]
	v_mfma_f32_16x16x32_bf16 v[122:125], v[144:147], v[174:177], v[122:125]
	v_mfma_f32_16x16x32_bf16 v[114:117], v[154:157], v[174:177], v[114:117]
	v_mfma_f32_16x16x32_bf16 v[106:109], v[144:147], v[182:185], v[106:109]
	v_mfma_f32_16x16x32_bf16 v[98:101], v[154:157], v[182:185], v[98:101]
	v_mfma_f32_16x16x32_bf16 v[90:93], v[144:147], v[190:193], v[90:93]
	v_mfma_f32_16x16x32_bf16 v[82:85], v[154:157], v[190:193], v[82:85]
	v_mfma_f32_16x16x32_bf16 v[130:133], v[150:153], v[170:173], v[130:133]
	v_mfma_f32_16x16x32_bf16 v[126:129], v[162:165], v[170:173], v[126:129]
	v_mfma_f32_16x16x32_bf16 v[122:125], v[150:153], v[178:181], v[122:125]
	v_mfma_f32_16x16x32_bf16 v[114:117], v[162:165], v[178:181], v[114:117]
	v_mfma_f32_16x16x32_bf16 v[106:109], v[150:153], v[186:189], v[106:109]
	v_mfma_f32_16x16x32_bf16 v[98:101], v[162:165], v[186:189], v[98:101]
	v_mfma_f32_16x16x32_bf16 v[90:93], v[150:153], v[194:197], v[90:93]
	v_mfma_f32_16x16x32_bf16 v[82:85], v[162:165], v[194:197], v[82:85]
	s_barrier
	s_add_i32 s74, 0, 0x14000
	v_add_u32_e32 v158, s74, v37
	s_add_i32 s55, s55, s38
	ds_read_b128 v[198:201], v158
	ds_read_b128 v[202:205], v158 offset:1024
	ds_read_b128 v[206:209], v158 offset:2048
	ds_read_b128 v[210:213], v158 offset:3072
	v_lshl_add_u64 v[158:159], s[18:19], 0, v[2:3]
	s_mov_b32 m0, s55
	v_lshl_add_u64 v[160:161], s[18:19], 0, v[134:135]
	global_load_lds_dwordx4 v[158:159], off
	s_add_i32 m0, s55, 0x2000
	s_nop 0
	global_load_lds_dwordx4 v[160:161], off
	s_barrier
	s_waitcnt lgkmcnt(0)
	s_waitcnt lgkmcnt(0)
	v_mfma_f32_16x16x32_bf16 v[118:121], v[198:201], v[166:169], v[118:121]
	v_mfma_f32_16x16x32_bf16 v[110:113], v[206:209], v[166:169], v[110:113]
	v_mfma_f32_16x16x32_bf16 v[102:105], v[198:201], v[174:177], v[102:105]
	v_mfma_f32_16x16x32_bf16 v[94:97], v[206:209], v[174:177], v[94:97]
	v_mfma_f32_16x16x32_bf16 v[86:89], v[198:201], v[182:185], v[86:89]
	v_mfma_f32_16x16x32_bf16 v[78:81], v[206:209], v[182:185], v[78:81]
	v_mfma_f32_16x16x32_bf16 v[74:77], v[198:201], v[190:193], v[74:77]
	v_mfma_f32_16x16x32_bf16 v[70:73], v[206:209], v[190:193], v[70:73]
	v_mfma_f32_16x16x32_bf16 v[118:121], v[202:205], v[170:173], v[118:121]
	v_mfma_f32_16x16x32_bf16 v[110:113], v[210:213], v[170:173], v[110:113]
	v_mfma_f32_16x16x32_bf16 v[102:105], v[202:205], v[178:181], v[102:105]
	v_mfma_f32_16x16x32_bf16 v[94:97], v[210:213], v[178:181], v[94:97]
	v_mfma_f32_16x16x32_bf16 v[86:89], v[202:205], v[186:189], v[86:89]
	v_mfma_f32_16x16x32_bf16 v[78:81], v[210:213], v[186:189], v[78:81]
	v_mfma_f32_16x16x32_bf16 v[74:77], v[202:205], v[194:197], v[74:77]
	v_mfma_f32_16x16x32_bf16 v[70:73], v[210:213], v[194:197], v[70:73]
	s_mov_b32 m0, s11
	v_lshl_add_u64 v[214:215], s[36:37], 0, v[138:139]
	s_barrier
	ds_read_b128 v[166:169], v149 offset:16384
	ds_read_b128 v[170:173], v149 offset:17408
	ds_read_b128 v[174:177], v149 offset:18432
	ds_read_b128 v[178:181], v149 offset:19456
	ds_read_b128 v[182:185], v149 offset:20480
	ds_read_b128 v[186:189], v149 offset:21504
	ds_read_b128 v[190:193], v149 offset:22528
	ds_read_b128 v[194:197], v149 offset:23552
	global_load_lds_dwordx4 v[214:215], off
	v_lshl_add_u64 v[216:217], s[36:37], 0, v[136:137]
	s_mov_b32 m0, s42
	s_nop 0
	global_load_lds_dwordx4 v[216:217], off
	s_barrier
	s_waitcnt lgkmcnt(0)
	s_waitcnt lgkmcnt(0)
	v_mfma_f32_16x16x32_bf16 v[66:69], v[144:147], v[166:169], v[66:69]
	v_mfma_f32_16x16x32_bf16 v[62:65], v[154:157], v[166:169], v[62:65]
	v_mfma_f32_16x16x32_bf16 v[58:61], v[144:147], v[174:177], v[58:61]
	v_mfma_f32_16x16x32_bf16 v[50:53], v[154:157], v[174:177], v[50:53]
	v_mfma_f32_16x16x32_bf16 v[42:45], v[144:147], v[182:185], v[42:45]
	v_mfma_f32_16x16x32_bf16 v[32:35], v[154:157], v[182:185], v[32:35]
	v_mfma_f32_16x16x32_bf16 v[24:27], v[144:147], v[190:193], v[24:27]
	v_mfma_f32_16x16x32_bf16 v[16:19], v[154:157], v[190:193], v[16:19]
	v_mfma_f32_16x16x32_bf16 v[66:69], v[150:153], v[170:173], v[66:69]
	v_mfma_f32_16x16x32_bf16 v[62:65], v[162:165], v[170:173], v[62:65]
	v_mfma_f32_16x16x32_bf16 v[58:61], v[150:153], v[178:181], v[58:61]
	v_mfma_f32_16x16x32_bf16 v[50:53], v[162:165], v[178:181], v[50:53]
	v_mfma_f32_16x16x32_bf16 v[42:45], v[150:153], v[186:189], v[42:45]
	v_mfma_f32_16x16x32_bf16 v[32:35], v[162:165], v[186:189], v[32:35]
	v_mfma_f32_16x16x32_bf16 v[24:27], v[150:153], v[194:197], v[24:27]
	v_mfma_f32_16x16x32_bf16 v[16:19], v[162:165], v[194:197], v[16:19]
	s_barrier
	s_add_u32 s56, s18, 0x40000
	s_addc_u32 s57, s19, 0
	s_add_i32 s55, s74, s38
	v_lshl_add_u64 v[144:145], s[56:57], 0, v[2:3]
	s_mov_b32 m0, s55
	s_nop 0
	global_load_lds_dwordx4 v[144:145], off
	v_lshl_add_u64 v[144:145], s[56:57], 0, v[134:135]
	s_add_i32 m0, s55, 0x2000
	s_nop 0
	global_load_lds_dwordx4 v[144:145], off
	s_waitcnt vmcnt(6)
	s_barrier
	v_mfma_f32_16x16x32_bf16 v[54:57], v[198:201], v[166:169], v[54:57]
	v_mfma_f32_16x16x32_bf16 v[46:49], v[206:209], v[166:169], v[46:49]
	v_mfma_f32_16x16x32_bf16 v[38:41], v[198:201], v[174:177], v[38:41]
	v_mfma_f32_16x16x32_bf16 v[28:31], v[206:209], v[174:177], v[28:31]
	v_mfma_f32_16x16x32_bf16 v[20:23], v[198:201], v[182:185], v[20:23]
	v_mfma_f32_16x16x32_bf16 v[12:15], v[206:209], v[182:185], v[12:15]
	v_mfma_f32_16x16x32_bf16 v[8:11], v[198:201], v[190:193], v[8:11]
	v_mfma_f32_16x16x32_bf16 v[4:7], v[206:209], v[190:193], v[4:7]
	v_mfma_f32_16x16x32_bf16 v[54:57], v[202:205], v[170:173], v[54:57]
	v_mfma_f32_16x16x32_bf16 v[46:49], v[210:213], v[170:173], v[46:49]
	v_mfma_f32_16x16x32_bf16 v[38:41], v[202:205], v[178:181], v[38:41]
	v_mfma_f32_16x16x32_bf16 v[28:31], v[210:213], v[178:181], v[28:31]
	v_mfma_f32_16x16x32_bf16 v[20:23], v[202:205], v[186:189], v[20:23]
	v_mfma_f32_16x16x32_bf16 v[12:15], v[210:213], v[186:189], v[12:15]
	v_mfma_f32_16x16x32_bf16 v[8:11], v[202:205], v[194:197], v[8:11]
	v_mfma_f32_16x16x32_bf16 v[4:7], v[210:213], v[194:197], v[4:7]
	s_add_i32 s55, 0, 0x18000
	v_add_u32_e32 v162, s55, v37
	s_barrier
	ds_read_b128 v[144:147], v162
	ds_read_b128 v[150:153], v162 offset:1024
	ds_read_b128 v[154:157], v162 offset:2048
	ds_read_b128 v[162:165], v162 offset:3072
	s_add_u32 s36, s36, 0x40000
	s_addc_u32 s37, s37, 0
	s_mov_b32 m0, s43
	v_lshl_add_u64 v[198:199], s[36:37], 0, v[138:139]
	ds_read_b128 v[166:169], v149 offset:32768
	ds_read_b128 v[170:173], v149 offset:33792
	ds_read_b128 v[174:177], v149 offset:34816
	ds_read_b128 v[178:181], v149 offset:35840
	ds_read_b128 v[182:185], v149 offset:36864
	ds_read_b128 v[186:189], v149 offset:37888
	ds_read_b128 v[190:193], v149 offset:38912
	ds_read_b128 v[194:197], v149 offset:39936
	global_load_lds_dwordx4 v[198:199], off
	v_lshl_add_u64 v[198:199], s[36:37], 0, v[136:137]
	s_mov_b32 m0, s44
	s_nop 0
	global_load_lds_dwordx4 v[198:199], off
	s_waitcnt lgkmcnt(8)
	s_barrier
	s_waitcnt lgkmcnt(0)
	s_waitcnt lgkmcnt(0)
	v_mfma_f32_16x16x32_bf16 v[130:133], v[144:147], v[166:169], v[130:133]
	v_mfma_f32_16x16x32_bf16 v[126:129], v[154:157], v[166:169], v[126:129]
	v_mfma_f32_16x16x32_bf16 v[122:125], v[144:147], v[174:177], v[122:125]
	v_mfma_f32_16x16x32_bf16 v[114:117], v[154:157], v[174:177], v[114:117]
	v_mfma_f32_16x16x32_bf16 v[106:109], v[144:147], v[182:185], v[106:109]
	v_mfma_f32_16x16x32_bf16 v[98:101], v[154:157], v[182:185], v[98:101]
	v_mfma_f32_16x16x32_bf16 v[90:93], v[144:147], v[190:193], v[90:93]
	v_mfma_f32_16x16x32_bf16 v[82:85], v[154:157], v[190:193], v[82:85]
	v_mfma_f32_16x16x32_bf16 v[130:133], v[150:153], v[170:173], v[130:133]
	v_mfma_f32_16x16x32_bf16 v[126:129], v[162:165], v[170:173], v[126:129]
	v_mfma_f32_16x16x32_bf16 v[122:125], v[150:153], v[178:181], v[122:125]
	v_mfma_f32_16x16x32_bf16 v[114:117], v[162:165], v[178:181], v[114:117]
	v_mfma_f32_16x16x32_bf16 v[106:109], v[150:153], v[186:189], v[106:109]
	v_mfma_f32_16x16x32_bf16 v[98:101], v[162:165], v[186:189], v[98:101]
	v_mfma_f32_16x16x32_bf16 v[90:93], v[150:153], v[194:197], v[90:93]
	v_mfma_f32_16x16x32_bf16 v[82:85], v[162:165], v[194:197], v[82:85]
	s_barrier
	s_add_i32 s36, 0, 0x1c000
	s_add_i32 s37, s55, s38
	v_add_u32_e32 v210, s36, v37
	v_lshl_add_u64 v[158:159], v[158:159], 0, s[24:25]
	s_mov_b32 m0, s37
	ds_read_b128 v[198:201], v210
	ds_read_b128 v[202:205], v210 offset:1024
	ds_read_b128 v[206:209], v210 offset:2048
	ds_read_b128 v[210:213], v210 offset:3072
	global_load_lds_dwordx4 v[158:159], off
	v_lshl_add_u64 v[158:159], v[160:161], 0, s[24:25]
	s_add_i32 m0, s37, 0x2000
	s_nop 0
	global_load_lds_dwordx4 v[158:159], off
	s_barrier
	s_waitcnt lgkmcnt(0)
	s_waitcnt lgkmcnt(0)
	v_mfma_f32_16x16x32_bf16 v[118:121], v[198:201], v[166:169], v[118:121]
	v_mfma_f32_16x16x32_bf16 v[110:113], v[206:209], v[166:169], v[110:113]
	v_mfma_f32_16x16x32_bf16 v[102:105], v[198:201], v[174:177], v[102:105]
	v_mfma_f32_16x16x32_bf16 v[94:97], v[206:209], v[174:177], v[94:97]
	v_mfma_f32_16x16x32_bf16 v[86:89], v[198:201], v[182:185], v[86:89]
	v_mfma_f32_16x16x32_bf16 v[78:81], v[206:209], v[182:185], v[78:81]
	v_mfma_f32_16x16x32_bf16 v[74:77], v[198:201], v[190:193], v[74:77]
	v_mfma_f32_16x16x32_bf16 v[70:73], v[206:209], v[190:193], v[70:73]
	v_mfma_f32_16x16x32_bf16 v[118:121], v[202:205], v[170:173], v[118:121]
	v_mfma_f32_16x16x32_bf16 v[110:113], v[210:213], v[170:173], v[110:113]
	v_mfma_f32_16x16x32_bf16 v[102:105], v[202:205], v[178:181], v[102:105]
	v_mfma_f32_16x16x32_bf16 v[94:97], v[210:213], v[178:181], v[94:97]
	v_mfma_f32_16x16x32_bf16 v[86:89], v[202:205], v[186:189], v[86:89]
	v_mfma_f32_16x16x32_bf16 v[78:81], v[210:213], v[186:189], v[78:81]
	v_mfma_f32_16x16x32_bf16 v[74:77], v[202:205], v[194:197], v[74:77]
	v_mfma_f32_16x16x32_bf16 v[70:73], v[210:213], v[194:197], v[70:73]
	s_mov_b32 m0, s45
	v_lshl_add_u64 v[158:159], v[214:215], 0, s[24:25]
	s_barrier
	ds_read_b128 v[166:169], v149 offset:49152
	ds_read_b128 v[170:173], v149 offset:50176
	ds_read_b128 v[174:177], v149 offset:51200
	ds_read_b128 v[178:181], v149 offset:52224
	ds_read_b128 v[182:185], v149 offset:53248
	ds_read_b128 v[186:189], v149 offset:54272
	ds_read_b128 v[190:193], v149 offset:55296
	ds_read_b128 v[194:197], v149 offset:56320
	global_load_lds_dwordx4 v[158:159], off
	v_lshl_add_u64 v[158:159], v[216:217], 0, s[24:25]
	s_mov_b32 m0, s46
	s_nop 0
	global_load_lds_dwordx4 v[158:159], off
	s_barrier
	s_waitcnt lgkmcnt(0)
	s_waitcnt lgkmcnt(0)
	v_mfma_f32_16x16x32_bf16 v[66:69], v[144:147], v[166:169], v[66:69]
	v_mfma_f32_16x16x32_bf16 v[62:65], v[154:157], v[166:169], v[62:65]
	v_mfma_f32_16x16x32_bf16 v[58:61], v[144:147], v[174:177], v[58:61]
	v_mfma_f32_16x16x32_bf16 v[50:53], v[154:157], v[174:177], v[50:53]
	v_mfma_f32_16x16x32_bf16 v[42:45], v[144:147], v[182:185], v[42:45]
	v_mfma_f32_16x16x32_bf16 v[32:35], v[154:157], v[182:185], v[32:35]
	v_mfma_f32_16x16x32_bf16 v[24:27], v[144:147], v[190:193], v[24:27]
	v_mfma_f32_16x16x32_bf16 v[16:19], v[154:157], v[190:193], v[16:19]
	v_mfma_f32_16x16x32_bf16 v[66:69], v[150:153], v[170:173], v[66:69]
	v_mfma_f32_16x16x32_bf16 v[62:65], v[162:165], v[170:173], v[62:65]
	v_mfma_f32_16x16x32_bf16 v[58:61], v[150:153], v[178:181], v[58:61]
	v_mfma_f32_16x16x32_bf16 v[50:53], v[162:165], v[178:181], v[50:53]
	v_mfma_f32_16x16x32_bf16 v[42:45], v[150:153], v[186:189], v[42:45]
	v_mfma_f32_16x16x32_bf16 v[32:35], v[162:165], v[186:189], v[32:35]
	v_mfma_f32_16x16x32_bf16 v[24:27], v[150:153], v[194:197], v[24:27]
	v_mfma_f32_16x16x32_bf16 v[16:19], v[162:165], v[194:197], v[16:19]
	s_barrier
	s_add_u32 s18, s18, 0x40080
	s_addc_u32 s19, s19, 0
	s_add_i32 s36, s36, s38
	v_lshl_add_u64 v[144:145], s[18:19], 0, v[2:3]
	s_mov_b32 m0, s36
	s_nop 0
	global_load_lds_dwordx4 v[144:145], off
	v_lshl_add_u64 v[144:145], s[18:19], 0, v[134:135]
	s_add_i32 m0, s36, 0x2000
	s_nop 0
	global_load_lds_dwordx4 v[144:145], off
	s_waitcnt vmcnt(6)
	s_barrier
	v_mfma_f32_16x16x32_bf16 v[54:57], v[198:201], v[166:169], v[54:57]
	v_mfma_f32_16x16x32_bf16 v[46:49], v[206:209], v[166:169], v[46:49]
	v_mfma_f32_16x16x32_bf16 v[38:41], v[198:201], v[174:177], v[38:41]
	v_mfma_f32_16x16x32_bf16 v[28:31], v[206:209], v[174:177], v[28:31]
	v_mfma_f32_16x16x32_bf16 v[20:23], v[198:201], v[182:185], v[20:23]
	v_mfma_f32_16x16x32_bf16 v[12:15], v[206:209], v[182:185], v[12:15]
	v_mfma_f32_16x16x32_bf16 v[8:11], v[198:201], v[190:193], v[8:11]
	v_mfma_f32_16x16x32_bf16 v[4:7], v[206:209], v[190:193], v[4:7]
	v_mfma_f32_16x16x32_bf16 v[54:57], v[202:205], v[170:173], v[54:57]
	v_mfma_f32_16x16x32_bf16 v[46:49], v[210:213], v[170:173], v[46:49]
	v_mfma_f32_16x16x32_bf16 v[38:41], v[202:205], v[178:181], v[38:41]
	v_mfma_f32_16x16x32_bf16 v[28:31], v[210:213], v[178:181], v[28:31]
	v_mfma_f32_16x16x32_bf16 v[20:23], v[202:205], v[186:189], v[20:23]
	v_mfma_f32_16x16x32_bf16 v[12:15], v[210:213], v[186:189], v[12:15]
	v_mfma_f32_16x16x32_bf16 v[8:11], v[202:205], v[194:197], v[8:11]
	v_mfma_f32_16x16x32_bf16 v[4:7], v[210:213], v[194:197], v[4:7]
	s_add_i32 s54, s54, 2
	s_add_u32 s16, s16, 0x100
	s_addc_u32 s17, s17, 0
	s_add_u32 s52, s52, 0x100
	s_addc_u32 s53, s53, 0
	s_cmp_gt_u32 s54, 5
	s_barrier
	s_cbranch_scc0 .LBB0_799
	v_readlane_b32 s16, v254, 20
	s_cmp_eq_u32 s49, 0
	v_readlane_b32 s17, v254, 21
	v_lshl_or_b32 v146, s50, 8, v148
	s_cselect_b32 s17, s35, s17
	s_cselect_b32 s16, s34, s16
	v_lshl_add_u32 v152, s10, 8, v1
	v_ashrrev_i32_e32 v147, 31, v146
	v_mov_b64_e32 v[144:145], s[16:17]
	s_movk_i32 s1, 0x600
	v_mad_i64_i32 v[150:151], s[16:17], v152, s1, v[144:145]
	v_lshlrev_b64 v[146:147], 1, v[146:147]
	v_lshl_add_u64 v[150:151], v[150:151], 0, v[146:147]
	v_cvt_pk_bf16_f32 v130, v130, v131
	v_cvt_pk_bf16_f32 v131, v132, v133
	v_cvt_pk_bf16_f32 v132, v126, v127
	v_cvt_pk_bf16_f32 v133, v128, v129
	global_store_dwordx4 v[150:151], v[130:133], off
	v_cvt_pk_bf16_f32 v118, v118, v119
	v_cvt_pk_bf16_f32 v119, v120, v121
	v_cvt_pk_bf16_f32 v120, v110, v111
	v_or_b32_e32 v110, 16, v152
	v_mad_i64_i32 v[110:111], s[16:17], v110, s1, v[144:145]
	v_cvt_pk_bf16_f32 v121, v112, v113
	global_store_dwordx4 v[150:151], v[118:121], off offset:256
	s_and_b64 vcc, exec, s[4:5]
	s_mov_b32 s49, s6
	v_lshl_add_u64 v[118:119], v[110:111], 0, v[146:147]
	v_cvt_pk_bf16_f32 v110, v122, v123
	v_cvt_pk_bf16_f32 v111, v124, v125
	v_cvt_pk_bf16_f32 v112, v114, v115
	v_cvt_pk_bf16_f32 v113, v116, v117
	global_store_dwordx4 v[118:119], v[110:113], off
	v_cvt_pk_bf16_f32 v102, v102, v103
	v_cvt_pk_bf16_f32 v103, v104, v105
	v_cvt_pk_bf16_f32 v104, v94, v95
	v_or_b32_e32 v94, 32, v152
	v_mad_i64_i32 v[94:95], s[16:17], v94, s1, v[144:145]
	v_cvt_pk_bf16_f32 v105, v96, v97
	global_store_dwordx4 v[118:119], v[102:105], off offset:256
	s_mov_b32 s50, s0
	s_mov_b32 s10, s8
	v_lshl_add_u64 v[102:103], v[94:95], 0, v[146:147]
	v_cvt_pk_bf16_f32 v94, v106, v107
	v_cvt_pk_bf16_f32 v95, v108, v109
	v_cvt_pk_bf16_f32 v96, v98, v99
	v_cvt_pk_bf16_f32 v97, v100, v101
	global_store_dwordx4 v[102:103], v[94:97], off
	v_cvt_pk_bf16_f32 v86, v86, v87
	v_cvt_pk_bf16_f32 v87, v88, v89
	v_cvt_pk_bf16_f32 v88, v78, v79
	v_or_b32_e32 v78, 48, v152
	v_mad_i64_i32 v[78:79], s[16:17], v78, s1, v[144:145]
	v_cvt_pk_bf16_f32 v89, v80, v81
	global_store_dwordx4 v[102:103], v[86:89], off offset:256
	s_mov_b64 s[18:19], s[14:15]
	s_nop 0
	v_lshl_add_u64 v[86:87], v[78:79], 0, v[146:147]
	v_cvt_pk_bf16_f32 v78, v90, v91
	v_cvt_pk_bf16_f32 v79, v92, v93
	v_cvt_pk_bf16_f32 v80, v82, v83
	v_cvt_pk_bf16_f32 v81, v84, v85
	global_store_dwordx4 v[86:87], v[78:81], off
	v_cvt_pk_bf16_f32 v74, v74, v75
	v_cvt_pk_bf16_f32 v75, v76, v77
	v_cvt_pk_bf16_f32 v76, v70, v71
	v_add_u32_e32 v70, 0x80, v152
	v_mad_i64_i32 v[70:71], s[16:17], v70, s1, v[144:145]
	v_lshl_add_u64 v[70:71], v[70:71], 0, v[146:147]
	v_cvt_pk_bf16_f32 v77, v72, v73
	global_store_dwordx4 v[86:87], v[74:77], off offset:256
	v_cvt_pk_bf16_f32 v66, v66, v67
	v_cvt_pk_bf16_f32 v67, v68, v69
	v_cvt_pk_bf16_f32 v68, v62, v63
	v_cvt_pk_bf16_f32 v69, v64, v65
	global_store_dwordx4 v[70:71], v[66:69], off
	v_cvt_pk_bf16_f32 v54, v54, v55
	v_cvt_pk_bf16_f32 v55, v56, v57
	v_cvt_pk_bf16_f32 v56, v46, v47
	v_add_u32_e32 v46, 0x90, v152
	v_mad_i64_i32 v[46:47], s[16:17], v46, s1, v[144:145]
	v_cvt_pk_bf16_f32 v57, v48, v49
	global_store_dwordx4 v[70:71], v[54:57], off offset:256
	s_nop 1
	v_lshl_add_u64 v[54:55], v[46:47], 0, v[146:147]
	v_cvt_pk_bf16_f32 v46, v58, v59
	v_cvt_pk_bf16_f32 v47, v60, v61
	v_cvt_pk_bf16_f32 v48, v50, v51
	v_cvt_pk_bf16_f32 v49, v52, v53
	global_store_dwordx4 v[54:55], v[46:49], off
	v_cvt_pk_bf16_f32 v38, v38, v39
	v_cvt_pk_bf16_f32 v39, v40, v41
	v_cvt_pk_bf16_f32 v40, v28, v29
	v_add_u32_e32 v28, 0xa0, v152
	v_mad_i64_i32 v[28:29], s[16:17], v28, s1, v[144:145]
	v_cvt_pk_bf16_f32 v41, v30, v31
	global_store_dwordx4 v[54:55], v[38:41], off offset:256
	s_nop 1
	v_lshl_add_u64 v[38:39], v[28:29], 0, v[146:147]
	v_cvt_pk_bf16_f32 v28, v42, v43
	v_cvt_pk_bf16_f32 v29, v44, v45
	v_cvt_pk_bf16_f32 v30, v32, v33
	v_cvt_pk_bf16_f32 v31, v34, v35
	global_store_dwordx4 v[38:39], v[28:31], off
	v_cvt_pk_bf16_f32 v20, v20, v21
	v_cvt_pk_bf16_f32 v21, v22, v23
	v_cvt_pk_bf16_f32 v22, v12, v13
	v_add_u32_e32 v12, 0xb0, v152
	v_mad_i64_i32 v[12:13], s[16:17], v12, s1, v[144:145]
	v_cvt_pk_bf16_f32 v23, v14, v15
	global_store_dwordx4 v[38:39], v[20:23], off offset:256
	s_mov_b64 s[16:17], s[12:13]
	s_nop 0
	v_lshl_add_u64 v[20:21], v[12:13], 0, v[146:147]
	v_cvt_pk_bf16_f32 v12, v24, v25
	v_cvt_pk_bf16_f32 v13, v26, v27
	v_cvt_pk_bf16_f32 v14, v16, v17
	v_cvt_pk_bf16_f32 v15, v18, v19
	global_store_dwordx4 v[20:21], v[12:15], off
	v_cvt_pk_bf16_f32 v8, v8, v9
	v_cvt_pk_bf16_f32 v9, v10, v11
	v_cvt_pk_bf16_f32 v10, v4, v5
	v_cvt_pk_bf16_f32 v11, v6, v7
	global_store_dwordx4 v[20:21], v[8:11], off offset:256
	s_cbranch_vccz .LBB0_796
	s_waitcnt vmcnt(0)
	s_cmpk_gt_u32 s27, 0xff
	s_cbranch_scc1 .LBB0_803
	s_barrier

.LBB0_813:
	s_add_u32 s16, s14, 0xfffc0080
	s_addc_u32 s17, s15, -1
	s_add_i32 s53, 0, 0x10000
	v_add_u32_e32 v158, s53, v37
	ds_read_b128 v[144:147], v158
	ds_read_b128 v[150:153], v158 offset:1024
	ds_read_b128 v[154:157], v158 offset:2048
	ds_read_b128 v[162:165], v158 offset:3072
	s_cmp_eq_u32 s52, 12
	s_cselect_b32 s19, s7, s17
	s_cselect_b32 s18, s48, s16
	s_cselect_b32 s17, s1, s51
	s_cselect_b32 s16, s49, s50
	v_lshl_add_u64 v[158:159], s[14:15], 0, v[140:141]
	s_add_i32 m0, s9, 0xc000
	ds_read_b128 v[166:169], v149
	ds_read_b128 v[170:173], v149 offset:1024
	ds_read_b128 v[174:177], v149 offset:2048
	ds_read_b128 v[178:181], v149 offset:3072
	ds_read_b128 v[182:185], v149 offset:4096
	ds_read_b128 v[186:189], v149 offset:5120
	ds_read_b128 v[190:193], v149 offset:6144
	ds_read_b128 v[194:197], v149 offset:7168
	global_load_lds_dwordx4 v[158:159], off
	v_lshl_add_u64 v[158:159], s[14:15], 0, v[142:143]
	s_add_i32 m0, s9, 0xe000
	s_nop 0
	global_load_lds_dwordx4 v[158:159], off
	s_waitcnt lgkmcnt(8)
	s_barrier
	s_waitcnt lgkmcnt(0)
	s_waitcnt lgkmcnt(0)
	v_mfma_f32_16x16x32_bf16 v[130:133], v[144:147], v[166:169], v[130:133]
	v_mfma_f32_16x16x32_bf16 v[126:129], v[154:157], v[166:169], v[126:129]
	v_mfma_f32_16x16x32_bf16 v[122:125], v[144:147], v[174:177], v[122:125]
	v_mfma_f32_16x16x32_bf16 v[114:117], v[154:157], v[174:177], v[114:117]
	v_mfma_f32_16x16x32_bf16 v[106:109], v[144:147], v[182:185], v[106:109]
	v_mfma_f32_16x16x32_bf16 v[98:101], v[154:157], v[182:185], v[98:101]
	v_mfma_f32_16x16x32_bf16 v[90:93], v[144:147], v[190:193], v[90:93]
	v_mfma_f32_16x16x32_bf16 v[82:85], v[154:157], v[190:193], v[82:85]
	v_mfma_f32_16x16x32_bf16 v[130:133], v[150:153], v[170:173], v[130:133]
	v_mfma_f32_16x16x32_bf16 v[126:129], v[162:165], v[170:173], v[126:129]
	v_mfma_f32_16x16x32_bf16 v[122:125], v[150:153], v[178:181], v[122:125]
	v_mfma_f32_16x16x32_bf16 v[114:117], v[162:165], v[178:181], v[114:117]
	v_mfma_f32_16x16x32_bf16 v[106:109], v[150:153], v[186:189], v[106:109]
	v_mfma_f32_16x16x32_bf16 v[98:101], v[162:165], v[186:189], v[98:101]
	v_mfma_f32_16x16x32_bf16 v[90:93], v[150:153], v[194:197], v[90:93]
	v_mfma_f32_16x16x32_bf16 v[82:85], v[162:165], v[194:197], v[82:85]
	s_barrier
	s_add_i32 s56, 0, 0x14000
	v_add_u32_e32 v158, s56, v37
	s_add_i32 s53, s53, s36
	ds_read_b128 v[198:201], v158
	ds_read_b128 v[202:205], v158 offset:1024
	ds_read_b128 v[206:209], v158 offset:2048
	ds_read_b128 v[210:213], v158 offset:3072
	v_lshl_add_u64 v[158:159], s[16:17], 0, v[2:3]
	s_mov_b32 m0, s53
	v_lshl_add_u64 v[160:161], s[16:17], 0, v[134:135]
	global_load_lds_dwordx4 v[158:159], off
	s_add_i32 m0, s53, 0x2000
	s_nop 0
	global_load_lds_dwordx4 v[160:161], off
	s_barrier
	s_waitcnt lgkmcnt(0)
	s_waitcnt lgkmcnt(0)
	v_mfma_f32_16x16x32_bf16 v[118:121], v[198:201], v[166:169], v[118:121]
	v_mfma_f32_16x16x32_bf16 v[110:113], v[206:209], v[166:169], v[110:113]
	v_mfma_f32_16x16x32_bf16 v[102:105], v[198:201], v[174:177], v[102:105]
	v_mfma_f32_16x16x32_bf16 v[94:97], v[206:209], v[174:177], v[94:97]
	v_mfma_f32_16x16x32_bf16 v[86:89], v[198:201], v[182:185], v[86:89]
	v_mfma_f32_16x16x32_bf16 v[78:81], v[206:209], v[182:185], v[78:81]
	v_mfma_f32_16x16x32_bf16 v[74:77], v[198:201], v[190:193], v[74:77]
	v_mfma_f32_16x16x32_bf16 v[70:73], v[206:209], v[190:193], v[70:73]
	v_mfma_f32_16x16x32_bf16 v[118:121], v[202:205], v[170:173], v[118:121]
	v_mfma_f32_16x16x32_bf16 v[110:113], v[210:213], v[170:173], v[110:113]
	v_mfma_f32_16x16x32_bf16 v[102:105], v[202:205], v[178:181], v[102:105]
	v_mfma_f32_16x16x32_bf16 v[94:97], v[210:213], v[178:181], v[94:97]
	v_mfma_f32_16x16x32_bf16 v[86:89], v[202:205], v[186:189], v[86:89]
	v_mfma_f32_16x16x32_bf16 v[78:81], v[210:213], v[186:189], v[78:81]
	v_mfma_f32_16x16x32_bf16 v[74:77], v[202:205], v[194:197], v[74:77]
	v_mfma_f32_16x16x32_bf16 v[70:73], v[210:213], v[194:197], v[70:73]
	s_mov_b32 m0, s9
	v_lshl_add_u64 v[214:215], s[18:19], 0, v[138:139]
	s_barrier
	ds_read_b128 v[166:169], v149 offset:16384
	ds_read_b128 v[170:173], v149 offset:17408
	ds_read_b128 v[174:177], v149 offset:18432
	ds_read_b128 v[178:181], v149 offset:19456
	ds_read_b128 v[182:185], v149 offset:20480
	ds_read_b128 v[186:189], v149 offset:21504
	ds_read_b128 v[190:193], v149 offset:22528
	ds_read_b128 v[194:197], v149 offset:23552
	global_load_lds_dwordx4 v[214:215], off
	v_lshl_add_u64 v[216:217], s[18:19], 0, v[136:137]
	s_mov_b32 m0, s40
	s_nop 0
	global_load_lds_dwordx4 v[216:217], off
	s_barrier
	s_waitcnt lgkmcnt(0)
	s_waitcnt lgkmcnt(0)
	v_mfma_f32_16x16x32_bf16 v[66:69], v[144:147], v[166:169], v[66:69]
	v_mfma_f32_16x16x32_bf16 v[62:65], v[154:157], v[166:169], v[62:65]
	v_mfma_f32_16x16x32_bf16 v[58:61], v[144:147], v[174:177], v[58:61]
	v_mfma_f32_16x16x32_bf16 v[50:53], v[154:157], v[174:177], v[50:53]
	v_mfma_f32_16x16x32_bf16 v[42:45], v[144:147], v[182:185], v[42:45]
	v_mfma_f32_16x16x32_bf16 v[32:35], v[154:157], v[182:185], v[32:35]
	v_mfma_f32_16x16x32_bf16 v[24:27], v[144:147], v[190:193], v[24:27]
	v_mfma_f32_16x16x32_bf16 v[16:19], v[154:157], v[190:193], v[16:19]
	v_mfma_f32_16x16x32_bf16 v[66:69], v[150:153], v[170:173], v[66:69]
	v_mfma_f32_16x16x32_bf16 v[62:65], v[162:165], v[170:173], v[62:65]
	v_mfma_f32_16x16x32_bf16 v[58:61], v[150:153], v[178:181], v[58:61]
	v_mfma_f32_16x16x32_bf16 v[50:53], v[162:165], v[178:181], v[50:53]
	v_mfma_f32_16x16x32_bf16 v[42:45], v[150:153], v[186:189], v[42:45]
	v_mfma_f32_16x16x32_bf16 v[32:35], v[162:165], v[186:189], v[32:35]
	v_mfma_f32_16x16x32_bf16 v[24:27], v[150:153], v[194:197], v[24:27]
	v_mfma_f32_16x16x32_bf16 v[16:19], v[162:165], v[194:197], v[16:19]
	s_barrier
	s_add_u32 s54, s16, 0x40000
	s_addc_u32 s55, s17, 0
	s_add_i32 s53, s56, s36
	v_lshl_add_u64 v[144:145], s[54:55], 0, v[2:3]
	s_mov_b32 m0, s53
	s_nop 0
	global_load_lds_dwordx4 v[144:145], off
	v_lshl_add_u64 v[144:145], s[54:55], 0, v[134:135]
	s_add_i32 m0, s53, 0x2000
	s_nop 0
	global_load_lds_dwordx4 v[144:145], off
	s_waitcnt vmcnt(6)
	s_barrier
	v_mfma_f32_16x16x32_bf16 v[54:57], v[198:201], v[166:169], v[54:57]
	v_mfma_f32_16x16x32_bf16 v[46:49], v[206:209], v[166:169], v[46:49]
	v_mfma_f32_16x16x32_bf16 v[38:41], v[198:201], v[174:177], v[38:41]
	v_mfma_f32_16x16x32_bf16 v[28:31], v[206:209], v[174:177], v[28:31]
	v_mfma_f32_16x16x32_bf16 v[20:23], v[198:201], v[182:185], v[20:23]
	v_mfma_f32_16x16x32_bf16 v[12:15], v[206:209], v[182:185], v[12:15]
	v_mfma_f32_16x16x32_bf16 v[8:11], v[198:201], v[190:193], v[8:11]
	v_mfma_f32_16x16x32_bf16 v[4:7], v[206:209], v[190:193], v[4:7]
	v_mfma_f32_16x16x32_bf16 v[54:57], v[202:205], v[170:173], v[54:57]
	v_mfma_f32_16x16x32_bf16 v[46:49], v[210:213], v[170:173], v[46:49]
	v_mfma_f32_16x16x32_bf16 v[38:41], v[202:205], v[178:181], v[38:41]
	v_mfma_f32_16x16x32_bf16 v[28:31], v[210:213], v[178:181], v[28:31]
	v_mfma_f32_16x16x32_bf16 v[20:23], v[202:205], v[186:189], v[20:23]
	v_mfma_f32_16x16x32_bf16 v[12:15], v[210:213], v[186:189], v[12:15]
	v_mfma_f32_16x16x32_bf16 v[8:11], v[202:205], v[194:197], v[8:11]
	v_mfma_f32_16x16x32_bf16 v[4:7], v[210:213], v[194:197], v[4:7]
	s_add_i32 s53, 0, 0x18000
	v_add_u32_e32 v162, s53, v37
	s_barrier
	ds_read_b128 v[144:147], v162
	ds_read_b128 v[150:153], v162 offset:1024
	ds_read_b128 v[154:157], v162 offset:2048
	ds_read_b128 v[162:165], v162 offset:3072
	s_add_u32 s18, s18, 0x40000
	s_addc_u32 s19, s19, 0
	s_mov_b32 m0, s41
	v_lshl_add_u64 v[198:199], s[18:19], 0, v[138:139]
	ds_read_b128 v[166:169], v149 offset:32768
	ds_read_b128 v[170:173], v149 offset:33792
	ds_read_b128 v[174:177], v149 offset:34816
	ds_read_b128 v[178:181], v149 offset:35840
	ds_read_b128 v[182:185], v149 offset:36864
	ds_read_b128 v[186:189], v149 offset:37888
	ds_read_b128 v[190:193], v149 offset:38912
	ds_read_b128 v[194:197], v149 offset:39936
	global_load_lds_dwordx4 v[198:199], off
	v_lshl_add_u64 v[198:199], s[18:19], 0, v[136:137]
	s_mov_b32 m0, s42
	s_nop 0
	global_load_lds_dwordx4 v[198:199], off
	s_waitcnt lgkmcnt(8)
	s_barrier
	s_waitcnt lgkmcnt(0)
	s_waitcnt lgkmcnt(0)
	v_mfma_f32_16x16x32_bf16 v[130:133], v[144:147], v[166:169], v[130:133]
	v_mfma_f32_16x16x32_bf16 v[126:129], v[154:157], v[166:169], v[126:129]
	v_mfma_f32_16x16x32_bf16 v[122:125], v[144:147], v[174:177], v[122:125]
	v_mfma_f32_16x16x32_bf16 v[114:117], v[154:157], v[174:177], v[114:117]
	v_mfma_f32_16x16x32_bf16 v[106:109], v[144:147], v[182:185], v[106:109]
	v_mfma_f32_16x16x32_bf16 v[98:101], v[154:157], v[182:185], v[98:101]
	v_mfma_f32_16x16x32_bf16 v[90:93], v[144:147], v[190:193], v[90:93]
	v_mfma_f32_16x16x32_bf16 v[82:85], v[154:157], v[190:193], v[82:85]
	v_mfma_f32_16x16x32_bf16 v[130:133], v[150:153], v[170:173], v[130:133]
	v_mfma_f32_16x16x32_bf16 v[126:129], v[162:165], v[170:173], v[126:129]
	v_mfma_f32_16x16x32_bf16 v[122:125], v[150:153], v[178:181], v[122:125]
	v_mfma_f32_16x16x32_bf16 v[114:117], v[162:165], v[178:181], v[114:117]
	v_mfma_f32_16x16x32_bf16 v[106:109], v[150:153], v[186:189], v[106:109]
	v_mfma_f32_16x16x32_bf16 v[98:101], v[162:165], v[186:189], v[98:101]
	v_mfma_f32_16x16x32_bf16 v[90:93], v[150:153], v[194:197], v[90:93]
	v_mfma_f32_16x16x32_bf16 v[82:85], v[162:165], v[194:197], v[82:85]
	s_barrier
	s_add_i32 s18, 0, 0x1c000
	s_add_i32 s19, s53, s36
	v_add_u32_e32 v210, s18, v37
	v_lshl_add_u64 v[158:159], v[158:159], 0, s[24:25]
	s_mov_b32 m0, s19
	ds_read_b128 v[198:201], v210
	ds_read_b128 v[202:205], v210 offset:1024
	ds_read_b128 v[206:209], v210 offset:2048
	ds_read_b128 v[210:213], v210 offset:3072
	global_load_lds_dwordx4 v[158:159], off
	v_lshl_add_u64 v[158:159], v[160:161], 0, s[24:25]
	s_add_i32 m0, s19, 0x2000
	s_nop 0
	global_load_lds_dwordx4 v[158:159], off
	s_barrier
	s_waitcnt lgkmcnt(0)
	s_waitcnt lgkmcnt(0)
	v_mfma_f32_16x16x32_bf16 v[118:121], v[198:201], v[166:169], v[118:121]
	v_mfma_f32_16x16x32_bf16 v[110:113], v[206:209], v[166:169], v[110:113]
	v_mfma_f32_16x16x32_bf16 v[102:105], v[198:201], v[174:177], v[102:105]
	v_mfma_f32_16x16x32_bf16 v[94:97], v[206:209], v[174:177], v[94:97]
	v_mfma_f32_16x16x32_bf16 v[86:89], v[198:201], v[182:185], v[86:89]
	v_mfma_f32_16x16x32_bf16 v[78:81], v[206:209], v[182:185], v[78:81]
	v_mfma_f32_16x16x32_bf16 v[74:77], v[198:201], v[190:193], v[74:77]
	v_mfma_f32_16x16x32_bf16 v[70:73], v[206:209], v[190:193], v[70:73]
	v_mfma_f32_16x16x32_bf16 v[118:121], v[202:205], v[170:173], v[118:121]
	v_mfma_f32_16x16x32_bf16 v[110:113], v[210:213], v[170:173], v[110:113]
	v_mfma_f32_16x16x32_bf16 v[102:105], v[202:205], v[178:181], v[102:105]
	v_mfma_f32_16x16x32_bf16 v[94:97], v[210:213], v[178:181], v[94:97]
	v_mfma_f32_16x16x32_bf16 v[86:89], v[202:205], v[186:189], v[86:89]
	v_mfma_f32_16x16x32_bf16 v[78:81], v[210:213], v[186:189], v[78:81]
	v_mfma_f32_16x16x32_bf16 v[74:77], v[202:205], v[194:197], v[74:77]
	v_mfma_f32_16x16x32_bf16 v[70:73], v[210:213], v[194:197], v[70:73]
	s_mov_b32 m0, s43
	v_lshl_add_u64 v[158:159], v[214:215], 0, s[24:25]
	s_barrier
	ds_read_b128 v[166:169], v149 offset:49152
	ds_read_b128 v[170:173], v149 offset:50176
	ds_read_b128 v[174:177], v149 offset:51200
	ds_read_b128 v[178:181], v149 offset:52224
	ds_read_b128 v[182:185], v149 offset:53248
	ds_read_b128 v[186:189], v149 offset:54272
	ds_read_b128 v[190:193], v149 offset:55296
	ds_read_b128 v[194:197], v149 offset:56320
	global_load_lds_dwordx4 v[158:159], off
	v_lshl_add_u64 v[158:159], v[216:217], 0, s[24:25]
	s_mov_b32 m0, s44
	s_nop 0
	global_load_lds_dwordx4 v[158:159], off
	s_barrier
	s_waitcnt lgkmcnt(0)
	s_waitcnt lgkmcnt(0)
	v_mfma_f32_16x16x32_bf16 v[66:69], v[144:147], v[166:169], v[66:69]
	v_mfma_f32_16x16x32_bf16 v[62:65], v[154:157], v[166:169], v[62:65]
	v_mfma_f32_16x16x32_bf16 v[58:61], v[144:147], v[174:177], v[58:61]
	v_mfma_f32_16x16x32_bf16 v[50:53], v[154:157], v[174:177], v[50:53]
	v_mfma_f32_16x16x32_bf16 v[42:45], v[144:147], v[182:185], v[42:45]
	v_mfma_f32_16x16x32_bf16 v[32:35], v[154:157], v[182:185], v[32:35]
	v_mfma_f32_16x16x32_bf16 v[24:27], v[144:147], v[190:193], v[24:27]
	v_mfma_f32_16x16x32_bf16 v[16:19], v[154:157], v[190:193], v[16:19]
	v_mfma_f32_16x16x32_bf16 v[66:69], v[150:153], v[170:173], v[66:69]
	v_mfma_f32_16x16x32_bf16 v[62:65], v[162:165], v[170:173], v[62:65]
	v_mfma_f32_16x16x32_bf16 v[58:61], v[150:153], v[178:181], v[58:61]
	v_mfma_f32_16x16x32_bf16 v[50:53], v[162:165], v[178:181], v[50:53]
	v_mfma_f32_16x16x32_bf16 v[42:45], v[150:153], v[186:189], v[42:45]
	v_mfma_f32_16x16x32_bf16 v[32:35], v[162:165], v[186:189], v[32:35]
	v_mfma_f32_16x16x32_bf16 v[24:27], v[150:153], v[194:197], v[24:27]
	v_mfma_f32_16x16x32_bf16 v[16:19], v[162:165], v[194:197], v[16:19]
	s_barrier
	s_add_u32 s16, s16, 0x40080
	s_addc_u32 s17, s17, 0
	s_add_i32 s18, s18, s36
	v_lshl_add_u64 v[144:145], s[16:17], 0, v[2:3]
	s_mov_b32 m0, s18
	s_nop 0
	global_load_lds_dwordx4 v[144:145], off
	v_lshl_add_u64 v[144:145], s[16:17], 0, v[134:135]
	s_add_i32 m0, s18, 0x2000
	s_nop 0
	global_load_lds_dwordx4 v[144:145], off
	s_waitcnt vmcnt(6)
	s_barrier
	v_mfma_f32_16x16x32_bf16 v[54:57], v[198:201], v[166:169], v[54:57]
	v_mfma_f32_16x16x32_bf16 v[46:49], v[206:209], v[166:169], v[46:49]
	v_mfma_f32_16x16x32_bf16 v[38:41], v[198:201], v[174:177], v[38:41]
	v_mfma_f32_16x16x32_bf16 v[28:31], v[206:209], v[174:177], v[28:31]
	v_mfma_f32_16x16x32_bf16 v[20:23], v[198:201], v[182:185], v[20:23]
	v_mfma_f32_16x16x32_bf16 v[12:15], v[206:209], v[182:185], v[12:15]
	v_mfma_f32_16x16x32_bf16 v[8:11], v[198:201], v[190:193], v[8:11]
	v_mfma_f32_16x16x32_bf16 v[4:7], v[206:209], v[190:193], v[4:7]
	v_mfma_f32_16x16x32_bf16 v[54:57], v[202:205], v[170:173], v[54:57]
	v_mfma_f32_16x16x32_bf16 v[46:49], v[210:213], v[170:173], v[46:49]
	v_mfma_f32_16x16x32_bf16 v[38:41], v[202:205], v[178:181], v[38:41]
	v_mfma_f32_16x16x32_bf16 v[28:31], v[210:213], v[178:181], v[28:31]
	v_mfma_f32_16x16x32_bf16 v[20:23], v[202:205], v[186:189], v[20:23]
	v_mfma_f32_16x16x32_bf16 v[12:15], v[210:213], v[186:189], v[12:15]
	v_mfma_f32_16x16x32_bf16 v[8:11], v[202:205], v[194:197], v[8:11]
	v_mfma_f32_16x16x32_bf16 v[4:7], v[210:213], v[194:197], v[4:7]
	s_add_i32 s52, s52, 2
	s_add_u32 s14, s14, 0x100
	s_addc_u32 s15, s15, 0
	s_add_u32 s50, s50, 0x100
	s_addc_u32 s51, s51, 0
	s_cmp_gt_u32 s52, 13
	s_barrier
	s_cbranch_scc0 .LBB0_813
	v_lshl_or_b32 v146, s47, 8, v148
	v_lshl_add_u32 v152, s8, 8, v1
	v_ashrrev_i32_e32 v147, 31, v146
	v_mov_b64_e32 v[144:145], s[34:35]
	v_mad_i64_i32 v[150:151], s[14:15], v152, s67, v[144:145]
	v_lshlrev_b64 v[146:147], 1, v[146:147]
	v_lshl_add_u64 v[150:151], v[150:151], 0, v[146:147]
	v_cvt_pk_bf16_f32 v130, v130, v131
	v_cvt_pk_bf16_f32 v131, v132, v133
	v_cvt_pk_bf16_f32 v132, v126, v127
	v_cvt_pk_bf16_f32 v133, v128, v129
	global_store_dwordx4 v[150:151], v[130:133], off
	v_cvt_pk_bf16_f32 v118, v118, v119
	v_cvt_pk_bf16_f32 v119, v120, v121
	v_cvt_pk_bf16_f32 v120, v110, v111
	v_or_b32_e32 v110, 16, v152
	v_mad_i64_i32 v[110:111], s[14:15], v110, s67, v[144:145]
	v_cvt_pk_bf16_f32 v121, v112, v113
	global_store_dwordx4 v[150:151], v[118:121], off offset:256
	s_and_b64 vcc, exec, s[4:5]
	s_mov_b32 s47, s0
	v_lshl_add_u64 v[118:119], v[110:111], 0, v[146:147]
	v_cvt_pk_bf16_f32 v110, v122, v123
	v_cvt_pk_bf16_f32 v111, v124, v125
	v_cvt_pk_bf16_f32 v112, v114, v115
	v_cvt_pk_bf16_f32 v113, v116, v117
	global_store_dwordx4 v[118:119], v[110:113], off
	v_cvt_pk_bf16_f32 v102, v102, v103
	v_cvt_pk_bf16_f32 v103, v104, v105
	v_cvt_pk_bf16_f32 v104, v94, v95
	v_or_b32_e32 v94, 32, v152
	v_mad_i64_i32 v[94:95], s[14:15], v94, s67, v[144:145]
	v_cvt_pk_bf16_f32 v105, v96, v97
	global_store_dwordx4 v[118:119], v[102:105], off offset:256
	s_mov_b32 s8, s6
	s_mov_b64 s[16:17], s[12:13]
	v_lshl_add_u64 v[102:103], v[94:95], 0, v[146:147]
	v_cvt_pk_bf16_f32 v94, v106, v107
	v_cvt_pk_bf16_f32 v95, v108, v109
	v_cvt_pk_bf16_f32 v96, v98, v99
	v_cvt_pk_bf16_f32 v97, v100, v101
	global_store_dwordx4 v[102:103], v[94:97], off
	v_cvt_pk_bf16_f32 v86, v86, v87
	v_cvt_pk_bf16_f32 v87, v88, v89
	v_cvt_pk_bf16_f32 v88, v78, v79
	v_or_b32_e32 v78, 48, v152
	v_mad_i64_i32 v[78:79], s[14:15], v78, s67, v[144:145]
	v_cvt_pk_bf16_f32 v89, v80, v81
	global_store_dwordx4 v[102:103], v[86:89], off offset:256
	s_nop 1
	v_lshl_add_u64 v[86:87], v[78:79], 0, v[146:147]
	v_cvt_pk_bf16_f32 v78, v90, v91
	v_cvt_pk_bf16_f32 v79, v92, v93
	v_cvt_pk_bf16_f32 v80, v82, v83
	v_cvt_pk_bf16_f32 v81, v84, v85
	global_store_dwordx4 v[86:87], v[78:81], off
	v_cvt_pk_bf16_f32 v74, v74, v75
	v_cvt_pk_bf16_f32 v75, v76, v77
	v_cvt_pk_bf16_f32 v76, v70, v71
	v_add_u32_e32 v70, 0x80, v152
	v_mad_i64_i32 v[70:71], s[14:15], v70, s67, v[144:145]
	v_lshl_add_u64 v[70:71], v[70:71], 0, v[146:147]
	v_cvt_pk_bf16_f32 v77, v72, v73
	global_store_dwordx4 v[86:87], v[74:77], off offset:256
	v_cvt_pk_bf16_f32 v66, v66, v67
	v_cvt_pk_bf16_f32 v67, v68, v69
	v_cvt_pk_bf16_f32 v68, v62, v63
	v_cvt_pk_bf16_f32 v69, v64, v65
	global_store_dwordx4 v[70:71], v[66:69], off
	v_cvt_pk_bf16_f32 v54, v54, v55
	v_cvt_pk_bf16_f32 v55, v56, v57
	v_cvt_pk_bf16_f32 v56, v46, v47
	v_add_u32_e32 v46, 0x90, v152
	v_mad_i64_i32 v[46:47], s[14:15], v46, s67, v[144:145]
	v_cvt_pk_bf16_f32 v57, v48, v49
	global_store_dwordx4 v[70:71], v[54:57], off offset:256
	s_nop 1
	v_lshl_add_u64 v[54:55], v[46:47], 0, v[146:147]
	v_cvt_pk_bf16_f32 v46, v58, v59
	v_cvt_pk_bf16_f32 v47, v60, v61
	v_cvt_pk_bf16_f32 v48, v50, v51
	v_cvt_pk_bf16_f32 v49, v52, v53
	global_store_dwordx4 v[54:55], v[46:49], off
	v_cvt_pk_bf16_f32 v38, v38, v39
	v_cvt_pk_bf16_f32 v39, v40, v41
	v_cvt_pk_bf16_f32 v40, v28, v29
	v_add_u32_e32 v28, 0xa0, v152
	v_mad_i64_i32 v[28:29], s[14:15], v28, s67, v[144:145]
	v_cvt_pk_bf16_f32 v41, v30, v31
	global_store_dwordx4 v[54:55], v[38:41], off offset:256
	s_nop 1
	v_lshl_add_u64 v[38:39], v[28:29], 0, v[146:147]
	v_cvt_pk_bf16_f32 v28, v42, v43
	v_cvt_pk_bf16_f32 v29, v44, v45
	v_cvt_pk_bf16_f32 v30, v32, v33
	v_cvt_pk_bf16_f32 v31, v34, v35
	global_store_dwordx4 v[38:39], v[28:31], off
	v_cvt_pk_bf16_f32 v20, v20, v21
	v_cvt_pk_bf16_f32 v21, v22, v23
	v_cvt_pk_bf16_f32 v22, v12, v13
	v_add_u32_e32 v12, 0xb0, v152
	v_mad_i64_i32 v[12:13], s[14:15], v12, s67, v[144:145]
	v_cvt_pk_bf16_f32 v23, v14, v15
	global_store_dwordx4 v[38:39], v[20:23], off offset:256
	s_mov_b64 s[14:15], s[10:11]
	s_nop 0
	v_lshl_add_u64 v[20:21], v[12:13], 0, v[146:147]
	v_cvt_pk_bf16_f32 v12, v24, v25
	v_cvt_pk_bf16_f32 v13, v26, v27
	v_cvt_pk_bf16_f32 v14, v16, v17
	v_cvt_pk_bf16_f32 v15, v18, v19
	global_store_dwordx4 v[20:21], v[12:15], off
	v_cvt_pk_bf16_f32 v8, v8, v9
	v_cvt_pk_bf16_f32 v9, v10, v11
	v_cvt_pk_bf16_f32 v10, v4, v5
	v_cvt_pk_bf16_f32 v11, v6, v7
	global_store_dwordx4 v[20:21], v[8:11], off offset:256
	s_cbranch_vccz .LBB0_810
	s_waitcnt vmcnt(0)
	s_cmpk_gt_u32 s27, 0xff
	s_cbranch_scc1 .LBB0_817
	s_barrier

.LBB0_827:
	s_add_u32 s16, s14, 0xfffc0080
	s_addc_u32 s17, s15, -1
	s_add_i32 s53, 0, 0x10000
	v_add_u32_e32 v158, s53, v37
	ds_read_b128 v[144:147], v158
	ds_read_b128 v[150:153], v158 offset:1024
	ds_read_b128 v[154:157], v158 offset:2048
	ds_read_b128 v[162:165], v158 offset:3072
	s_cmp_eq_u32 s52, 12
	s_cselect_b32 s19, s7, s17
	s_cselect_b32 s18, s48, s16
	s_cselect_b32 s17, s1, s51
	s_cselect_b32 s16, s49, s50
	v_lshl_add_u64 v[158:159], s[14:15], 0, v[140:141]
	s_add_i32 m0, s9, 0xc000
	ds_read_b128 v[166:169], v149
	ds_read_b128 v[170:173], v149 offset:1024
	ds_read_b128 v[174:177], v149 offset:2048
	ds_read_b128 v[178:181], v149 offset:3072
	ds_read_b128 v[182:185], v149 offset:4096
	ds_read_b128 v[186:189], v149 offset:5120
	ds_read_b128 v[190:193], v149 offset:6144
	ds_read_b128 v[194:197], v149 offset:7168
	global_load_lds_dwordx4 v[158:159], off
	v_lshl_add_u64 v[158:159], s[14:15], 0, v[142:143]
	s_add_i32 m0, s9, 0xe000
	s_nop 0
	global_load_lds_dwordx4 v[158:159], off
	s_waitcnt lgkmcnt(8)
	s_barrier
	s_waitcnt lgkmcnt(0)
	s_waitcnt lgkmcnt(0)
	v_mfma_f32_16x16x32_bf16 v[130:133], v[144:147], v[166:169], v[130:133]
	v_mfma_f32_16x16x32_bf16 v[126:129], v[154:157], v[166:169], v[126:129]
	v_mfma_f32_16x16x32_bf16 v[122:125], v[144:147], v[174:177], v[122:125]
	v_mfma_f32_16x16x32_bf16 v[114:117], v[154:157], v[174:177], v[114:117]
	v_mfma_f32_16x16x32_bf16 v[106:109], v[144:147], v[182:185], v[106:109]
	v_mfma_f32_16x16x32_bf16 v[98:101], v[154:157], v[182:185], v[98:101]
	v_mfma_f32_16x16x32_bf16 v[90:93], v[144:147], v[190:193], v[90:93]
	v_mfma_f32_16x16x32_bf16 v[82:85], v[154:157], v[190:193], v[82:85]
	v_mfma_f32_16x16x32_bf16 v[130:133], v[150:153], v[170:173], v[130:133]
	v_mfma_f32_16x16x32_bf16 v[126:129], v[162:165], v[170:173], v[126:129]
	v_mfma_f32_16x16x32_bf16 v[122:125], v[150:153], v[178:181], v[122:125]
	v_mfma_f32_16x16x32_bf16 v[114:117], v[162:165], v[178:181], v[114:117]
	v_mfma_f32_16x16x32_bf16 v[106:109], v[150:153], v[186:189], v[106:109]
	v_mfma_f32_16x16x32_bf16 v[98:101], v[162:165], v[186:189], v[98:101]
	v_mfma_f32_16x16x32_bf16 v[90:93], v[150:153], v[194:197], v[90:93]
	v_mfma_f32_16x16x32_bf16 v[82:85], v[162:165], v[194:197], v[82:85]
	s_barrier
	s_add_i32 s56, 0, 0x14000
	v_add_u32_e32 v158, s56, v37
	s_add_i32 s53, s53, s36
	ds_read_b128 v[198:201], v158
	ds_read_b128 v[202:205], v158 offset:1024
	ds_read_b128 v[206:209], v158 offset:2048
	ds_read_b128 v[210:213], v158 offset:3072
	v_lshl_add_u64 v[158:159], s[16:17], 0, v[2:3]
	s_mov_b32 m0, s53
	v_lshl_add_u64 v[160:161], s[16:17], 0, v[134:135]
	global_load_lds_dwordx4 v[158:159], off
	s_add_i32 m0, s53, 0x2000
	s_nop 0
	global_load_lds_dwordx4 v[160:161], off
	s_barrier
	s_waitcnt lgkmcnt(0)
	s_waitcnt lgkmcnt(0)
	v_mfma_f32_16x16x32_bf16 v[118:121], v[198:201], v[166:169], v[118:121]
	v_mfma_f32_16x16x32_bf16 v[110:113], v[206:209], v[166:169], v[110:113]
	v_mfma_f32_16x16x32_bf16 v[102:105], v[198:201], v[174:177], v[102:105]
	v_mfma_f32_16x16x32_bf16 v[94:97], v[206:209], v[174:177], v[94:97]
	v_mfma_f32_16x16x32_bf16 v[86:89], v[198:201], v[182:185], v[86:89]
	v_mfma_f32_16x16x32_bf16 v[78:81], v[206:209], v[182:185], v[78:81]
	v_mfma_f32_16x16x32_bf16 v[74:77], v[198:201], v[190:193], v[74:77]
	v_mfma_f32_16x16x32_bf16 v[70:73], v[206:209], v[190:193], v[70:73]
	v_mfma_f32_16x16x32_bf16 v[118:121], v[202:205], v[170:173], v[118:121]
	v_mfma_f32_16x16x32_bf16 v[110:113], v[210:213], v[170:173], v[110:113]
	v_mfma_f32_16x16x32_bf16 v[102:105], v[202:205], v[178:181], v[102:105]
	v_mfma_f32_16x16x32_bf16 v[94:97], v[210:213], v[178:181], v[94:97]
	v_mfma_f32_16x16x32_bf16 v[86:89], v[202:205], v[186:189], v[86:89]
	v_mfma_f32_16x16x32_bf16 v[78:81], v[210:213], v[186:189], v[78:81]
	v_mfma_f32_16x16x32_bf16 v[74:77], v[202:205], v[194:197], v[74:77]
	v_mfma_f32_16x16x32_bf16 v[70:73], v[210:213], v[194:197], v[70:73]
	s_mov_b32 m0, s9
	v_lshl_add_u64 v[214:215], s[18:19], 0, v[138:139]
	s_barrier
	ds_read_b128 v[166:169], v149 offset:16384
	ds_read_b128 v[170:173], v149 offset:17408
	ds_read_b128 v[174:177], v149 offset:18432
	ds_read_b128 v[178:181], v149 offset:19456
	ds_read_b128 v[182:185], v149 offset:20480
	ds_read_b128 v[186:189], v149 offset:21504
	ds_read_b128 v[190:193], v149 offset:22528
	ds_read_b128 v[194:197], v149 offset:23552
	global_load_lds_dwordx4 v[214:215], off
	v_lshl_add_u64 v[216:217], s[18:19], 0, v[136:137]
	s_mov_b32 m0, s40
	s_nop 0
	global_load_lds_dwordx4 v[216:217], off
	s_barrier
	s_waitcnt lgkmcnt(0)
	s_waitcnt lgkmcnt(0)
	v_mfma_f32_16x16x32_bf16 v[66:69], v[144:147], v[166:169], v[66:69]
	v_mfma_f32_16x16x32_bf16 v[62:65], v[154:157], v[166:169], v[62:65]
	v_mfma_f32_16x16x32_bf16 v[58:61], v[144:147], v[174:177], v[58:61]
	v_mfma_f32_16x16x32_bf16 v[50:53], v[154:157], v[174:177], v[50:53]
	v_mfma_f32_16x16x32_bf16 v[42:45], v[144:147], v[182:185], v[42:45]
	v_mfma_f32_16x16x32_bf16 v[32:35], v[154:157], v[182:185], v[32:35]
	v_mfma_f32_16x16x32_bf16 v[24:27], v[144:147], v[190:193], v[24:27]
	v_mfma_f32_16x16x32_bf16 v[16:19], v[154:157], v[190:193], v[16:19]
	v_mfma_f32_16x16x32_bf16 v[66:69], v[150:153], v[170:173], v[66:69]
	v_mfma_f32_16x16x32_bf16 v[62:65], v[162:165], v[170:173], v[62:65]
	v_mfma_f32_16x16x32_bf16 v[58:61], v[150:153], v[178:181], v[58:61]
	v_mfma_f32_16x16x32_bf16 v[50:53], v[162:165], v[178:181], v[50:53]
	v_mfma_f32_16x16x32_bf16 v[42:45], v[150:153], v[186:189], v[42:45]
	v_mfma_f32_16x16x32_bf16 v[32:35], v[162:165], v[186:189], v[32:35]
	v_mfma_f32_16x16x32_bf16 v[24:27], v[150:153], v[194:197], v[24:27]
	v_mfma_f32_16x16x32_bf16 v[16:19], v[162:165], v[194:197], v[16:19]
	s_barrier
	s_add_u32 s54, s16, 0x40000
	s_addc_u32 s55, s17, 0
	s_add_i32 s53, s56, s36
	v_lshl_add_u64 v[144:145], s[54:55], 0, v[2:3]
	s_mov_b32 m0, s53
	s_nop 0
	global_load_lds_dwordx4 v[144:145], off
	v_lshl_add_u64 v[144:145], s[54:55], 0, v[134:135]
	s_add_i32 m0, s53, 0x2000
	s_nop 0
	global_load_lds_dwordx4 v[144:145], off
	s_waitcnt vmcnt(6)
	s_barrier
	v_mfma_f32_16x16x32_bf16 v[54:57], v[198:201], v[166:169], v[54:57]
	v_mfma_f32_16x16x32_bf16 v[46:49], v[206:209], v[166:169], v[46:49]
	v_mfma_f32_16x16x32_bf16 v[38:41], v[198:201], v[174:177], v[38:41]
	v_mfma_f32_16x16x32_bf16 v[28:31], v[206:209], v[174:177], v[28:31]
	v_mfma_f32_16x16x32_bf16 v[20:23], v[198:201], v[182:185], v[20:23]
	v_mfma_f32_16x16x32_bf16 v[12:15], v[206:209], v[182:185], v[12:15]
	v_mfma_f32_16x16x32_bf16 v[8:11], v[198:201], v[190:193], v[8:11]
	v_mfma_f32_16x16x32_bf16 v[4:7], v[206:209], v[190:193], v[4:7]
	v_mfma_f32_16x16x32_bf16 v[54:57], v[202:205], v[170:173], v[54:57]
	v_mfma_f32_16x16x32_bf16 v[46:49], v[210:213], v[170:173], v[46:49]
	v_mfma_f32_16x16x32_bf16 v[38:41], v[202:205], v[178:181], v[38:41]
	v_mfma_f32_16x16x32_bf16 v[28:31], v[210:213], v[178:181], v[28:31]
	v_mfma_f32_16x16x32_bf16 v[20:23], v[202:205], v[186:189], v[20:23]
	v_mfma_f32_16x16x32_bf16 v[12:15], v[210:213], v[186:189], v[12:15]
	v_mfma_f32_16x16x32_bf16 v[8:11], v[202:205], v[194:197], v[8:11]
	v_mfma_f32_16x16x32_bf16 v[4:7], v[210:213], v[194:197], v[4:7]
	s_add_i32 s53, 0, 0x18000
	v_add_u32_e32 v162, s53, v37
	s_barrier
	ds_read_b128 v[144:147], v162
	ds_read_b128 v[150:153], v162 offset:1024
	ds_read_b128 v[154:157], v162 offset:2048
	ds_read_b128 v[162:165], v162 offset:3072
	s_add_u32 s18, s18, 0x40000
	s_addc_u32 s19, s19, 0
	s_mov_b32 m0, s41
	v_lshl_add_u64 v[198:199], s[18:19], 0, v[138:139]
	ds_read_b128 v[166:169], v149 offset:32768
	ds_read_b128 v[170:173], v149 offset:33792
	ds_read_b128 v[174:177], v149 offset:34816
	ds_read_b128 v[178:181], v149 offset:35840
	ds_read_b128 v[182:185], v149 offset:36864
	ds_read_b128 v[186:189], v149 offset:37888
	ds_read_b128 v[190:193], v149 offset:38912
	ds_read_b128 v[194:197], v149 offset:39936
	global_load_lds_dwordx4 v[198:199], off
	v_lshl_add_u64 v[198:199], s[18:19], 0, v[136:137]
	s_mov_b32 m0, s42
	s_nop 0
	global_load_lds_dwordx4 v[198:199], off
	s_waitcnt lgkmcnt(8)
	s_barrier
	s_waitcnt lgkmcnt(0)
	s_waitcnt lgkmcnt(0)
	v_mfma_f32_16x16x32_bf16 v[130:133], v[144:147], v[166:169], v[130:133]
	v_mfma_f32_16x16x32_bf16 v[126:129], v[154:157], v[166:169], v[126:129]
	v_mfma_f32_16x16x32_bf16 v[122:125], v[144:147], v[174:177], v[122:125]
	v_mfma_f32_16x16x32_bf16 v[114:117], v[154:157], v[174:177], v[114:117]
	v_mfma_f32_16x16x32_bf16 v[106:109], v[144:147], v[182:185], v[106:109]
	v_mfma_f32_16x16x32_bf16 v[98:101], v[154:157], v[182:185], v[98:101]
	v_mfma_f32_16x16x32_bf16 v[90:93], v[144:147], v[190:193], v[90:93]
	v_mfma_f32_16x16x32_bf16 v[82:85], v[154:157], v[190:193], v[82:85]
	v_mfma_f32_16x16x32_bf16 v[130:133], v[150:153], v[170:173], v[130:133]
	v_mfma_f32_16x16x32_bf16 v[126:129], v[162:165], v[170:173], v[126:129]
	v_mfma_f32_16x16x32_bf16 v[122:125], v[150:153], v[178:181], v[122:125]
	v_mfma_f32_16x16x32_bf16 v[114:117], v[162:165], v[178:181], v[114:117]
	v_mfma_f32_16x16x32_bf16 v[106:109], v[150:153], v[186:189], v[106:109]
	v_mfma_f32_16x16x32_bf16 v[98:101], v[162:165], v[186:189], v[98:101]
	v_mfma_f32_16x16x32_bf16 v[90:93], v[150:153], v[194:197], v[90:93]
	v_mfma_f32_16x16x32_bf16 v[82:85], v[162:165], v[194:197], v[82:85]
	s_barrier
	s_add_i32 s18, 0, 0x1c000
	s_add_i32 s19, s53, s36
	v_add_u32_e32 v210, s18, v37
	v_lshl_add_u64 v[158:159], v[158:159], 0, s[24:25]
	s_mov_b32 m0, s19
	ds_read_b128 v[198:201], v210
	ds_read_b128 v[202:205], v210 offset:1024
	ds_read_b128 v[206:209], v210 offset:2048
	ds_read_b128 v[210:213], v210 offset:3072
	global_load_lds_dwordx4 v[158:159], off
	v_lshl_add_u64 v[158:159], v[160:161], 0, s[24:25]
	s_add_i32 m0, s19, 0x2000
	s_nop 0
	global_load_lds_dwordx4 v[158:159], off
	s_barrier
	s_waitcnt lgkmcnt(0)
	s_waitcnt lgkmcnt(0)
	v_mfma_f32_16x16x32_bf16 v[118:121], v[198:201], v[166:169], v[118:121]
	v_mfma_f32_16x16x32_bf16 v[110:113], v[206:209], v[166:169], v[110:113]
	v_mfma_f32_16x16x32_bf16 v[102:105], v[198:201], v[174:177], v[102:105]
	v_mfma_f32_16x16x32_bf16 v[94:97], v[206:209], v[174:177], v[94:97]
	v_mfma_f32_16x16x32_bf16 v[86:89], v[198:201], v[182:185], v[86:89]
	v_mfma_f32_16x16x32_bf16 v[78:81], v[206:209], v[182:185], v[78:81]
	v_mfma_f32_16x16x32_bf16 v[74:77], v[198:201], v[190:193], v[74:77]
	v_mfma_f32_16x16x32_bf16 v[70:73], v[206:209], v[190:193], v[70:73]
	v_mfma_f32_16x16x32_bf16 v[118:121], v[202:205], v[170:173], v[118:121]
	v_mfma_f32_16x16x32_bf16 v[110:113], v[210:213], v[170:173], v[110:113]
	v_mfma_f32_16x16x32_bf16 v[102:105], v[202:205], v[178:181], v[102:105]
	v_mfma_f32_16x16x32_bf16 v[94:97], v[210:213], v[178:181], v[94:97]
	v_mfma_f32_16x16x32_bf16 v[86:89], v[202:205], v[186:189], v[86:89]
	v_mfma_f32_16x16x32_bf16 v[78:81], v[210:213], v[186:189], v[78:81]
	v_mfma_f32_16x16x32_bf16 v[74:77], v[202:205], v[194:197], v[74:77]
	v_mfma_f32_16x16x32_bf16 v[70:73], v[210:213], v[194:197], v[70:73]
	s_mov_b32 m0, s43
	v_lshl_add_u64 v[158:159], v[214:215], 0, s[24:25]
	s_barrier
	ds_read_b128 v[166:169], v149 offset:49152
	ds_read_b128 v[170:173], v149 offset:50176
	ds_read_b128 v[174:177], v149 offset:51200
	ds_read_b128 v[178:181], v149 offset:52224
	ds_read_b128 v[182:185], v149 offset:53248
	ds_read_b128 v[186:189], v149 offset:54272
	ds_read_b128 v[190:193], v149 offset:55296
	ds_read_b128 v[194:197], v149 offset:56320
	global_load_lds_dwordx4 v[158:159], off
	v_lshl_add_u64 v[158:159], v[216:217], 0, s[24:25]
	s_mov_b32 m0, s44
	s_nop 0
	global_load_lds_dwordx4 v[158:159], off
	s_barrier
	s_waitcnt lgkmcnt(0)
	s_waitcnt lgkmcnt(0)
	v_mfma_f32_16x16x32_bf16 v[66:69], v[144:147], v[166:169], v[66:69]
	v_mfma_f32_16x16x32_bf16 v[62:65], v[154:157], v[166:169], v[62:65]
	v_mfma_f32_16x16x32_bf16 v[58:61], v[144:147], v[174:177], v[58:61]
	v_mfma_f32_16x16x32_bf16 v[50:53], v[154:157], v[174:177], v[50:53]
	v_mfma_f32_16x16x32_bf16 v[42:45], v[144:147], v[182:185], v[42:45]
	v_mfma_f32_16x16x32_bf16 v[32:35], v[154:157], v[182:185], v[32:35]
	v_mfma_f32_16x16x32_bf16 v[24:27], v[144:147], v[190:193], v[24:27]
	v_mfma_f32_16x16x32_bf16 v[16:19], v[154:157], v[190:193], v[16:19]
	v_mfma_f32_16x16x32_bf16 v[66:69], v[150:153], v[170:173], v[66:69]
	v_mfma_f32_16x16x32_bf16 v[62:65], v[162:165], v[170:173], v[62:65]
	v_mfma_f32_16x16x32_bf16 v[58:61], v[150:153], v[178:181], v[58:61]
	v_mfma_f32_16x16x32_bf16 v[50:53], v[162:165], v[178:181], v[50:53]
	v_mfma_f32_16x16x32_bf16 v[42:45], v[150:153], v[186:189], v[42:45]
	v_mfma_f32_16x16x32_bf16 v[32:35], v[162:165], v[186:189], v[32:35]
	v_mfma_f32_16x16x32_bf16 v[24:27], v[150:153], v[194:197], v[24:27]
	v_mfma_f32_16x16x32_bf16 v[16:19], v[162:165], v[194:197], v[16:19]
	s_barrier
	s_add_u32 s16, s16, 0x40080
	s_addc_u32 s17, s17, 0
	s_add_i32 s18, s18, s36
	v_lshl_add_u64 v[144:145], s[16:17], 0, v[2:3]
	s_mov_b32 m0, s18
	s_nop 0
	global_load_lds_dwordx4 v[144:145], off
	v_lshl_add_u64 v[144:145], s[16:17], 0, v[134:135]
	s_add_i32 m0, s18, 0x2000
	s_nop 0
	global_load_lds_dwordx4 v[144:145], off
	s_waitcnt vmcnt(6)
	s_barrier
	v_mfma_f32_16x16x32_bf16 v[54:57], v[198:201], v[166:169], v[54:57]
	v_mfma_f32_16x16x32_bf16 v[46:49], v[206:209], v[166:169], v[46:49]
	v_mfma_f32_16x16x32_bf16 v[38:41], v[198:201], v[174:177], v[38:41]
	v_mfma_f32_16x16x32_bf16 v[28:31], v[206:209], v[174:177], v[28:31]
	v_mfma_f32_16x16x32_bf16 v[20:23], v[198:201], v[182:185], v[20:23]
	v_mfma_f32_16x16x32_bf16 v[12:15], v[206:209], v[182:185], v[12:15]
	v_mfma_f32_16x16x32_bf16 v[8:11], v[198:201], v[190:193], v[8:11]
	v_mfma_f32_16x16x32_bf16 v[4:7], v[206:209], v[190:193], v[4:7]
	v_mfma_f32_16x16x32_bf16 v[54:57], v[202:205], v[170:173], v[54:57]
	v_mfma_f32_16x16x32_bf16 v[46:49], v[210:213], v[170:173], v[46:49]
	v_mfma_f32_16x16x32_bf16 v[38:41], v[202:205], v[178:181], v[38:41]
	v_mfma_f32_16x16x32_bf16 v[28:31], v[210:213], v[178:181], v[28:31]
	v_mfma_f32_16x16x32_bf16 v[20:23], v[202:205], v[186:189], v[20:23]
	v_mfma_f32_16x16x32_bf16 v[12:15], v[210:213], v[186:189], v[12:15]
	v_mfma_f32_16x16x32_bf16 v[8:11], v[202:205], v[194:197], v[8:11]
	v_mfma_f32_16x16x32_bf16 v[4:7], v[210:213], v[194:197], v[4:7]
	s_add_i32 s52, s52, 2
	s_add_u32 s14, s14, 0x100
	s_addc_u32 s15, s15, 0
	s_add_u32 s50, s50, 0x100
	s_addc_u32 s51, s51, 0
	s_cmp_gt_u32 s52, 13
	s_barrier
	s_cbranch_scc0 .LBB0_827
	v_lshl_or_b32 v146, s47, 8, v148
	v_lshl_add_u32 v152, s8, 8, v1
	v_ashrrev_i32_e32 v147, 31, v146
	v_mov_b64_e32 v[144:145], s[34:35]
	v_mad_i64_i32 v[150:151], s[14:15], v152, s57, v[144:145]
	v_lshlrev_b64 v[146:147], 1, v[146:147]
	v_lshl_add_u64 v[150:151], v[150:151], 0, v[146:147]
	v_cvt_pk_bf16_f32 v130, v130, v131
	v_cvt_pk_bf16_f32 v131, v132, v133
	v_cvt_pk_bf16_f32 v132, v126, v127
	v_cvt_pk_bf16_f32 v133, v128, v129
	global_store_dwordx4 v[150:151], v[130:133], off
	v_cvt_pk_bf16_f32 v118, v118, v119
	v_cvt_pk_bf16_f32 v119, v120, v121
	v_cvt_pk_bf16_f32 v120, v110, v111
	v_or_b32_e32 v110, 16, v152
	v_mad_i64_i32 v[110:111], s[14:15], v110, s57, v[144:145]
	v_cvt_pk_bf16_f32 v121, v112, v113
	global_store_dwordx4 v[150:151], v[118:121], off offset:256
	s_and_b64 vcc, exec, s[4:5]
	s_mov_b32 s47, s0
	v_lshl_add_u64 v[118:119], v[110:111], 0, v[146:147]
	v_cvt_pk_bf16_f32 v110, v122, v123
	v_cvt_pk_bf16_f32 v111, v124, v125
	v_cvt_pk_bf16_f32 v112, v114, v115
	v_cvt_pk_bf16_f32 v113, v116, v117
	global_store_dwordx4 v[118:119], v[110:113], off
	v_cvt_pk_bf16_f32 v102, v102, v103
	v_cvt_pk_bf16_f32 v103, v104, v105
	v_cvt_pk_bf16_f32 v104, v94, v95
	v_or_b32_e32 v94, 32, v152
	v_mad_i64_i32 v[94:95], s[14:15], v94, s57, v[144:145]
	v_cvt_pk_bf16_f32 v105, v96, v97
	global_store_dwordx4 v[118:119], v[102:105], off offset:256
	s_mov_b32 s8, s6
	s_mov_b64 s[16:17], s[12:13]
	v_lshl_add_u64 v[102:103], v[94:95], 0, v[146:147]
	v_cvt_pk_bf16_f32 v94, v106, v107
	v_cvt_pk_bf16_f32 v95, v108, v109
	v_cvt_pk_bf16_f32 v96, v98, v99
	v_cvt_pk_bf16_f32 v97, v100, v101
	global_store_dwordx4 v[102:103], v[94:97], off
	v_cvt_pk_bf16_f32 v86, v86, v87
	v_cvt_pk_bf16_f32 v87, v88, v89
	v_cvt_pk_bf16_f32 v88, v78, v79
	v_or_b32_e32 v78, 48, v152
	v_mad_i64_i32 v[78:79], s[14:15], v78, s57, v[144:145]
	v_cvt_pk_bf16_f32 v89, v80, v81
	global_store_dwordx4 v[102:103], v[86:89], off offset:256
	s_nop 1
	v_lshl_add_u64 v[86:87], v[78:79], 0, v[146:147]
	v_cvt_pk_bf16_f32 v78, v90, v91
	v_cvt_pk_bf16_f32 v79, v92, v93
	v_cvt_pk_bf16_f32 v80, v82, v83
	v_cvt_pk_bf16_f32 v81, v84, v85
	global_store_dwordx4 v[86:87], v[78:81], off
	v_cvt_pk_bf16_f32 v74, v74, v75
	v_cvt_pk_bf16_f32 v75, v76, v77
	v_cvt_pk_bf16_f32 v76, v70, v71
	v_add_u32_e32 v70, 0x80, v152
	v_mad_i64_i32 v[70:71], s[14:15], v70, s57, v[144:145]
	v_lshl_add_u64 v[70:71], v[70:71], 0, v[146:147]
	v_cvt_pk_bf16_f32 v77, v72, v73
	global_store_dwordx4 v[86:87], v[74:77], off offset:256
	v_cvt_pk_bf16_f32 v66, v66, v67
	v_cvt_pk_bf16_f32 v67, v68, v69
	v_cvt_pk_bf16_f32 v68, v62, v63
	v_cvt_pk_bf16_f32 v69, v64, v65
	global_store_dwordx4 v[70:71], v[66:69], off
	v_cvt_pk_bf16_f32 v54, v54, v55
	v_cvt_pk_bf16_f32 v55, v56, v57
	v_cvt_pk_bf16_f32 v56, v46, v47
	v_add_u32_e32 v46, 0x90, v152
	v_mad_i64_i32 v[46:47], s[14:15], v46, s57, v[144:145]
	v_cvt_pk_bf16_f32 v57, v48, v49
	global_store_dwordx4 v[70:71], v[54:57], off offset:256
	s_nop 1
	v_lshl_add_u64 v[54:55], v[46:47], 0, v[146:147]
	v_cvt_pk_bf16_f32 v46, v58, v59
	v_cvt_pk_bf16_f32 v47, v60, v61
	v_cvt_pk_bf16_f32 v48, v50, v51
	v_cvt_pk_bf16_f32 v49, v52, v53
	global_store_dwordx4 v[54:55], v[46:49], off
	v_cvt_pk_bf16_f32 v38, v38, v39
	v_cvt_pk_bf16_f32 v39, v40, v41
	v_cvt_pk_bf16_f32 v40, v28, v29
	v_add_u32_e32 v28, 0xa0, v152
	v_mad_i64_i32 v[28:29], s[14:15], v28, s57, v[144:145]
	v_cvt_pk_bf16_f32 v41, v30, v31
	global_store_dwordx4 v[54:55], v[38:41], off offset:256
	s_nop 1
	v_lshl_add_u64 v[38:39], v[28:29], 0, v[146:147]
	v_cvt_pk_bf16_f32 v28, v42, v43
	v_cvt_pk_bf16_f32 v29, v44, v45
	v_cvt_pk_bf16_f32 v30, v32, v33
	v_cvt_pk_bf16_f32 v31, v34, v35
	global_store_dwordx4 v[38:39], v[28:31], off
	v_cvt_pk_bf16_f32 v20, v20, v21
	v_cvt_pk_bf16_f32 v21, v22, v23
	v_cvt_pk_bf16_f32 v22, v12, v13
	v_add_u32_e32 v12, 0xb0, v152
	v_mad_i64_i32 v[12:13], s[14:15], v12, s57, v[144:145]
	v_cvt_pk_bf16_f32 v23, v14, v15
	global_store_dwordx4 v[38:39], v[20:23], off offset:256
	s_mov_b64 s[14:15], s[10:11]
	s_nop 0
	v_lshl_add_u64 v[20:21], v[12:13], 0, v[146:147]
	v_cvt_pk_bf16_f32 v12, v24, v25
	v_cvt_pk_bf16_f32 v13, v26, v27
	v_cvt_pk_bf16_f32 v14, v16, v17
	v_cvt_pk_bf16_f32 v15, v18, v19
	global_store_dwordx4 v[20:21], v[12:15], off
	v_cvt_pk_bf16_f32 v8, v8, v9
	v_cvt_pk_bf16_f32 v9, v10, v11
	v_cvt_pk_bf16_f32 v10, v4, v5
	v_cvt_pk_bf16_f32 v11, v6, v7
	global_store_dwordx4 v[20:21], v[8:11], off offset:256
	s_cbranch_vccz .LBB0_824
	s_waitcnt vmcnt(0)
	s_cmpk_gt_u32 s27, 0xff
	s_cbranch_scc1 .LBB0_831
	s_barrier

.LBB0_841:
	s_add_u32 s16, s14, 0xfffc0080
	s_addc_u32 s17, s15, -1
	s_add_i32 s51, 0, 0x10000
	v_add_u32_e32 v158, s51, v37
	ds_read_b128 v[144:147], v158
	ds_read_b128 v[150:153], v158 offset:1024
	ds_read_b128 v[154:157], v158 offset:2048
	ds_read_b128 v[162:165], v158 offset:3072
	s_cmp_eq_u32 s50, 12
	s_cselect_b32 s19, s7, s17
	s_cselect_b32 s18, s46, s16
	s_cselect_b32 s17, s1, s49
	s_cselect_b32 s16, s47, s48
	v_lshl_add_u64 v[158:159], s[14:15], 0, v[140:141]
	s_add_i32 m0, s13, 0xc000
	ds_read_b128 v[166:169], v149
	ds_read_b128 v[170:173], v149 offset:1024
	ds_read_b128 v[174:177], v149 offset:2048
	ds_read_b128 v[178:181], v149 offset:3072
	ds_read_b128 v[182:185], v149 offset:4096
	ds_read_b128 v[186:189], v149 offset:5120
	ds_read_b128 v[190:193], v149 offset:6144
	ds_read_b128 v[194:197], v149 offset:7168
	global_load_lds_dwordx4 v[158:159], off
	v_lshl_add_u64 v[158:159], s[14:15], 0, v[142:143]
	s_add_i32 m0, s13, 0xe000
	s_nop 0
	global_load_lds_dwordx4 v[158:159], off
	s_waitcnt lgkmcnt(8)
	s_barrier
	s_waitcnt lgkmcnt(0)
	s_waitcnt lgkmcnt(0)
	v_mfma_f32_16x16x32_bf16 v[130:133], v[144:147], v[166:169], v[130:133]
	v_mfma_f32_16x16x32_bf16 v[126:129], v[154:157], v[166:169], v[126:129]
	v_mfma_f32_16x16x32_bf16 v[122:125], v[144:147], v[174:177], v[122:125]
	v_mfma_f32_16x16x32_bf16 v[114:117], v[154:157], v[174:177], v[114:117]
	v_mfma_f32_16x16x32_bf16 v[106:109], v[144:147], v[182:185], v[106:109]
	v_mfma_f32_16x16x32_bf16 v[98:101], v[154:157], v[182:185], v[98:101]
	v_mfma_f32_16x16x32_bf16 v[90:93], v[144:147], v[190:193], v[90:93]
	v_mfma_f32_16x16x32_bf16 v[82:85], v[154:157], v[190:193], v[82:85]
	v_mfma_f32_16x16x32_bf16 v[130:133], v[150:153], v[170:173], v[130:133]
	v_mfma_f32_16x16x32_bf16 v[126:129], v[162:165], v[170:173], v[126:129]
	v_mfma_f32_16x16x32_bf16 v[122:125], v[150:153], v[178:181], v[122:125]
	v_mfma_f32_16x16x32_bf16 v[114:117], v[162:165], v[178:181], v[114:117]
	v_mfma_f32_16x16x32_bf16 v[106:109], v[150:153], v[186:189], v[106:109]
	v_mfma_f32_16x16x32_bf16 v[98:101], v[162:165], v[186:189], v[98:101]
	v_mfma_f32_16x16x32_bf16 v[90:93], v[150:153], v[194:197], v[90:93]
	v_mfma_f32_16x16x32_bf16 v[82:85], v[162:165], v[194:197], v[82:85]
	s_barrier
	s_add_i32 s54, 0, 0x14000
	v_add_u32_e32 v158, s54, v37
	s_add_i32 s51, s51, s36
	ds_read_b128 v[198:201], v158
	ds_read_b128 v[202:205], v158 offset:1024
	ds_read_b128 v[206:209], v158 offset:2048
	ds_read_b128 v[210:213], v158 offset:3072
	v_lshl_add_u64 v[158:159], s[16:17], 0, v[2:3]
	s_mov_b32 m0, s51
	v_lshl_add_u64 v[160:161], s[16:17], 0, v[134:135]
	global_load_lds_dwordx4 v[158:159], off
	s_add_i32 m0, s51, 0x2000
	s_nop 0
	global_load_lds_dwordx4 v[160:161], off
	s_barrier
	s_waitcnt lgkmcnt(0)
	s_waitcnt lgkmcnt(0)
	v_mfma_f32_16x16x32_bf16 v[118:121], v[198:201], v[166:169], v[118:121]
	v_mfma_f32_16x16x32_bf16 v[110:113], v[206:209], v[166:169], v[110:113]
	v_mfma_f32_16x16x32_bf16 v[102:105], v[198:201], v[174:177], v[102:105]
	v_mfma_f32_16x16x32_bf16 v[94:97], v[206:209], v[174:177], v[94:97]
	v_mfma_f32_16x16x32_bf16 v[86:89], v[198:201], v[182:185], v[86:89]
	v_mfma_f32_16x16x32_bf16 v[78:81], v[206:209], v[182:185], v[78:81]
	v_mfma_f32_16x16x32_bf16 v[74:77], v[198:201], v[190:193], v[74:77]
	v_mfma_f32_16x16x32_bf16 v[70:73], v[206:209], v[190:193], v[70:73]
	v_mfma_f32_16x16x32_bf16 v[118:121], v[202:205], v[170:173], v[118:121]
	v_mfma_f32_16x16x32_bf16 v[110:113], v[210:213], v[170:173], v[110:113]
	v_mfma_f32_16x16x32_bf16 v[102:105], v[202:205], v[178:181], v[102:105]
	v_mfma_f32_16x16x32_bf16 v[94:97], v[210:213], v[178:181], v[94:97]
	v_mfma_f32_16x16x32_bf16 v[86:89], v[202:205], v[186:189], v[86:89]
	v_mfma_f32_16x16x32_bf16 v[78:81], v[210:213], v[186:189], v[78:81]
	v_mfma_f32_16x16x32_bf16 v[74:77], v[202:205], v[194:197], v[74:77]
	v_mfma_f32_16x16x32_bf16 v[70:73], v[210:213], v[194:197], v[70:73]
	s_mov_b32 m0, s13
	v_lshl_add_u64 v[214:215], s[18:19], 0, v[138:139]
	s_barrier
	ds_read_b128 v[166:169], v149 offset:16384
	ds_read_b128 v[170:173], v149 offset:17408
	ds_read_b128 v[174:177], v149 offset:18432
	ds_read_b128 v[178:181], v149 offset:19456
	ds_read_b128 v[182:185], v149 offset:20480
	ds_read_b128 v[186:189], v149 offset:21504
	ds_read_b128 v[190:193], v149 offset:22528
	ds_read_b128 v[194:197], v149 offset:23552
	global_load_lds_dwordx4 v[214:215], off
	v_lshl_add_u64 v[216:217], s[18:19], 0, v[136:137]
	s_mov_b32 m0, s38
	s_nop 0
	global_load_lds_dwordx4 v[216:217], off
	s_barrier
	s_waitcnt lgkmcnt(0)
	s_waitcnt lgkmcnt(0)
	v_mfma_f32_16x16x32_bf16 v[66:69], v[144:147], v[166:169], v[66:69]
	v_mfma_f32_16x16x32_bf16 v[62:65], v[154:157], v[166:169], v[62:65]
	v_mfma_f32_16x16x32_bf16 v[58:61], v[144:147], v[174:177], v[58:61]
	v_mfma_f32_16x16x32_bf16 v[50:53], v[154:157], v[174:177], v[50:53]
	v_mfma_f32_16x16x32_bf16 v[42:45], v[144:147], v[182:185], v[42:45]
	v_mfma_f32_16x16x32_bf16 v[32:35], v[154:157], v[182:185], v[32:35]
	v_mfma_f32_16x16x32_bf16 v[24:27], v[144:147], v[190:193], v[24:27]
	v_mfma_f32_16x16x32_bf16 v[16:19], v[154:157], v[190:193], v[16:19]
	v_mfma_f32_16x16x32_bf16 v[66:69], v[150:153], v[170:173], v[66:69]
	v_mfma_f32_16x16x32_bf16 v[62:65], v[162:165], v[170:173], v[62:65]
	v_mfma_f32_16x16x32_bf16 v[58:61], v[150:153], v[178:181], v[58:61]
	v_mfma_f32_16x16x32_bf16 v[50:53], v[162:165], v[178:181], v[50:53]
	v_mfma_f32_16x16x32_bf16 v[42:45], v[150:153], v[186:189], v[42:45]
	v_mfma_f32_16x16x32_bf16 v[32:35], v[162:165], v[186:189], v[32:35]
	v_mfma_f32_16x16x32_bf16 v[24:27], v[150:153], v[194:197], v[24:27]
	v_mfma_f32_16x16x32_bf16 v[16:19], v[162:165], v[194:197], v[16:19]
	s_barrier
	s_add_u32 s52, s16, 0x40000
	s_addc_u32 s53, s17, 0
	s_add_i32 s51, s54, s36
	v_lshl_add_u64 v[144:145], s[52:53], 0, v[2:3]
	s_mov_b32 m0, s51
	s_nop 0
	global_load_lds_dwordx4 v[144:145], off
	v_lshl_add_u64 v[144:145], s[52:53], 0, v[134:135]
	s_add_i32 m0, s51, 0x2000
	s_nop 0
	global_load_lds_dwordx4 v[144:145], off
	s_waitcnt vmcnt(6)
	s_barrier
	v_mfma_f32_16x16x32_bf16 v[54:57], v[198:201], v[166:169], v[54:57]
	v_mfma_f32_16x16x32_bf16 v[46:49], v[206:209], v[166:169], v[46:49]
	v_mfma_f32_16x16x32_bf16 v[38:41], v[198:201], v[174:177], v[38:41]
	v_mfma_f32_16x16x32_bf16 v[28:31], v[206:209], v[174:177], v[28:31]
	v_mfma_f32_16x16x32_bf16 v[20:23], v[198:201], v[182:185], v[20:23]
	v_mfma_f32_16x16x32_bf16 v[12:15], v[206:209], v[182:185], v[12:15]
	v_mfma_f32_16x16x32_bf16 v[8:11], v[198:201], v[190:193], v[8:11]
	v_mfma_f32_16x16x32_bf16 v[4:7], v[206:209], v[190:193], v[4:7]
	v_mfma_f32_16x16x32_bf16 v[54:57], v[202:205], v[170:173], v[54:57]
	v_mfma_f32_16x16x32_bf16 v[46:49], v[210:213], v[170:173], v[46:49]
	v_mfma_f32_16x16x32_bf16 v[38:41], v[202:205], v[178:181], v[38:41]
	v_mfma_f32_16x16x32_bf16 v[28:31], v[210:213], v[178:181], v[28:31]
	v_mfma_f32_16x16x32_bf16 v[20:23], v[202:205], v[186:189], v[20:23]
	v_mfma_f32_16x16x32_bf16 v[12:15], v[210:213], v[186:189], v[12:15]
	v_mfma_f32_16x16x32_bf16 v[8:11], v[202:205], v[194:197], v[8:11]
	v_mfma_f32_16x16x32_bf16 v[4:7], v[210:213], v[194:197], v[4:7]
	s_add_i32 s51, 0, 0x18000
	v_add_u32_e32 v162, s51, v37
	s_barrier
	ds_read_b128 v[144:147], v162
	ds_read_b128 v[150:153], v162 offset:1024
	ds_read_b128 v[154:157], v162 offset:2048
	ds_read_b128 v[162:165], v162 offset:3072
	s_add_u32 s18, s18, 0x40000
	s_addc_u32 s19, s19, 0
	s_mov_b32 m0, s39
	v_lshl_add_u64 v[198:199], s[18:19], 0, v[138:139]
	ds_read_b128 v[166:169], v149 offset:32768
	ds_read_b128 v[170:173], v149 offset:33792
	ds_read_b128 v[174:177], v149 offset:34816
	ds_read_b128 v[178:181], v149 offset:35840
	ds_read_b128 v[182:185], v149 offset:36864
	ds_read_b128 v[186:189], v149 offset:37888
	ds_read_b128 v[190:193], v149 offset:38912
	ds_read_b128 v[194:197], v149 offset:39936
	global_load_lds_dwordx4 v[198:199], off
	v_lshl_add_u64 v[198:199], s[18:19], 0, v[136:137]
	s_mov_b32 m0, s40
	s_nop 0
	global_load_lds_dwordx4 v[198:199], off
	s_waitcnt lgkmcnt(8)
	s_barrier
	s_waitcnt lgkmcnt(0)
	s_waitcnt lgkmcnt(0)
	v_mfma_f32_16x16x32_bf16 v[130:133], v[144:147], v[166:169], v[130:133]
	v_mfma_f32_16x16x32_bf16 v[126:129], v[154:157], v[166:169], v[126:129]
	v_mfma_f32_16x16x32_bf16 v[122:125], v[144:147], v[174:177], v[122:125]
	v_mfma_f32_16x16x32_bf16 v[114:117], v[154:157], v[174:177], v[114:117]
	v_mfma_f32_16x16x32_bf16 v[106:109], v[144:147], v[182:185], v[106:109]
	v_mfma_f32_16x16x32_bf16 v[98:101], v[154:157], v[182:185], v[98:101]
	v_mfma_f32_16x16x32_bf16 v[90:93], v[144:147], v[190:193], v[90:93]
	v_mfma_f32_16x16x32_bf16 v[82:85], v[154:157], v[190:193], v[82:85]
	v_mfma_f32_16x16x32_bf16 v[130:133], v[150:153], v[170:173], v[130:133]
	v_mfma_f32_16x16x32_bf16 v[126:129], v[162:165], v[170:173], v[126:129]
	v_mfma_f32_16x16x32_bf16 v[122:125], v[150:153], v[178:181], v[122:125]
	v_mfma_f32_16x16x32_bf16 v[114:117], v[162:165], v[178:181], v[114:117]
	v_mfma_f32_16x16x32_bf16 v[106:109], v[150:153], v[186:189], v[106:109]
	v_mfma_f32_16x16x32_bf16 v[98:101], v[162:165], v[186:189], v[98:101]
	v_mfma_f32_16x16x32_bf16 v[90:93], v[150:153], v[194:197], v[90:93]
	v_mfma_f32_16x16x32_bf16 v[82:85], v[162:165], v[194:197], v[82:85]
	s_barrier
	s_add_i32 s18, 0, 0x1c000
	s_add_i32 s19, s51, s36
	v_add_u32_e32 v210, s18, v37
	v_lshl_add_u64 v[158:159], v[158:159], 0, s[24:25]
	s_mov_b32 m0, s19
	ds_read_b128 v[198:201], v210
	ds_read_b128 v[202:205], v210 offset:1024
	ds_read_b128 v[206:209], v210 offset:2048
	ds_read_b128 v[210:213], v210 offset:3072
	global_load_lds_dwordx4 v[158:159], off
	v_lshl_add_u64 v[158:159], v[160:161], 0, s[24:25]
	s_add_i32 m0, s19, 0x2000
	s_nop 0
	global_load_lds_dwordx4 v[158:159], off
	s_barrier
	s_waitcnt lgkmcnt(0)
	s_waitcnt lgkmcnt(0)
	v_mfma_f32_16x16x32_bf16 v[118:121], v[198:201], v[166:169], v[118:121]
	v_mfma_f32_16x16x32_bf16 v[110:113], v[206:209], v[166:169], v[110:113]
	v_mfma_f32_16x16x32_bf16 v[102:105], v[198:201], v[174:177], v[102:105]
	v_mfma_f32_16x16x32_bf16 v[94:97], v[206:209], v[174:177], v[94:97]
	v_mfma_f32_16x16x32_bf16 v[86:89], v[198:201], v[182:185], v[86:89]
	v_mfma_f32_16x16x32_bf16 v[78:81], v[206:209], v[182:185], v[78:81]
	v_mfma_f32_16x16x32_bf16 v[74:77], v[198:201], v[190:193], v[74:77]
	v_mfma_f32_16x16x32_bf16 v[70:73], v[206:209], v[190:193], v[70:73]
	v_mfma_f32_16x16x32_bf16 v[118:121], v[202:205], v[170:173], v[118:121]
	v_mfma_f32_16x16x32_bf16 v[110:113], v[210:213], v[170:173], v[110:113]
	v_mfma_f32_16x16x32_bf16 v[102:105], v[202:205], v[178:181], v[102:105]
	v_mfma_f32_16x16x32_bf16 v[94:97], v[210:213], v[178:181], v[94:97]
	v_mfma_f32_16x16x32_bf16 v[86:89], v[202:205], v[186:189], v[86:89]
	v_mfma_f32_16x16x32_bf16 v[78:81], v[210:213], v[186:189], v[78:81]
	v_mfma_f32_16x16x32_bf16 v[74:77], v[202:205], v[194:197], v[74:77]
	v_mfma_f32_16x16x32_bf16 v[70:73], v[210:213], v[194:197], v[70:73]
	s_mov_b32 m0, s41
	v_lshl_add_u64 v[158:159], v[214:215], 0, s[24:25]
	s_barrier
	ds_read_b128 v[166:169], v149 offset:49152
	ds_read_b128 v[170:173], v149 offset:50176
	ds_read_b128 v[174:177], v149 offset:51200
	ds_read_b128 v[178:181], v149 offset:52224
	ds_read_b128 v[182:185], v149 offset:53248
	ds_read_b128 v[186:189], v149 offset:54272
	ds_read_b128 v[190:193], v149 offset:55296
	ds_read_b128 v[194:197], v149 offset:56320
	global_load_lds_dwordx4 v[158:159], off
	v_lshl_add_u64 v[158:159], v[216:217], 0, s[24:25]
	s_mov_b32 m0, s42
	s_nop 0
	global_load_lds_dwordx4 v[158:159], off
	s_barrier
	s_waitcnt lgkmcnt(0)
	s_waitcnt lgkmcnt(0)
	v_mfma_f32_16x16x32_bf16 v[66:69], v[144:147], v[166:169], v[66:69]
	v_mfma_f32_16x16x32_bf16 v[62:65], v[154:157], v[166:169], v[62:65]
	v_mfma_f32_16x16x32_bf16 v[58:61], v[144:147], v[174:177], v[58:61]
	v_mfma_f32_16x16x32_bf16 v[50:53], v[154:157], v[174:177], v[50:53]
	v_mfma_f32_16x16x32_bf16 v[42:45], v[144:147], v[182:185], v[42:45]
	v_mfma_f32_16x16x32_bf16 v[32:35], v[154:157], v[182:185], v[32:35]
	v_mfma_f32_16x16x32_bf16 v[24:27], v[144:147], v[190:193], v[24:27]
	v_mfma_f32_16x16x32_bf16 v[16:19], v[154:157], v[190:193], v[16:19]
	v_mfma_f32_16x16x32_bf16 v[66:69], v[150:153], v[170:173], v[66:69]
	v_mfma_f32_16x16x32_bf16 v[62:65], v[162:165], v[170:173], v[62:65]
	v_mfma_f32_16x16x32_bf16 v[58:61], v[150:153], v[178:181], v[58:61]
	v_mfma_f32_16x16x32_bf16 v[50:53], v[162:165], v[178:181], v[50:53]
	v_mfma_f32_16x16x32_bf16 v[42:45], v[150:153], v[186:189], v[42:45]
	v_mfma_f32_16x16x32_bf16 v[32:35], v[162:165], v[186:189], v[32:35]
	v_mfma_f32_16x16x32_bf16 v[24:27], v[150:153], v[194:197], v[24:27]
	v_mfma_f32_16x16x32_bf16 v[16:19], v[162:165], v[194:197], v[16:19]
	s_barrier
	s_add_u32 s16, s16, 0x40080
	s_addc_u32 s17, s17, 0
	s_add_i32 s18, s18, s36
	v_lshl_add_u64 v[144:145], s[16:17], 0, v[2:3]
	s_mov_b32 m0, s18
	s_nop 0
	global_load_lds_dwordx4 v[144:145], off
	v_lshl_add_u64 v[144:145], s[16:17], 0, v[134:135]
	s_add_i32 m0, s18, 0x2000
	s_nop 0
	global_load_lds_dwordx4 v[144:145], off
	s_waitcnt vmcnt(6)
	s_barrier
	v_mfma_f32_16x16x32_bf16 v[54:57], v[198:201], v[166:169], v[54:57]
	v_mfma_f32_16x16x32_bf16 v[46:49], v[206:209], v[166:169], v[46:49]
	v_mfma_f32_16x16x32_bf16 v[38:41], v[198:201], v[174:177], v[38:41]
	v_mfma_f32_16x16x32_bf16 v[28:31], v[206:209], v[174:177], v[28:31]
	v_mfma_f32_16x16x32_bf16 v[20:23], v[198:201], v[182:185], v[20:23]
	v_mfma_f32_16x16x32_bf16 v[12:15], v[206:209], v[182:185], v[12:15]
	v_mfma_f32_16x16x32_bf16 v[8:11], v[198:201], v[190:193], v[8:11]
	v_mfma_f32_16x16x32_bf16 v[4:7], v[206:209], v[190:193], v[4:7]
	v_mfma_f32_16x16x32_bf16 v[54:57], v[202:205], v[170:173], v[54:57]
	v_mfma_f32_16x16x32_bf16 v[46:49], v[210:213], v[170:173], v[46:49]
	v_mfma_f32_16x16x32_bf16 v[38:41], v[202:205], v[178:181], v[38:41]
	v_mfma_f32_16x16x32_bf16 v[28:31], v[210:213], v[178:181], v[28:31]
	v_mfma_f32_16x16x32_bf16 v[20:23], v[202:205], v[186:189], v[20:23]
	v_mfma_f32_16x16x32_bf16 v[12:15], v[210:213], v[186:189], v[12:15]
	v_mfma_f32_16x16x32_bf16 v[8:11], v[202:205], v[194:197], v[8:11]
	v_mfma_f32_16x16x32_bf16 v[4:7], v[210:213], v[194:197], v[4:7]
	s_add_i32 s50, s50, 2
	s_add_u32 s14, s14, 0x100
	s_addc_u32 s15, s15, 0
	s_add_u32 s48, s48, 0x100
	s_addc_u32 s49, s49, 0
	s_cmp_gt_u32 s50, 13
	s_barrier
	s_cbranch_scc0 .LBB0_841
	v_lshl_or_b32 v146, s45, 8, v148
	v_lshl_add_u32 v152, s12, 8, v1
	v_ashrrev_i32_e32 v147, 31, v146
	v_mov_b64_e32 v[144:145], s[34:35]
	v_mad_i64_i32 v[150:151], s[14:15], v152, s67, v[144:145]
	v_lshlrev_b64 v[146:147], 1, v[146:147]
	v_lshl_add_u64 v[150:151], v[150:151], 0, v[146:147]
	v_cvt_pk_bf16_f32 v130, v130, v131
	v_cvt_pk_bf16_f32 v131, v132, v133
	v_cvt_pk_bf16_f32 v132, v126, v127
	v_cvt_pk_bf16_f32 v133, v128, v129
	global_store_dwordx4 v[150:151], v[130:133], off
	v_cvt_pk_bf16_f32 v118, v118, v119
	v_cvt_pk_bf16_f32 v119, v120, v121
	v_cvt_pk_bf16_f32 v120, v110, v111
	v_or_b32_e32 v110, 16, v152
	v_mad_i64_i32 v[110:111], s[14:15], v110, s67, v[144:145]
	v_cvt_pk_bf16_f32 v121, v112, v113
	global_store_dwordx4 v[150:151], v[118:121], off offset:256
	s_and_b64 vcc, exec, s[4:5]
	s_mov_b32 s45, s0
	v_lshl_add_u64 v[118:119], v[110:111], 0, v[146:147]
	v_cvt_pk_bf16_f32 v110, v122, v123
	v_cvt_pk_bf16_f32 v111, v124, v125
	v_cvt_pk_bf16_f32 v112, v114, v115
	v_cvt_pk_bf16_f32 v113, v116, v117
	global_store_dwordx4 v[118:119], v[110:113], off
	v_cvt_pk_bf16_f32 v102, v102, v103
	v_cvt_pk_bf16_f32 v103, v104, v105
	v_cvt_pk_bf16_f32 v104, v94, v95
	v_or_b32_e32 v94, 32, v152
	v_mad_i64_i32 v[94:95], s[14:15], v94, s67, v[144:145]
	v_cvt_pk_bf16_f32 v105, v96, v97
	global_store_dwordx4 v[118:119], v[102:105], off offset:256
	s_mov_b32 s12, s6
	s_mov_b64 s[16:17], s[10:11]
	v_lshl_add_u64 v[102:103], v[94:95], 0, v[146:147]
	v_cvt_pk_bf16_f32 v94, v106, v107
	v_cvt_pk_bf16_f32 v95, v108, v109
	v_cvt_pk_bf16_f32 v96, v98, v99
	v_cvt_pk_bf16_f32 v97, v100, v101
	global_store_dwordx4 v[102:103], v[94:97], off
	v_cvt_pk_bf16_f32 v86, v86, v87
	v_cvt_pk_bf16_f32 v87, v88, v89
	v_cvt_pk_bf16_f32 v88, v78, v79
	v_or_b32_e32 v78, 48, v152
	v_mad_i64_i32 v[78:79], s[14:15], v78, s67, v[144:145]
	v_cvt_pk_bf16_f32 v89, v80, v81
	global_store_dwordx4 v[102:103], v[86:89], off offset:256
	s_nop 1
	v_lshl_add_u64 v[86:87], v[78:79], 0, v[146:147]
	v_cvt_pk_bf16_f32 v78, v90, v91
	v_cvt_pk_bf16_f32 v79, v92, v93
	v_cvt_pk_bf16_f32 v80, v82, v83
	v_cvt_pk_bf16_f32 v81, v84, v85
	global_store_dwordx4 v[86:87], v[78:81], off
	v_cvt_pk_bf16_f32 v74, v74, v75
	v_cvt_pk_bf16_f32 v75, v76, v77
	v_cvt_pk_bf16_f32 v76, v70, v71
	v_add_u32_e32 v70, 0x80, v152
	v_mad_i64_i32 v[70:71], s[14:15], v70, s67, v[144:145]
	v_lshl_add_u64 v[70:71], v[70:71], 0, v[146:147]
	v_cvt_pk_bf16_f32 v77, v72, v73
	global_store_dwordx4 v[86:87], v[74:77], off offset:256
	v_cvt_pk_bf16_f32 v66, v66, v67
	v_cvt_pk_bf16_f32 v67, v68, v69
	v_cvt_pk_bf16_f32 v68, v62, v63
	v_cvt_pk_bf16_f32 v69, v64, v65
	global_store_dwordx4 v[70:71], v[66:69], off
	v_cvt_pk_bf16_f32 v54, v54, v55
	v_cvt_pk_bf16_f32 v55, v56, v57
	v_cvt_pk_bf16_f32 v56, v46, v47
	v_add_u32_e32 v46, 0x90, v152
	v_mad_i64_i32 v[46:47], s[14:15], v46, s67, v[144:145]
	v_cvt_pk_bf16_f32 v57, v48, v49
	global_store_dwordx4 v[70:71], v[54:57], off offset:256
	s_nop 1
	v_lshl_add_u64 v[54:55], v[46:47], 0, v[146:147]
	v_cvt_pk_bf16_f32 v46, v58, v59
	v_cvt_pk_bf16_f32 v47, v60, v61
	v_cvt_pk_bf16_f32 v48, v50, v51
	v_cvt_pk_bf16_f32 v49, v52, v53
	global_store_dwordx4 v[54:55], v[46:49], off
	v_cvt_pk_bf16_f32 v38, v38, v39
	v_cvt_pk_bf16_f32 v39, v40, v41
	v_cvt_pk_bf16_f32 v40, v28, v29
	v_add_u32_e32 v28, 0xa0, v152
	v_mad_i64_i32 v[28:29], s[14:15], v28, s67, v[144:145]
	v_cvt_pk_bf16_f32 v41, v30, v31
	global_store_dwordx4 v[54:55], v[38:41], off offset:256
	s_nop 1
	v_lshl_add_u64 v[38:39], v[28:29], 0, v[146:147]
	v_cvt_pk_bf16_f32 v28, v42, v43
	v_cvt_pk_bf16_f32 v29, v44, v45
	v_cvt_pk_bf16_f32 v30, v32, v33
	v_cvt_pk_bf16_f32 v31, v34, v35
	global_store_dwordx4 v[38:39], v[28:31], off
	v_cvt_pk_bf16_f32 v20, v20, v21
	v_cvt_pk_bf16_f32 v21, v22, v23
	v_cvt_pk_bf16_f32 v22, v12, v13
	v_add_u32_e32 v12, 0xb0, v152
	v_mad_i64_i32 v[12:13], s[14:15], v12, s67, v[144:145]
	v_cvt_pk_bf16_f32 v23, v14, v15
	global_store_dwordx4 v[38:39], v[20:23], off offset:256
	s_mov_b64 s[14:15], s[8:9]
	s_nop 0
	v_lshl_add_u64 v[20:21], v[12:13], 0, v[146:147]
	v_cvt_pk_bf16_f32 v12, v24, v25
	v_cvt_pk_bf16_f32 v13, v26, v27
	v_cvt_pk_bf16_f32 v14, v16, v17
	v_cvt_pk_bf16_f32 v15, v18, v19
	global_store_dwordx4 v[20:21], v[12:15], off
	v_cvt_pk_bf16_f32 v8, v8, v9
	v_cvt_pk_bf16_f32 v9, v10, v11
	v_cvt_pk_bf16_f32 v10, v4, v5
	v_cvt_pk_bf16_f32 v11, v6, v7
	global_store_dwordx4 v[20:21], v[8:11], off offset:256
	s_cbranch_vccz .LBB0_838
	s_waitcnt vmcnt(0)
	s_cmpk_gt_u32 s27, 0xff
	s_cbranch_scc1 .LBB0_845
	s_barrier
